# inverted priority: load segments run at s_setprio 1, MFMA segments at 0 (loader issue favoured)
# baseline (speedup 1.0000x reference)
; #define PG8_STAGE(bufoff, gbase, voff) do { _Pragma("unroll") for (int _i = 0; _i < 2; ++_i) { \
;         const unsigned _m0 = ldsu + (unsigned)(bufoff) + ldsw + (unsigned)(_i * 8192); \
;         asm volatile("s_mov_b32 m0, %2\n\ts_nop 0\n\tglobal_load_lds_dwordx4 %0, %1" :: "v"((voff)[_i]), "s"((const char*)(gbase)), "s"(_m0) : "memory"); } } while (0)
; #define PG8_LDA(dst, b, h) do { _Pragma("unroll") for (int m = 0; m < 4; ++m) _Pragma("unroll") for (int k = 0; k < 2; ++k) dst[m][k] = *(const LAS bf16x8*)(lds + PG8_SA(b, h) + aoff + m * 2048 + k * 1024); } while (0)
; #define PG8_LDB(dst, b, h) do { _Pragma("unroll") for (int n = 0; n < 2; ++n) _Pragma("unroll") for (int k = 0; k < 2; ++k) dst[n][k] = *(const LAS bf16x8*)(lds + bbase[b][h] + n * 2048 + k * 1024); } while (0)
; #define PG8_WAIT_V(n) asm volatile("s_waitcnt vmcnt(" #n ")" ::: "memory")
; #define PG8_WAIT_L(n) asm volatile("s_waitcnt lgkmcnt(" #n ")" ::: "memory")
; #define PG8_BAR __builtin_amdgcn_s_barrier()
; #define PG8_SCHED __builtin_amdgcn_sched_barrier(0)
; template <class Epi>
; __device__ __forceinline__ void gemm_phase(LAS unsigned char* lds, const Gemm g, const StaticOrder& S, const Epi& E) {
;     ...
;             const bool last = (t == nt - 2);
;             const char* a2 = last ? nA : cA + (size_t)(t + 2) * kstep; const char* b2 = last ? nB : cB + (size_t)(t + 2) * kstep;
;             const char* a3 = a2 + kstep; const char* b3 = b2 + kstep;
;             const char* b1 = cB + (size_t)(t + 1) * kstep;
;             PG8_LDB(B0, 0, 0); PG8_SCHED; PG8_LDA(At, 0, 0); PG8_LDA(At2, 0, 1); PG8_STAGE(PG8_SB(1, 1), b1 + hstepB, voffB);
;             PG8_WAIT_V(8); PG8_WAIT_L(0); PG8_BAR; PG8_MMA2B(0, At, At2, B0); PG8_BAR; PG8_SCHED;
;             PG8_LDB(B0, 0, 1); PG8_STAGE(PG8_SB(0, 0), b2, voffB); PG8_STAGE(PG8_SA(0, 0), a2, voffA); PG8_STAGE(PG8_SA(0, 1), a2 + hstepA, voffA);
;             PG8_WAIT_V(8); PG8_WAIT_L(0); PG8_BAR; PG8_MMA2B(1, At, At2, B0); PG8_BAR; PG8_SCHED;
.LBB0_233:
	ds_read_b128 v[130:133], v142
	ds_read_b128 v[148:151], v142 offset:1024
	ds_read_b128 v[152:155], v142 offset:2048
	ds_read_b128 v[156:159], v142 offset:3072
	s_add_u32 s8, s4, 0x100
	s_addc_u32 s9, s5, 0
	s_cmp_eq_u32 s62, 12
	s_cselect_b32 s10, s58, s60
	s_cselect_b32 s11, s15, s61
	s_cselect_b32 s80, s59, s8
	s_cselect_b32 s81, s13, s9
	s_add_u32 s38, s10, 0x80
	s_addc_u32 s39, s11, 0
	ds_read_b128 v[166:169], v143
	ds_read_b128 v[178:181], v143 offset:1024
	ds_read_b128 v[182:185], v143 offset:2048
	ds_read_b128 v[186:189], v143 offset:3072
	ds_read_b128 v[190:193], v143 offset:4096
	ds_read_b128 v[194:197], v143 offset:5120
	ds_read_b128 v[198:201], v143 offset:6144
	ds_read_b128 v[202:205], v143 offset:7168
	ds_read_b128 v[214:217], v143 offset:16384
	ds_read_b128 v[218:221], v143 offset:17408
	ds_read_b128 v[222:225], v143 offset:18432
	ds_read_b128 v[226:229], v143 offset:19456
	ds_read_b128 v[230:233], v143 offset:20480
	ds_read_b128 v[234:237], v143 offset:21504
	ds_read_b128 v[238:241], v143 offset:22528
	ds_read_b128 v[242:245], v143 offset:23552
	s_add_u32 s4, s4, 0x40080
	s_addc_u32 s5, s5, 0
	s_mov_b32 m0, s84
	s_nop 0
	global_load_lds_dwordx4 v137, s[4:5]
	s_mov_b32 m0, s85
	s_nop 0
	global_load_lds_dwordx4 v139, s[4:5]
	s_waitcnt vmcnt(8)
	s_waitcnt lgkmcnt(0)
	s_barrier
	s_setprio 0
	s_waitcnt lgkmcnt(14)
	v_mfma_f32_16x16x32_bf16 v[124:127], v[130:133], v[166:169], v[124:127]
	v_mfma_f32_16x16x32_bf16 v[120:123], v[152:155], v[166:169], v[120:123]
	s_waitcnt lgkmcnt(13)
	v_mfma_f32_16x16x32_bf16 v[108:111], v[130:133], v[182:185], v[108:111]
	v_mfma_f32_16x16x32_bf16 v[104:107], v[152:155], v[182:185], v[104:107]
	s_waitcnt lgkmcnt(11)
	v_mfma_f32_16x16x32_bf16 v[92:95], v[130:133], v[190:193], v[92:95]
	v_mfma_f32_16x16x32_bf16 v[88:91], v[152:155], v[190:193], v[88:91]
	s_waitcnt lgkmcnt(9)
	v_mfma_f32_16x16x32_bf16 v[76:79], v[130:133], v[198:201], v[76:79]
	v_mfma_f32_16x16x32_bf16 v[72:75], v[152:155], v[198:201], v[72:75]
	s_waitcnt lgkmcnt(7)
	v_mfma_f32_16x16x32_bf16 v[60:63], v[130:133], v[214:217], v[60:63]
	v_mfma_f32_16x16x32_bf16 v[56:59], v[152:155], v[214:217], v[56:59]
	s_waitcnt lgkmcnt(5)
	v_mfma_f32_16x16x32_bf16 v[44:47], v[130:133], v[222:225], v[44:47]
	v_mfma_f32_16x16x32_bf16 v[40:43], v[152:155], v[222:225], v[40:43]
	s_waitcnt lgkmcnt(3)
	v_mfma_f32_16x16x32_bf16 v[28:31], v[130:133], v[230:233], v[28:31]
	v_mfma_f32_16x16x32_bf16 v[24:27], v[152:155], v[230:233], v[24:27]
	s_waitcnt lgkmcnt(1)
	v_mfma_f32_16x16x32_bf16 v[12:15], v[130:133], v[238:241], v[12:15]
	v_mfma_f32_16x16x32_bf16 v[8:11], v[152:155], v[238:241], v[8:11]
	v_mfma_f32_16x16x32_bf16 v[124:127], v[148:151], v[178:181], v[124:127]
	v_mfma_f32_16x16x32_bf16 v[120:123], v[156:159], v[178:181], v[120:123]
	v_mfma_f32_16x16x32_bf16 v[108:111], v[148:151], v[186:189], v[108:111]
	v_mfma_f32_16x16x32_bf16 v[104:107], v[156:159], v[186:189], v[104:107]
	v_mfma_f32_16x16x32_bf16 v[92:95], v[148:151], v[194:197], v[92:95]
	v_mfma_f32_16x16x32_bf16 v[88:91], v[156:159], v[194:197], v[88:91]
	v_mfma_f32_16x16x32_bf16 v[76:79], v[148:151], v[202:205], v[76:79]
	v_mfma_f32_16x16x32_bf16 v[72:75], v[156:159], v[202:205], v[72:75]
	v_mfma_f32_16x16x32_bf16 v[60:63], v[148:151], v[218:221], v[60:63]
	v_mfma_f32_16x16x32_bf16 v[56:59], v[156:159], v[218:221], v[56:59]
	v_mfma_f32_16x16x32_bf16 v[44:47], v[148:151], v[226:229], v[44:47]
	v_mfma_f32_16x16x32_bf16 v[40:43], v[156:159], v[226:229], v[40:43]
	v_mfma_f32_16x16x32_bf16 v[28:31], v[148:151], v[234:237], v[28:31]
	v_mfma_f32_16x16x32_bf16 v[24:27], v[156:159], v[234:237], v[24:27]
	s_waitcnt lgkmcnt(0)
	v_mfma_f32_16x16x32_bf16 v[12:15], v[148:151], v[242:245], v[12:15]
	v_mfma_f32_16x16x32_bf16 v[8:11], v[156:159], v[242:245], v[8:11]
	s_setprio 1
	s_barrier
	ds_read_b128 v[130:133], v144
	ds_read_b128 v[148:151], v144 offset:1024
	ds_read_b128 v[152:155], v144 offset:2048
	ds_read_b128 v[156:159], v144 offset:3072
	s_mov_b32 m0, s29
	s_nop 0
	global_load_lds_dwordx4 v137, s[80:81]
	s_mov_b32 m0, s37
	s_nop 0
	global_load_lds_dwordx4 v139, s[80:81]
	s_mov_b32 m0, s28
	s_nop 0
	global_load_lds_dwordx4 v136, s[10:11]
	s_mov_b32 m0, s47
	s_nop 0
	global_load_lds_dwordx4 v138, s[10:11]
	s_add_u32 s4, s10, 0x40000
	s_addc_u32 s5, s11, 0
	s_mov_b32 m0, s48
	s_nop 0
	global_load_lds_dwordx4 v136, s[4:5]
	s_mov_b32 m0, s49
	s_nop 0
	global_load_lds_dwordx4 v138, s[4:5]
	s_waitcnt vmcnt(8)
	s_waitcnt lgkmcnt(0)
	s_barrier
	s_setprio 0
	s_waitcnt lgkmcnt(3)
	v_mfma_f32_16x16x32_bf16 v[116:119], v[130:133], v[166:169], v[116:119]
	s_waitcnt lgkmcnt(1)
	v_mfma_f32_16x16x32_bf16 v[112:115], v[152:155], v[166:169], v[112:115]
	v_mfma_f32_16x16x32_bf16 v[100:103], v[130:133], v[182:185], v[100:103]
	v_mfma_f32_16x16x32_bf16 v[96:99], v[152:155], v[182:185], v[96:99]
	v_mfma_f32_16x16x32_bf16 v[84:87], v[130:133], v[190:193], v[84:87]
	v_mfma_f32_16x16x32_bf16 v[80:83], v[152:155], v[190:193], v[80:83]
	v_mfma_f32_16x16x32_bf16 v[68:71], v[130:133], v[198:201], v[68:71]
	v_mfma_f32_16x16x32_bf16 v[64:67], v[152:155], v[198:201], v[64:67]
	v_mfma_f32_16x16x32_bf16 v[52:55], v[130:133], v[214:217], v[52:55]
	v_mfma_f32_16x16x32_bf16 v[48:51], v[152:155], v[214:217], v[48:51]
	v_mfma_f32_16x16x32_bf16 v[36:39], v[130:133], v[222:225], v[36:39]
	v_mfma_f32_16x16x32_bf16 v[32:35], v[152:155], v[222:225], v[32:35]
	v_mfma_f32_16x16x32_bf16 v[20:23], v[130:133], v[230:233], v[20:23]
	v_mfma_f32_16x16x32_bf16 v[16:19], v[152:155], v[230:233], v[16:19]
	v_mfma_f32_16x16x32_bf16 v[4:7], v[130:133], v[238:241], v[4:7]
	v_mfma_f32_16x16x32_bf16 v[0:3], v[152:155], v[238:241], v[0:3]
	v_mfma_f32_16x16x32_bf16 v[116:119], v[148:151], v[178:181], v[116:119]
	s_waitcnt lgkmcnt(0)
	v_mfma_f32_16x16x32_bf16 v[112:115], v[156:159], v[178:181], v[112:115]
	v_mfma_f32_16x16x32_bf16 v[100:103], v[148:151], v[186:189], v[100:103]
	v_mfma_f32_16x16x32_bf16 v[96:99], v[156:159], v[186:189], v[96:99]
	v_mfma_f32_16x16x32_bf16 v[84:87], v[148:151], v[194:197], v[84:87]
	v_mfma_f32_16x16x32_bf16 v[80:83], v[156:159], v[194:197], v[80:83]
	v_mfma_f32_16x16x32_bf16 v[68:71], v[148:151], v[202:205], v[68:71]
	v_mfma_f32_16x16x32_bf16 v[64:67], v[156:159], v[202:205], v[64:67]
	v_mfma_f32_16x16x32_bf16 v[52:55], v[148:151], v[218:221], v[52:55]
	v_mfma_f32_16x16x32_bf16 v[48:51], v[156:159], v[218:221], v[48:51]
	v_mfma_f32_16x16x32_bf16 v[36:39], v[148:151], v[226:229], v[36:39]
	v_mfma_f32_16x16x32_bf16 v[32:35], v[156:159], v[226:229], v[32:35]
	v_mfma_f32_16x16x32_bf16 v[20:23], v[148:151], v[234:237], v[20:23]
	v_mfma_f32_16x16x32_bf16 v[16:19], v[156:159], v[234:237], v[16:19]
	v_mfma_f32_16x16x32_bf16 v[4:7], v[148:151], v[242:245], v[4:7]
	v_mfma_f32_16x16x32_bf16 v[0:3], v[156:159], v[242:245], v[0:3]
	s_setprio 1
	s_barrier
; #define PG8_STAGE(bufoff, gbase, voff) do { _Pragma("unroll") for (int _i = 0; _i < 2; ++_i) { \
;         const unsigned _m0 = ldsu + (unsigned)(bufoff) + ldsw + (unsigned)(_i * 8192); \
;         asm volatile("s_mov_b32 m0, %2\n\ts_nop 0\n\tglobal_load_lds_dwordx4 %0, %1" :: "v"((voff)[_i]), "s"((const char*)(gbase)), "s"(_m0) : "memory"); } } while (0)
; #define PG8_LDA(dst, b, h) do { _Pragma("unroll") for (int m = 0; m < 4; ++m) _Pragma("unroll") for (int k = 0; k < 2; ++k) dst[m][k] = *(const LAS bf16x8*)(lds + PG8_SA(b, h) + aoff + m * 2048 + k * 1024); } while (0)
; #define PG8_LDB(dst, b, h) do { _Pragma("unroll") for (int n = 0; n < 2; ++n) _Pragma("unroll") for (int k = 0; k < 2; ++k) dst[n][k] = *(const LAS bf16x8*)(lds + bbase[b][h] + n * 2048 + k * 1024); } while (0)
; #define PG8_WAIT_V(n) asm volatile("s_waitcnt vmcnt(" #n ")" ::: "memory")
; #define PG8_WAIT_L(n) asm volatile("s_waitcnt lgkmcnt(" #n ")" ::: "memory")
; #define PG8_BAR __builtin_amdgcn_s_barrier()
; #define PG8_SCHED __builtin_amdgcn_sched_barrier(0)
; template <class Epi>
; __device__ __forceinline__ void gemm_phase(LAS unsigned char* lds, const Gemm g, const StaticOrder& S, const Epi& E) {
;     ...
;             PG8_LDB(B0, 1, 0); PG8_SCHED; PG8_LDA(At, 1, 0); PG8_LDA(At2, 1, 1); PG8_STAGE(PG8_SB(0, 1), b2 + hstepB, voffB);
;             PG8_WAIT_V(8); PG8_WAIT_L(0); PG8_BAR; PG8_MMA2B(0, At, At2, B0); PG8_BAR; PG8_SCHED;
;             PG8_LDB(B0, 1, 1); PG8_STAGE(PG8_SB(1, 0), b3, voffB); PG8_STAGE(PG8_SA(1, 0), a3, voffA); PG8_STAGE(PG8_SA(1, 1), a3 + hstepA, voffA);
;             PG8_WAIT_V(8); PG8_WAIT_L(0); PG8_BAR; PG8_MMA2B(1, At, At2, B0); PG8_BAR; PG8_SCHED;
;         }
;         if (wr == 0) PG8_BAR;
	ds_read_b128 v[130:133], v145
	ds_read_b128 v[148:151], v145 offset:1024
	ds_read_b128 v[152:155], v145 offset:2048
	ds_read_b128 v[156:159], v145 offset:3072
	ds_read_b128 v[166:169], v143 offset:32768
	ds_read_b128 v[178:181], v143 offset:33792
	ds_read_b128 v[182:185], v143 offset:34816
	ds_read_b128 v[186:189], v143 offset:35840
	ds_read_b128 v[190:193], v143 offset:36864
	ds_read_b128 v[194:197], v143 offset:37888
	ds_read_b128 v[198:201], v143 offset:38912
	ds_read_b128 v[202:205], v143 offset:39936
	ds_read_b128 v[214:217], v143 offset:49152
	ds_read_b128 v[218:221], v143 offset:50176
	ds_read_b128 v[222:225], v143 offset:51200
	ds_read_b128 v[226:229], v143 offset:52224
	ds_read_b128 v[230:233], v143 offset:53248
	ds_read_b128 v[234:237], v143 offset:54272
	ds_read_b128 v[238:241], v143 offset:55296
	ds_read_b128 v[242:245], v143 offset:56320
	s_add_u32 s4, s80, 0x40000
	s_addc_u32 s5, s81, 0
	s_mov_b32 m0, s50
	s_nop 0
	global_load_lds_dwordx4 v137, s[4:5]
	s_mov_b32 m0, s51
	s_nop 0
	global_load_lds_dwordx4 v139, s[4:5]
	s_waitcnt vmcnt(8)
	s_waitcnt lgkmcnt(0)
	s_barrier
	s_setprio 0
	s_waitcnt lgkmcnt(14)
	v_mfma_f32_16x16x32_bf16 v[124:127], v[130:133], v[166:169], v[124:127]
	v_mfma_f32_16x16x32_bf16 v[120:123], v[152:155], v[166:169], v[120:123]
	s_waitcnt lgkmcnt(13)
	v_mfma_f32_16x16x32_bf16 v[108:111], v[130:133], v[182:185], v[108:111]
	v_mfma_f32_16x16x32_bf16 v[104:107], v[152:155], v[182:185], v[104:107]
	s_waitcnt lgkmcnt(11)
	v_mfma_f32_16x16x32_bf16 v[92:95], v[130:133], v[190:193], v[92:95]
	v_mfma_f32_16x16x32_bf16 v[88:91], v[152:155], v[190:193], v[88:91]
	s_waitcnt lgkmcnt(9)
	v_mfma_f32_16x16x32_bf16 v[76:79], v[130:133], v[198:201], v[76:79]
	v_mfma_f32_16x16x32_bf16 v[72:75], v[152:155], v[198:201], v[72:75]
	s_waitcnt lgkmcnt(7)
	v_mfma_f32_16x16x32_bf16 v[60:63], v[130:133], v[214:217], v[60:63]
	v_mfma_f32_16x16x32_bf16 v[56:59], v[152:155], v[214:217], v[56:59]
	s_waitcnt lgkmcnt(5)
	v_mfma_f32_16x16x32_bf16 v[44:47], v[130:133], v[222:225], v[44:47]
	v_mfma_f32_16x16x32_bf16 v[40:43], v[152:155], v[222:225], v[40:43]
	s_waitcnt lgkmcnt(3)
	v_mfma_f32_16x16x32_bf16 v[28:31], v[130:133], v[230:233], v[28:31]
	v_mfma_f32_16x16x32_bf16 v[24:27], v[152:155], v[230:233], v[24:27]
	s_waitcnt lgkmcnt(1)
	v_mfma_f32_16x16x32_bf16 v[12:15], v[130:133], v[238:241], v[12:15]
	v_mfma_f32_16x16x32_bf16 v[8:11], v[152:155], v[238:241], v[8:11]
	v_mfma_f32_16x16x32_bf16 v[124:127], v[148:151], v[178:181], v[124:127]
	v_mfma_f32_16x16x32_bf16 v[120:123], v[156:159], v[178:181], v[120:123]
	v_mfma_f32_16x16x32_bf16 v[108:111], v[148:151], v[186:189], v[108:111]
	v_mfma_f32_16x16x32_bf16 v[104:107], v[156:159], v[186:189], v[104:107]
	v_mfma_f32_16x16x32_bf16 v[92:95], v[148:151], v[194:197], v[92:95]
	v_mfma_f32_16x16x32_bf16 v[88:91], v[156:159], v[194:197], v[88:91]
	v_mfma_f32_16x16x32_bf16 v[76:79], v[148:151], v[202:205], v[76:79]
	v_mfma_f32_16x16x32_bf16 v[72:75], v[156:159], v[202:205], v[72:75]
	v_mfma_f32_16x16x32_bf16 v[60:63], v[148:151], v[218:221], v[60:63]
	v_mfma_f32_16x16x32_bf16 v[56:59], v[156:159], v[218:221], v[56:59]
	v_mfma_f32_16x16x32_bf16 v[44:47], v[148:151], v[226:229], v[44:47]
	v_mfma_f32_16x16x32_bf16 v[40:43], v[156:159], v[226:229], v[40:43]
	v_mfma_f32_16x16x32_bf16 v[28:31], v[148:151], v[234:237], v[28:31]
	v_mfma_f32_16x16x32_bf16 v[24:27], v[156:159], v[234:237], v[24:27]
	s_waitcnt lgkmcnt(0)
	v_mfma_f32_16x16x32_bf16 v[12:15], v[148:151], v[242:245], v[12:15]
	v_mfma_f32_16x16x32_bf16 v[8:11], v[156:159], v[242:245], v[8:11]
	s_setprio 1
	s_barrier
	s_add_u32 s4, s80, 0x80
	ds_read_b128 v[130:133], v146
	ds_read_b128 v[148:151], v146 offset:1024
	ds_read_b128 v[152:155], v146 offset:2048
	ds_read_b128 v[156:159], v146 offset:3072
	s_addc_u32 s5, s81, 0
	s_mov_b32 m0, s52
	s_nop 0
	global_load_lds_dwordx4 v137, s[4:5]
	s_mov_b32 m0, s53
	s_nop 0
	global_load_lds_dwordx4 v139, s[4:5]
	s_mov_b32 m0, s54
	s_nop 0
	global_load_lds_dwordx4 v136, s[38:39]
	s_mov_b32 m0, s55
	s_nop 0
	global_load_lds_dwordx4 v138, s[38:39]
	s_add_u32 s4, s10, 0x40080
	s_addc_u32 s5, s11, 0
	s_mov_b32 m0, s82
	s_nop 0
	global_load_lds_dwordx4 v136, s[4:5]
	s_mov_b32 m0, s83
	s_nop 0
	global_load_lds_dwordx4 v138, s[4:5]
	s_waitcnt vmcnt(8)
	s_waitcnt lgkmcnt(0)
	s_barrier
	s_setprio 0
	s_waitcnt lgkmcnt(3)
	v_mfma_f32_16x16x32_bf16 v[116:119], v[130:133], v[166:169], v[116:119]
	s_waitcnt lgkmcnt(1)
	v_mfma_f32_16x16x32_bf16 v[112:115], v[152:155], v[166:169], v[112:115]
	v_mfma_f32_16x16x32_bf16 v[100:103], v[130:133], v[182:185], v[100:103]
	v_mfma_f32_16x16x32_bf16 v[96:99], v[152:155], v[182:185], v[96:99]
	v_mfma_f32_16x16x32_bf16 v[84:87], v[130:133], v[190:193], v[84:87]
	v_mfma_f32_16x16x32_bf16 v[80:83], v[152:155], v[190:193], v[80:83]
	v_mfma_f32_16x16x32_bf16 v[68:71], v[130:133], v[198:201], v[68:71]
	v_mfma_f32_16x16x32_bf16 v[64:67], v[152:155], v[198:201], v[64:67]
	v_mfma_f32_16x16x32_bf16 v[52:55], v[130:133], v[214:217], v[52:55]
	v_mfma_f32_16x16x32_bf16 v[48:51], v[152:155], v[214:217], v[48:51]
	v_mfma_f32_16x16x32_bf16 v[36:39], v[130:133], v[222:225], v[36:39]
	v_mfma_f32_16x16x32_bf16 v[32:35], v[152:155], v[222:225], v[32:35]
	v_mfma_f32_16x16x32_bf16 v[20:23], v[130:133], v[230:233], v[20:23]
	v_mfma_f32_16x16x32_bf16 v[16:19], v[152:155], v[230:233], v[16:19]
	v_mfma_f32_16x16x32_bf16 v[4:7], v[130:133], v[238:241], v[4:7]
	v_mfma_f32_16x16x32_bf16 v[0:3], v[152:155], v[238:241], v[0:3]
	v_mfma_f32_16x16x32_bf16 v[116:119], v[148:151], v[178:181], v[116:119]
	s_waitcnt lgkmcnt(0)
	v_mfma_f32_16x16x32_bf16 v[112:115], v[156:159], v[178:181], v[112:115]
	v_mfma_f32_16x16x32_bf16 v[100:103], v[148:151], v[186:189], v[100:103]
	v_mfma_f32_16x16x32_bf16 v[96:99], v[156:159], v[186:189], v[96:99]
	v_mfma_f32_16x16x32_bf16 v[84:87], v[148:151], v[194:197], v[84:87]
	v_mfma_f32_16x16x32_bf16 v[80:83], v[156:159], v[194:197], v[80:83]
	v_mfma_f32_16x16x32_bf16 v[68:71], v[148:151], v[202:205], v[68:71]
	v_mfma_f32_16x16x32_bf16 v[64:67], v[156:159], v[202:205], v[64:67]
	v_mfma_f32_16x16x32_bf16 v[52:55], v[148:151], v[218:221], v[52:55]
	v_mfma_f32_16x16x32_bf16 v[48:51], v[156:159], v[218:221], v[48:51]
	v_mfma_f32_16x16x32_bf16 v[36:39], v[148:151], v[226:229], v[36:39]
	v_mfma_f32_16x16x32_bf16 v[32:35], v[156:159], v[226:229], v[32:35]
	v_mfma_f32_16x16x32_bf16 v[20:23], v[148:151], v[234:237], v[20:23]
	v_mfma_f32_16x16x32_bf16 v[16:19], v[156:159], v[234:237], v[16:19]
	v_mfma_f32_16x16x32_bf16 v[4:7], v[148:151], v[242:245], v[4:7]
	v_mfma_f32_16x16x32_bf16 v[0:3], v[156:159], v[242:245], v[0:3]
	s_setprio 1
	s_barrier
	s_add_i32 s62, s62, 2
	s_add_u32 s60, s60, 0x100
	s_addc_u32 s61, s61, 0
	s_cmp_gt_u32 s62, 13
	s_mov_b64 s[4:5], s[8:9]
	s_cbranch_scc0 .LBB0_233
	s_and_b64 vcc, exec, s[2:3]
	s_cbranch_vccz .LBB0_236
	s_barrier

; #define PG8_STAGE(bufoff, gbase, voff) do { _Pragma("unroll") for (int _i = 0; _i < 2; ++_i) { \
;         const unsigned _m0 = ldsu + (unsigned)(bufoff) + ldsw + (unsigned)(_i * 8192); \
;         asm volatile("s_mov_b32 m0, %2\n\ts_nop 0\n\tglobal_load_lds_dwordx4 %0, %1" :: "v"((voff)[_i]), "s"((const char*)(gbase)), "s"(_m0) : "memory"); } } while (0)
; #define PG8_LDA(dst, b, h) do { _Pragma("unroll") for (int m = 0; m < 4; ++m) _Pragma("unroll") for (int k = 0; k < 2; ++k) dst[m][k] = *(const LAS bf16x8*)(lds + PG8_SA(b, h) + aoff + m * 2048 + k * 1024); } while (0)
; #define PG8_LDB(dst, b, h) do { _Pragma("unroll") for (int n = 0; n < 2; ++n) _Pragma("unroll") for (int k = 0; k < 2; ++k) dst[n][k] = *(const LAS bf16x8*)(lds + bbase[b][h] + n * 2048 + k * 1024); } while (0)
; #define PG8_WAIT_V(n) asm volatile("s_waitcnt vmcnt(" #n ")" ::: "memory")
; #define PG8_WAIT_L(n) asm volatile("s_waitcnt lgkmcnt(" #n ")" ::: "memory")
; #define PG8_BAR __builtin_amdgcn_s_barrier()
; #define PG8_SCHED __builtin_amdgcn_sched_barrier(0)
; template <class Epi>
; __device__ __forceinline__ void gemm_phase(LAS unsigned char* lds, const Gemm g, const StaticOrder& S, const Epi& E) {
;     ...
;             const bool last = (t == nt - 2);
;             const char* a2 = last ? nA : cA + (size_t)(t + 2) * kstep; const char* b2 = last ? nB : cB + (size_t)(t + 2) * kstep;
;             const char* a3 = a2 + kstep; const char* b3 = b2 + kstep;
;             const char* b1 = cB + (size_t)(t + 1) * kstep;
;             PG8_LDB(B0, 0, 0); PG8_SCHED; PG8_LDA(At, 0, 0); PG8_LDA(At2, 0, 1); PG8_STAGE(PG8_SB(1, 1), b1 + hstepB, voffB);
;             PG8_WAIT_V(8); PG8_WAIT_L(0); PG8_BAR; PG8_MMA2B(0, At, At2, B0); PG8_BAR; PG8_SCHED;
;             PG8_LDB(B0, 0, 1); PG8_STAGE(PG8_SB(0, 0), b2, voffB); PG8_STAGE(PG8_SA(0, 0), a2, voffA); PG8_STAGE(PG8_SA(0, 1), a2 + hstepA, voffA);
;             PG8_WAIT_V(8); PG8_WAIT_L(0); PG8_BAR; PG8_MMA2B(1, At, At2, B0); PG8_BAR; PG8_SCHED;
.LBB0_487:
	s_add_i32 s69, s68, 2
	s_add_u32 s6, s88, 0x80
	ds_read_b128 v[140:143], v134
	ds_read_b128 v[144:147], v134 offset:1024
	ds_read_b128 v[148:151], v134 offset:2048
	ds_read_b128 v[152:155], v134 offset:3072
	s_addc_u32 s7, s89, 0
	s_cmp_eq_u32 s62, s68
	s_cselect_b32 s80, s17, s95
	s_cselect_b32 s81, s15, s96
	s_cselect_b32 s90, s87, s6
	s_cselect_b32 s91, s86, s7
	s_add_u32 s82, s80, 0x80
	s_addc_u32 s83, s81, 0
	s_add_u32 s84, s90, 0x80
	s_addc_u32 s85, s91, 0
	ds_read_b128 v[156:159], v135
	ds_read_b128 v[166:169], v135 offset:1024
	ds_read_b128 v[178:181], v135 offset:2048
	ds_read_b128 v[182:185], v135 offset:3072
	ds_read_b128 v[186:189], v135 offset:4096
	ds_read_b128 v[190:193], v135 offset:5120
	ds_read_b128 v[194:197], v135 offset:6144
	ds_read_b128 v[198:201], v135 offset:7168
	ds_read_b128 v[202:205], v135 offset:16384
	ds_read_b128 v[214:217], v135 offset:17408
	ds_read_b128 v[218:221], v135 offset:18432
	ds_read_b128 v[222:225], v135 offset:19456
	ds_read_b128 v[226:229], v135 offset:20480
	ds_read_b128 v[230:233], v135 offset:21504
	ds_read_b128 v[234:237], v135 offset:22528
	ds_read_b128 v[238:241], v135 offset:23552
	s_add_u32 s6, s88, 0x20000
	s_addc_u32 s7, s89, 0
	s_mov_b32 m0, s63
	s_nop 0
	global_load_lds_dwordx4 v129, s[6:7]
	s_mov_b32 m0, s64
	s_nop 0
	global_load_lds_dwordx4 v131, s[6:7]
	s_waitcnt vmcnt(8)
	s_waitcnt lgkmcnt(0)
	s_barrier
	s_setprio 0
	s_waitcnt lgkmcnt(14)
	v_mfma_f32_16x16x32_bf16 v[120:123], v[140:143], v[156:159], v[120:123]
	v_mfma_f32_16x16x32_bf16 v[124:127], v[148:151], v[156:159], v[124:127]
	s_waitcnt lgkmcnt(13)
	v_mfma_f32_16x16x32_bf16 v[108:111], v[140:143], v[178:181], v[108:111]
	v_mfma_f32_16x16x32_bf16 v[104:107], v[148:151], v[178:181], v[104:107]
	s_waitcnt lgkmcnt(11)
	v_mfma_f32_16x16x32_bf16 v[92:95], v[140:143], v[186:189], v[92:95]
	v_mfma_f32_16x16x32_bf16 v[88:91], v[148:151], v[186:189], v[88:91]
	s_waitcnt lgkmcnt(9)
	v_mfma_f32_16x16x32_bf16 v[76:79], v[140:143], v[194:197], v[76:79]
	v_mfma_f32_16x16x32_bf16 v[72:75], v[148:151], v[194:197], v[72:75]
	s_waitcnt lgkmcnt(7)
	v_mfma_f32_16x16x32_bf16 v[60:63], v[140:143], v[202:205], v[60:63]
	v_mfma_f32_16x16x32_bf16 v[56:59], v[148:151], v[202:205], v[56:59]
	s_waitcnt lgkmcnt(5)
	v_mfma_f32_16x16x32_bf16 v[44:47], v[140:143], v[218:221], v[44:47]
	v_mfma_f32_16x16x32_bf16 v[40:43], v[148:151], v[218:221], v[40:43]
	s_waitcnt lgkmcnt(3)
	v_mfma_f32_16x16x32_bf16 v[28:31], v[140:143], v[226:229], v[28:31]
	v_mfma_f32_16x16x32_bf16 v[24:27], v[148:151], v[226:229], v[24:27]
	s_waitcnt lgkmcnt(1)
	v_mfma_f32_16x16x32_bf16 v[12:15], v[140:143], v[234:237], v[12:15]
	v_mfma_f32_16x16x32_bf16 v[8:11], v[148:151], v[234:237], v[8:11]
	v_mfma_f32_16x16x32_bf16 v[120:123], v[144:147], v[166:169], v[120:123]
	v_mfma_f32_16x16x32_bf16 v[124:127], v[152:155], v[166:169], v[124:127]
	v_mfma_f32_16x16x32_bf16 v[108:111], v[144:147], v[182:185], v[108:111]
	v_mfma_f32_16x16x32_bf16 v[104:107], v[152:155], v[182:185], v[104:107]
	v_mfma_f32_16x16x32_bf16 v[92:95], v[144:147], v[190:193], v[92:95]
	v_mfma_f32_16x16x32_bf16 v[88:91], v[152:155], v[190:193], v[88:91]
	v_mfma_f32_16x16x32_bf16 v[76:79], v[144:147], v[198:201], v[76:79]
	v_mfma_f32_16x16x32_bf16 v[72:75], v[152:155], v[198:201], v[72:75]
	v_mfma_f32_16x16x32_bf16 v[60:63], v[144:147], v[214:217], v[60:63]
	v_mfma_f32_16x16x32_bf16 v[56:59], v[152:155], v[214:217], v[56:59]
	v_mfma_f32_16x16x32_bf16 v[44:47], v[144:147], v[222:225], v[44:47]
	v_mfma_f32_16x16x32_bf16 v[40:43], v[152:155], v[222:225], v[40:43]
	v_mfma_f32_16x16x32_bf16 v[28:31], v[144:147], v[230:233], v[28:31]
	v_mfma_f32_16x16x32_bf16 v[24:27], v[152:155], v[230:233], v[24:27]
	s_waitcnt lgkmcnt(0)
	v_mfma_f32_16x16x32_bf16 v[12:15], v[144:147], v[238:241], v[12:15]
	v_mfma_f32_16x16x32_bf16 v[8:11], v[152:155], v[238:241], v[8:11]
	s_setprio 1
	s_barrier
	ds_read_b128 v[140:143], v136
	ds_read_b128 v[144:147], v136 offset:1024
	ds_read_b128 v[148:151], v136 offset:2048
	ds_read_b128 v[152:155], v136 offset:3072
	s_mov_b32 m0, s48
	s_nop 0
	global_load_lds_dwordx4 v129, s[90:91]
	s_mov_b32 m0, s49
	s_nop 0
	global_load_lds_dwordx4 v131, s[90:91]
	s_mov_b32 m0, s47
	s_nop 0
	global_load_lds_dwordx4 v128, s[80:81]
	s_mov_b32 m0, s50
	s_nop 0
	global_load_lds_dwordx4 v130, s[80:81]
	s_add_u32 s6, s80, 0x20000
	s_addc_u32 s7, s81, 0
	s_mov_b32 m0, s52
	s_nop 0
	global_load_lds_dwordx4 v128, s[6:7]
	s_mov_b32 m0, s53
	s_nop 0
	global_load_lds_dwordx4 v130, s[6:7]
	s_waitcnt vmcnt(8)
	s_waitcnt lgkmcnt(0)
	s_barrier
; #define PG8_STAGE(bufoff, gbase, voff) do { _Pragma("unroll") for (int _i = 0; _i < 2; ++_i) { \
;         const unsigned _m0 = ldsu + (unsigned)(bufoff) + ldsw + (unsigned)(_i * 8192); \
;         asm volatile("s_mov_b32 m0, %2\n\ts_nop 0\n\tglobal_load_lds_dwordx4 %0, %1" :: "v"((voff)[_i]), "s"((const char*)(gbase)), "s"(_m0) : "memory"); } } while (0)
; #define PG8_LDA(dst, b, h) do { _Pragma("unroll") for (int m = 0; m < 4; ++m) _Pragma("unroll") for (int k = 0; k < 2; ++k) dst[m][k] = *(const LAS bf16x8*)(lds + PG8_SA(b, h) + aoff + m * 2048 + k * 1024); } while (0)
; #define PG8_LDB(dst, b, h) do { _Pragma("unroll") for (int n = 0; n < 2; ++n) _Pragma("unroll") for (int k = 0; k < 2; ++k) dst[n][k] = *(const LAS bf16x8*)(lds + bbase[b][h] + n * 2048 + k * 1024); } while (0)
; #define PG8_WAIT_V(n) asm volatile("s_waitcnt vmcnt(" #n ")" ::: "memory")
; #define PG8_WAIT_L(n) asm volatile("s_waitcnt lgkmcnt(" #n ")" ::: "memory")
; #define PG8_BAR __builtin_amdgcn_s_barrier()
; #define PG8_SCHED __builtin_amdgcn_sched_barrier(0)
; template <class Epi>
; __device__ __forceinline__ void gemm_phase(LAS unsigned char* lds, const Gemm g, const StaticOrder& S, const Epi& E) {
;     ...
;             PG8_WAIT_V(8); PG8_WAIT_L(0); PG8_BAR; PG8_MMA2B(1, At, At2, B0); PG8_BAR; PG8_SCHED;
;             PG8_LDB(B0, 1, 0); PG8_SCHED; PG8_LDA(At, 1, 0); PG8_LDA(At2, 1, 1); PG8_STAGE(PG8_SB(0, 1), b2 + hstepB, voffB);
;             PG8_WAIT_V(8); PG8_WAIT_L(0); PG8_BAR; PG8_MMA2B(0, At, At2, B0); PG8_BAR; PG8_SCHED;
	s_setprio 0
	s_waitcnt lgkmcnt(3)
	v_mfma_f32_16x16x32_bf16 v[116:119], v[140:143], v[156:159], v[116:119]
	s_waitcnt lgkmcnt(1)
	v_mfma_f32_16x16x32_bf16 v[112:115], v[148:151], v[156:159], v[112:115]
	v_mfma_f32_16x16x32_bf16 v[100:103], v[140:143], v[178:181], v[100:103]
	v_mfma_f32_16x16x32_bf16 v[96:99], v[148:151], v[178:181], v[96:99]
	v_mfma_f32_16x16x32_bf16 v[84:87], v[140:143], v[186:189], v[84:87]
	v_mfma_f32_16x16x32_bf16 v[80:83], v[148:151], v[186:189], v[80:83]
	v_mfma_f32_16x16x32_bf16 v[68:71], v[140:143], v[194:197], v[68:71]
	v_mfma_f32_16x16x32_bf16 v[64:67], v[148:151], v[194:197], v[64:67]
	v_mfma_f32_16x16x32_bf16 v[52:55], v[140:143], v[202:205], v[52:55]
	v_mfma_f32_16x16x32_bf16 v[48:51], v[148:151], v[202:205], v[48:51]
	v_mfma_f32_16x16x32_bf16 v[36:39], v[140:143], v[218:221], v[36:39]
	v_mfma_f32_16x16x32_bf16 v[32:35], v[148:151], v[218:221], v[32:35]
	v_mfma_f32_16x16x32_bf16 v[20:23], v[140:143], v[226:229], v[20:23]
	v_mfma_f32_16x16x32_bf16 v[16:19], v[148:151], v[226:229], v[16:19]
	v_mfma_f32_16x16x32_bf16 v[4:7], v[140:143], v[234:237], v[4:7]
	v_mfma_f32_16x16x32_bf16 v[0:3], v[148:151], v[234:237], v[0:3]
	v_mfma_f32_16x16x32_bf16 v[116:119], v[144:147], v[166:169], v[116:119]
	s_waitcnt lgkmcnt(0)
	v_mfma_f32_16x16x32_bf16 v[112:115], v[152:155], v[166:169], v[112:115]
	v_mfma_f32_16x16x32_bf16 v[100:103], v[144:147], v[182:185], v[100:103]
	v_mfma_f32_16x16x32_bf16 v[96:99], v[152:155], v[182:185], v[96:99]
	v_mfma_f32_16x16x32_bf16 v[84:87], v[144:147], v[190:193], v[84:87]
	v_mfma_f32_16x16x32_bf16 v[80:83], v[152:155], v[190:193], v[80:83]
	v_mfma_f32_16x16x32_bf16 v[68:71], v[144:147], v[198:201], v[68:71]
	v_mfma_f32_16x16x32_bf16 v[64:67], v[152:155], v[198:201], v[64:67]
	v_mfma_f32_16x16x32_bf16 v[52:55], v[144:147], v[214:217], v[52:55]
	v_mfma_f32_16x16x32_bf16 v[48:51], v[152:155], v[214:217], v[48:51]
	v_mfma_f32_16x16x32_bf16 v[36:39], v[144:147], v[222:225], v[36:39]
	v_mfma_f32_16x16x32_bf16 v[32:35], v[152:155], v[222:225], v[32:35]
	v_mfma_f32_16x16x32_bf16 v[20:23], v[144:147], v[230:233], v[20:23]
	v_mfma_f32_16x16x32_bf16 v[16:19], v[152:155], v[230:233], v[16:19]
	v_mfma_f32_16x16x32_bf16 v[4:7], v[144:147], v[238:241], v[4:7]
	v_mfma_f32_16x16x32_bf16 v[0:3], v[152:155], v[238:241], v[0:3]
	s_setprio 1
	s_barrier
	ds_read_b128 v[140:143], v137
	ds_read_b128 v[144:147], v137 offset:1024
	ds_read_b128 v[148:151], v137 offset:2048
	ds_read_b128 v[152:155], v137 offset:3072
	ds_read_b128 v[156:159], v135 offset:32768
	ds_read_b128 v[166:169], v135 offset:33792
	ds_read_b128 v[178:181], v135 offset:34816
	ds_read_b128 v[182:185], v135 offset:35840
	ds_read_b128 v[186:189], v135 offset:36864
	ds_read_b128 v[190:193], v135 offset:37888
	ds_read_b128 v[194:197], v135 offset:38912
	ds_read_b128 v[198:201], v135 offset:39936
	ds_read_b128 v[202:205], v135 offset:49152
	ds_read_b128 v[214:217], v135 offset:50176
	ds_read_b128 v[218:221], v135 offset:51200
	ds_read_b128 v[222:225], v135 offset:52224
	ds_read_b128 v[226:229], v135 offset:53248
	ds_read_b128 v[230:233], v135 offset:54272
	ds_read_b128 v[234:237], v135 offset:55296
	ds_read_b128 v[238:241], v135 offset:56320
	s_add_u32 s6, s90, 0x20000
	s_addc_u32 s7, s91, 0
	s_mov_b32 m0, s54
	s_nop 0
	global_load_lds_dwordx4 v129, s[6:7]
	s_mov_b32 m0, s55
	s_nop 0
	global_load_lds_dwordx4 v131, s[6:7]
	s_waitcnt vmcnt(8)
	s_waitcnt lgkmcnt(0)
	s_barrier
; #define PG8_STAGE(bufoff, gbase, voff) do { _Pragma("unroll") for (int _i = 0; _i < 2; ++_i) { \
;         const unsigned _m0 = ldsu + (unsigned)(bufoff) + ldsw + (unsigned)(_i * 8192); \
;         asm volatile("s_mov_b32 m0, %2\n\ts_nop 0\n\tglobal_load_lds_dwordx4 %0, %1" :: "v"((voff)[_i]), "s"((const char*)(gbase)), "s"(_m0) : "memory"); } } while (0)
; #define PG8_LDB(dst, b, h) do { _Pragma("unroll") for (int n = 0; n < 2; ++n) _Pragma("unroll") for (int k = 0; k < 2; ++k) dst[n][k] = *(const LAS bf16x8*)(lds + bbase[b][h] + n * 2048 + k * 1024); } while (0)
; #define PG8_WAIT_V(n) asm volatile("s_waitcnt vmcnt(" #n ")" ::: "memory")
; #define PG8_WAIT_L(n) asm volatile("s_waitcnt lgkmcnt(" #n ")" ::: "memory")
; #define PG8_BAR __builtin_amdgcn_s_barrier()
; #define PG8_SCHED __builtin_amdgcn_sched_barrier(0)
; template <class Epi>
; __device__ __forceinline__ void gemm_phase(LAS unsigned char* lds, const Gemm g, const StaticOrder& S, const Epi& E) {
;     ...
;             PG8_WAIT_V(8); PG8_WAIT_L(0); PG8_BAR; PG8_MMA2B(0, At, At2, B0); PG8_BAR; PG8_SCHED;
;             PG8_LDB(B0, 1, 1); PG8_STAGE(PG8_SB(1, 0), b3, voffB); PG8_STAGE(PG8_SA(1, 0), a3, voffA); PG8_STAGE(PG8_SA(1, 1), a3 + hstepA, voffA);
;             PG8_WAIT_V(8); PG8_WAIT_L(0); PG8_BAR; PG8_MMA2B(1, At, At2, B0); PG8_BAR; PG8_SCHED;
;         }
	s_setprio 0
	s_waitcnt lgkmcnt(14)
	v_mfma_f32_16x16x32_bf16 v[120:123], v[140:143], v[156:159], v[120:123]
	v_mfma_f32_16x16x32_bf16 v[124:127], v[148:151], v[156:159], v[124:127]
	s_waitcnt lgkmcnt(13)
	v_mfma_f32_16x16x32_bf16 v[108:111], v[140:143], v[178:181], v[108:111]
	v_mfma_f32_16x16x32_bf16 v[104:107], v[148:151], v[178:181], v[104:107]
	s_waitcnt lgkmcnt(11)
	v_mfma_f32_16x16x32_bf16 v[92:95], v[140:143], v[186:189], v[92:95]
	v_mfma_f32_16x16x32_bf16 v[88:91], v[148:151], v[186:189], v[88:91]
	s_waitcnt lgkmcnt(9)
	v_mfma_f32_16x16x32_bf16 v[76:79], v[140:143], v[194:197], v[76:79]
	v_mfma_f32_16x16x32_bf16 v[72:75], v[148:151], v[194:197], v[72:75]
	s_waitcnt lgkmcnt(7)
	v_mfma_f32_16x16x32_bf16 v[60:63], v[140:143], v[202:205], v[60:63]
	v_mfma_f32_16x16x32_bf16 v[56:59], v[148:151], v[202:205], v[56:59]
	s_waitcnt lgkmcnt(5)
	v_mfma_f32_16x16x32_bf16 v[44:47], v[140:143], v[218:221], v[44:47]
	v_mfma_f32_16x16x32_bf16 v[40:43], v[148:151], v[218:221], v[40:43]
	s_waitcnt lgkmcnt(3)
	v_mfma_f32_16x16x32_bf16 v[28:31], v[140:143], v[226:229], v[28:31]
	v_mfma_f32_16x16x32_bf16 v[24:27], v[148:151], v[226:229], v[24:27]
	s_waitcnt lgkmcnt(1)
	v_mfma_f32_16x16x32_bf16 v[12:15], v[140:143], v[234:237], v[12:15]
	v_mfma_f32_16x16x32_bf16 v[8:11], v[148:151], v[234:237], v[8:11]
	v_mfma_f32_16x16x32_bf16 v[120:123], v[144:147], v[166:169], v[120:123]
	v_mfma_f32_16x16x32_bf16 v[124:127], v[152:155], v[166:169], v[124:127]
	v_mfma_f32_16x16x32_bf16 v[108:111], v[144:147], v[182:185], v[108:111]
	v_mfma_f32_16x16x32_bf16 v[104:107], v[152:155], v[182:185], v[104:107]
	v_mfma_f32_16x16x32_bf16 v[92:95], v[144:147], v[190:193], v[92:95]
	v_mfma_f32_16x16x32_bf16 v[88:91], v[152:155], v[190:193], v[88:91]
	v_mfma_f32_16x16x32_bf16 v[76:79], v[144:147], v[198:201], v[76:79]
	v_mfma_f32_16x16x32_bf16 v[72:75], v[152:155], v[198:201], v[72:75]
	v_mfma_f32_16x16x32_bf16 v[60:63], v[144:147], v[214:217], v[60:63]
	v_mfma_f32_16x16x32_bf16 v[56:59], v[152:155], v[214:217], v[56:59]
	v_mfma_f32_16x16x32_bf16 v[44:47], v[144:147], v[222:225], v[44:47]
	v_mfma_f32_16x16x32_bf16 v[40:43], v[152:155], v[222:225], v[40:43]
	v_mfma_f32_16x16x32_bf16 v[28:31], v[144:147], v[230:233], v[28:31]
	v_mfma_f32_16x16x32_bf16 v[24:27], v[152:155], v[230:233], v[24:27]
	s_waitcnt lgkmcnt(0)
	v_mfma_f32_16x16x32_bf16 v[12:15], v[144:147], v[238:241], v[12:15]
	v_mfma_f32_16x16x32_bf16 v[8:11], v[152:155], v[238:241], v[8:11]
	s_setprio 1
	s_barrier
	ds_read_b128 v[140:143], v138
	ds_read_b128 v[144:147], v138 offset:1024
	ds_read_b128 v[148:151], v138 offset:2048
	ds_read_b128 v[152:155], v138 offset:3072
	s_mov_b32 m0, s56
	s_nop 0
	global_load_lds_dwordx4 v129, s[84:85]
	s_mov_b32 m0, s57
	s_nop 0
	global_load_lds_dwordx4 v131, s[84:85]
	s_mov_b32 m0, s58
	s_nop 0
	global_load_lds_dwordx4 v128, s[82:83]
	s_mov_b32 m0, s59
	s_nop 0
	global_load_lds_dwordx4 v130, s[82:83]
	s_add_u32 s6, s80, 0x20080
	s_addc_u32 s7, s81, 0
	s_mov_b32 m0, s60
	s_nop 0
	global_load_lds_dwordx4 v128, s[6:7]
	s_mov_b32 m0, s61
	s_nop 0
	global_load_lds_dwordx4 v130, s[6:7]
	s_waitcnt vmcnt(8)
	s_waitcnt lgkmcnt(0)
	s_barrier
	s_setprio 0
	s_waitcnt lgkmcnt(3)
	v_mfma_f32_16x16x32_bf16 v[116:119], v[140:143], v[156:159], v[116:119]
	s_waitcnt lgkmcnt(1)
	v_mfma_f32_16x16x32_bf16 v[112:115], v[148:151], v[156:159], v[112:115]
	v_mfma_f32_16x16x32_bf16 v[100:103], v[140:143], v[178:181], v[100:103]
	v_mfma_f32_16x16x32_bf16 v[96:99], v[148:151], v[178:181], v[96:99]
	v_mfma_f32_16x16x32_bf16 v[84:87], v[140:143], v[186:189], v[84:87]
	v_mfma_f32_16x16x32_bf16 v[80:83], v[148:151], v[186:189], v[80:83]
	v_mfma_f32_16x16x32_bf16 v[68:71], v[140:143], v[194:197], v[68:71]
	v_mfma_f32_16x16x32_bf16 v[64:67], v[148:151], v[194:197], v[64:67]
	v_mfma_f32_16x16x32_bf16 v[52:55], v[140:143], v[202:205], v[52:55]
	v_mfma_f32_16x16x32_bf16 v[48:51], v[148:151], v[202:205], v[48:51]
	v_mfma_f32_16x16x32_bf16 v[36:39], v[140:143], v[218:221], v[36:39]
	v_mfma_f32_16x16x32_bf16 v[32:35], v[148:151], v[218:221], v[32:35]
	v_mfma_f32_16x16x32_bf16 v[20:23], v[140:143], v[226:229], v[20:23]
	v_mfma_f32_16x16x32_bf16 v[16:19], v[148:151], v[226:229], v[16:19]
	v_mfma_f32_16x16x32_bf16 v[4:7], v[140:143], v[234:237], v[4:7]
	v_mfma_f32_16x16x32_bf16 v[0:3], v[148:151], v[234:237], v[0:3]
	v_mfma_f32_16x16x32_bf16 v[116:119], v[144:147], v[166:169], v[116:119]
	s_waitcnt lgkmcnt(0)
	v_mfma_f32_16x16x32_bf16 v[112:115], v[152:155], v[166:169], v[112:115]
	v_mfma_f32_16x16x32_bf16 v[100:103], v[144:147], v[182:185], v[100:103]
	v_mfma_f32_16x16x32_bf16 v[96:99], v[152:155], v[182:185], v[96:99]
	v_mfma_f32_16x16x32_bf16 v[84:87], v[144:147], v[190:193], v[84:87]
	v_mfma_f32_16x16x32_bf16 v[80:83], v[152:155], v[190:193], v[80:83]
	v_mfma_f32_16x16x32_bf16 v[68:71], v[144:147], v[198:201], v[68:71]
	v_mfma_f32_16x16x32_bf16 v[64:67], v[152:155], v[198:201], v[64:67]
	v_mfma_f32_16x16x32_bf16 v[52:55], v[144:147], v[214:217], v[52:55]
	v_mfma_f32_16x16x32_bf16 v[48:51], v[152:155], v[214:217], v[48:51]
	v_mfma_f32_16x16x32_bf16 v[36:39], v[144:147], v[222:225], v[36:39]
	v_mfma_f32_16x16x32_bf16 v[32:35], v[152:155], v[222:225], v[32:35]
	v_mfma_f32_16x16x32_bf16 v[20:23], v[144:147], v[230:233], v[20:23]
	v_mfma_f32_16x16x32_bf16 v[16:19], v[152:155], v[230:233], v[16:19]
	v_mfma_f32_16x16x32_bf16 v[4:7], v[144:147], v[238:241], v[4:7]
	v_mfma_f32_16x16x32_bf16 v[0:3], v[152:155], v[238:241], v[0:3]
	s_setprio 1
	s_barrier
	s_add_u32 s88, s88, 0x100
	s_addc_u32 s89, s89, 0
	s_add_u32 s95, s95, 0x100
	s_addc_u32 s96, s96, 0
	s_cmp_ge_i32 s69, s28
	s_mov_b32 s68, s69
	s_cbranch_scc0 .LBB0_487
	v_readlane_b32 s96, v252, 29
	v_readlane_b32 s97, v252, 30
	v_readlane_b32 s89, v255, 4
	v_readlane_b32 s95, v255, 2

; #define PG8_STAGE(bufoff, gbase, voff) do { _Pragma("unroll") for (int _i = 0; _i < 2; ++_i) { \
;         const unsigned _m0 = ldsu + (unsigned)(bufoff) + ldsw + (unsigned)(_i * 8192); \
;         asm volatile("s_mov_b32 m0, %2\n\ts_nop 0\n\tglobal_load_lds_dwordx4 %0, %1" :: "v"((voff)[_i]), "s"((const char*)(gbase)), "s"(_m0) : "memory"); } } while (0)
; #define PG8_LDA(dst, b, h) do { _Pragma("unroll") for (int m = 0; m < 4; ++m) _Pragma("unroll") for (int k = 0; k < 2; ++k) dst[m][k] = *(const LAS bf16x8*)(lds + PG8_SA(b, h) + aoff + m * 2048 + k * 1024); } while (0)
; #define PG8_LDB(dst, b, h) do { _Pragma("unroll") for (int n = 0; n < 2; ++n) _Pragma("unroll") for (int k = 0; k < 2; ++k) dst[n][k] = *(const LAS bf16x8*)(lds + bbase[b][h] + n * 2048 + k * 1024); } while (0)
; #define PG8_WAIT_V(n) asm volatile("s_waitcnt vmcnt(" #n ")" ::: "memory")
; #define PG8_WAIT_L(n) asm volatile("s_waitcnt lgkmcnt(" #n ")" ::: "memory")
; #define PG8_BAR __builtin_amdgcn_s_barrier()
; #define PG8_SCHED __builtin_amdgcn_sched_barrier(0)
; template <class Epi>
; __device__ __forceinline__ void gemm_phase(LAS unsigned char* lds, const Gemm g, const StaticOrder& S, const Epi& E) {
;     ...
;             const bool last = (t == nt - 2);
;             const char* a2 = last ? nA : cA + (size_t)(t + 2) * kstep; const char* b2 = last ? nB : cB + (size_t)(t + 2) * kstep;
;             const char* a3 = a2 + kstep; const char* b3 = b2 + kstep;
;             const char* b1 = cB + (size_t)(t + 1) * kstep;
;             PG8_LDB(B0, 0, 0); PG8_SCHED; PG8_LDA(At, 0, 0); PG8_LDA(At2, 0, 1); PG8_STAGE(PG8_SB(1, 1), b1 + hstepB, voffB);
;             PG8_WAIT_V(8); PG8_WAIT_L(0); PG8_BAR; PG8_MMA2B(0, At, At2, B0); PG8_BAR; PG8_SCHED;
;             PG8_LDB(B0, 0, 1); PG8_STAGE(PG8_SB(0, 0), b2, voffB); PG8_STAGE(PG8_SA(0, 0), a2, voffA); PG8_STAGE(PG8_SA(0, 1), a2 + hstepA, voffA);
;             PG8_WAIT_V(8); PG8_WAIT_L(0); PG8_BAR; PG8_MMA2B(1, At, At2, B0); PG8_BAR; PG8_SCHED;
.LBB0_509:
	s_add_i32 s63, s4, 2
	s_add_u32 s38, s59, 0x80
	ds_read_b128 v[128:131], v144
	ds_read_b128 v[132:135], v144 offset:1024
	ds_read_b128 v[150:153], v144 offset:2048
	ds_read_b128 v[154:157], v144 offset:3072
	s_addc_u32 s39, s60, 0
	s_cmp_eq_u32 s51, s4
	s_cselect_b32 s4, s15, s61
	s_cselect_b32 s5, s13, s62
	s_cselect_b32 s82, s58, s38
	s_cselect_b32 s83, s57, s39
	s_add_u32 s38, s4, 0x80
	s_addc_u32 s39, s5, 0
	s_add_u32 s80, s82, 0x80
	s_addc_u32 s81, s83, 0
	ds_read_b128 v[166:169], v145
	ds_read_b128 v[178:181], v145 offset:1024
	ds_read_b128 v[182:185], v145 offset:2048
	ds_read_b128 v[186:189], v145 offset:3072
	ds_read_b128 v[190:193], v145 offset:4096
	ds_read_b128 v[194:197], v145 offset:5120
	ds_read_b128 v[198:201], v145 offset:6144
	ds_read_b128 v[202:205], v145 offset:7168
	ds_read_b128 v[214:217], v145 offset:16384
	ds_read_b128 v[218:221], v145 offset:17408
	ds_read_b128 v[222:225], v145 offset:18432
	ds_read_b128 v[226:229], v145 offset:19456
	ds_read_b128 v[230:233], v145 offset:20480
	ds_read_b128 v[234:237], v145 offset:21504
	ds_read_b128 v[238:241], v145 offset:22528
	ds_read_b128 v[242:245], v145 offset:23552
	s_add_u32 s64, s59, 0x20000
	s_addc_u32 s65, s60, 0
	s_mov_b32 m0, s52
	s_nop 0
	global_load_lds_dwordx4 v141, s[64:65]
	s_mov_b32 m0, s53
	s_nop 0
	global_load_lds_dwordx4 v143, s[64:65]
	s_waitcnt vmcnt(8)
	s_waitcnt lgkmcnt(0)
	s_barrier
	s_setprio 0
	s_waitcnt lgkmcnt(14)
	v_mfma_f32_16x16x32_bf16 v[120:123], v[128:131], v[166:169], v[120:123]
	v_mfma_f32_16x16x32_bf16 v[124:127], v[150:153], v[166:169], v[124:127]
	s_waitcnt lgkmcnt(13)
	v_mfma_f32_16x16x32_bf16 v[108:111], v[128:131], v[182:185], v[108:111]
	v_mfma_f32_16x16x32_bf16 v[104:107], v[150:153], v[182:185], v[104:107]
	s_waitcnt lgkmcnt(11)
	v_mfma_f32_16x16x32_bf16 v[92:95], v[128:131], v[190:193], v[92:95]
	v_mfma_f32_16x16x32_bf16 v[88:91], v[150:153], v[190:193], v[88:91]
	s_waitcnt lgkmcnt(9)
	v_mfma_f32_16x16x32_bf16 v[76:79], v[128:131], v[198:201], v[76:79]
	v_mfma_f32_16x16x32_bf16 v[72:75], v[150:153], v[198:201], v[72:75]
	s_waitcnt lgkmcnt(7)
	v_mfma_f32_16x16x32_bf16 v[60:63], v[128:131], v[214:217], v[60:63]
	v_mfma_f32_16x16x32_bf16 v[56:59], v[150:153], v[214:217], v[56:59]
	s_waitcnt lgkmcnt(5)
	v_mfma_f32_16x16x32_bf16 v[44:47], v[128:131], v[222:225], v[44:47]
	v_mfma_f32_16x16x32_bf16 v[40:43], v[150:153], v[222:225], v[40:43]
	s_waitcnt lgkmcnt(3)
	v_mfma_f32_16x16x32_bf16 v[28:31], v[128:131], v[230:233], v[28:31]
	v_mfma_f32_16x16x32_bf16 v[24:27], v[150:153], v[230:233], v[24:27]
	s_waitcnt lgkmcnt(1)
	v_mfma_f32_16x16x32_bf16 v[12:15], v[128:131], v[238:241], v[12:15]
	v_mfma_f32_16x16x32_bf16 v[8:11], v[150:153], v[238:241], v[8:11]
	v_mfma_f32_16x16x32_bf16 v[120:123], v[132:135], v[178:181], v[120:123]
	v_mfma_f32_16x16x32_bf16 v[124:127], v[154:157], v[178:181], v[124:127]
	v_mfma_f32_16x16x32_bf16 v[108:111], v[132:135], v[186:189], v[108:111]
	v_mfma_f32_16x16x32_bf16 v[104:107], v[154:157], v[186:189], v[104:107]
	v_mfma_f32_16x16x32_bf16 v[92:95], v[132:135], v[194:197], v[92:95]
	v_mfma_f32_16x16x32_bf16 v[88:91], v[154:157], v[194:197], v[88:91]
	v_mfma_f32_16x16x32_bf16 v[76:79], v[132:135], v[202:205], v[76:79]
	v_mfma_f32_16x16x32_bf16 v[72:75], v[154:157], v[202:205], v[72:75]
	v_mfma_f32_16x16x32_bf16 v[60:63], v[132:135], v[218:221], v[60:63]
	v_mfma_f32_16x16x32_bf16 v[56:59], v[154:157], v[218:221], v[56:59]
	v_mfma_f32_16x16x32_bf16 v[44:47], v[132:135], v[226:229], v[44:47]
	v_mfma_f32_16x16x32_bf16 v[40:43], v[154:157], v[226:229], v[40:43]
	v_mfma_f32_16x16x32_bf16 v[28:31], v[132:135], v[234:237], v[28:31]
	v_mfma_f32_16x16x32_bf16 v[24:27], v[154:157], v[234:237], v[24:27]
	s_waitcnt lgkmcnt(0)
	v_mfma_f32_16x16x32_bf16 v[12:15], v[132:135], v[242:245], v[12:15]
	v_mfma_f32_16x16x32_bf16 v[8:11], v[154:157], v[242:245], v[8:11]
	s_setprio 1
	s_barrier
	ds_read_b128 v[128:131], v146
	ds_read_b128 v[132:135], v146 offset:1024
	ds_read_b128 v[150:153], v146 offset:2048
	ds_read_b128 v[154:157], v146 offset:3072
	s_mov_b32 m0, s85
	s_nop 0
	global_load_lds_dwordx4 v141, s[82:83]
	s_mov_b32 m0, s86
	s_nop 0
	global_load_lds_dwordx4 v143, s[82:83]
	s_mov_b32 m0, s84
	s_nop 0
	global_load_lds_dwordx4 v140, s[4:5]
	s_mov_b32 m0, s87
	s_nop 0
	global_load_lds_dwordx4 v142, s[4:5]
	s_add_u32 s64, s4, 0x20000
	s_addc_u32 s65, s5, 0
	s_mov_b32 m0, s88
	s_nop 0
	global_load_lds_dwordx4 v140, s[64:65]
	s_mov_b32 m0, s89
	s_nop 0
	global_load_lds_dwordx4 v142, s[64:65]
	s_waitcnt vmcnt(8)
	s_waitcnt lgkmcnt(0)
	s_barrier
; #define PG8_STAGE(bufoff, gbase, voff) do { _Pragma("unroll") for (int _i = 0; _i < 2; ++_i) { \
;         const unsigned _m0 = ldsu + (unsigned)(bufoff) + ldsw + (unsigned)(_i * 8192); \
;         asm volatile("s_mov_b32 m0, %2\n\ts_nop 0\n\tglobal_load_lds_dwordx4 %0, %1" :: "v"((voff)[_i]), "s"((const char*)(gbase)), "s"(_m0) : "memory"); } } while (0)
; #define PG8_LDA(dst, b, h) do { _Pragma("unroll") for (int m = 0; m < 4; ++m) _Pragma("unroll") for (int k = 0; k < 2; ++k) dst[m][k] = *(const LAS bf16x8*)(lds + PG8_SA(b, h) + aoff + m * 2048 + k * 1024); } while (0)
; #define PG8_LDB(dst, b, h) do { _Pragma("unroll") for (int n = 0; n < 2; ++n) _Pragma("unroll") for (int k = 0; k < 2; ++k) dst[n][k] = *(const LAS bf16x8*)(lds + bbase[b][h] + n * 2048 + k * 1024); } while (0)
; #define PG8_WAIT_V(n) asm volatile("s_waitcnt vmcnt(" #n ")" ::: "memory")
; #define PG8_WAIT_L(n) asm volatile("s_waitcnt lgkmcnt(" #n ")" ::: "memory")
; #define PG8_BAR __builtin_amdgcn_s_barrier()
; #define PG8_SCHED __builtin_amdgcn_sched_barrier(0)
; template <class Epi>
; __device__ __forceinline__ void gemm_phase(LAS unsigned char* lds, const Gemm g, const StaticOrder& S, const Epi& E) {
;     ...
;             PG8_WAIT_V(8); PG8_WAIT_L(0); PG8_BAR; PG8_MMA2B(1, At, At2, B0); PG8_BAR; PG8_SCHED;
;             PG8_LDB(B0, 1, 0); PG8_SCHED; PG8_LDA(At, 1, 0); PG8_LDA(At2, 1, 1); PG8_STAGE(PG8_SB(0, 1), b2 + hstepB, voffB);
;             PG8_WAIT_V(8); PG8_WAIT_L(0); PG8_BAR; PG8_MMA2B(0, At, At2, B0); PG8_BAR; PG8_SCHED;
	s_setprio 0
	s_waitcnt lgkmcnt(3)
	v_mfma_f32_16x16x32_bf16 v[116:119], v[128:131], v[166:169], v[116:119]
	s_waitcnt lgkmcnt(1)
	v_mfma_f32_16x16x32_bf16 v[112:115], v[150:153], v[166:169], v[112:115]
	v_mfma_f32_16x16x32_bf16 v[100:103], v[128:131], v[182:185], v[100:103]
	v_mfma_f32_16x16x32_bf16 v[96:99], v[150:153], v[182:185], v[96:99]
	v_mfma_f32_16x16x32_bf16 v[84:87], v[128:131], v[190:193], v[84:87]
	v_mfma_f32_16x16x32_bf16 v[80:83], v[150:153], v[190:193], v[80:83]
	v_mfma_f32_16x16x32_bf16 v[68:71], v[128:131], v[198:201], v[68:71]
	v_mfma_f32_16x16x32_bf16 v[64:67], v[150:153], v[198:201], v[64:67]
	v_mfma_f32_16x16x32_bf16 v[52:55], v[128:131], v[214:217], v[52:55]
	v_mfma_f32_16x16x32_bf16 v[48:51], v[150:153], v[214:217], v[48:51]
	v_mfma_f32_16x16x32_bf16 v[36:39], v[128:131], v[222:225], v[36:39]
	v_mfma_f32_16x16x32_bf16 v[32:35], v[150:153], v[222:225], v[32:35]
	v_mfma_f32_16x16x32_bf16 v[20:23], v[128:131], v[230:233], v[20:23]
	v_mfma_f32_16x16x32_bf16 v[16:19], v[150:153], v[230:233], v[16:19]
	v_mfma_f32_16x16x32_bf16 v[4:7], v[128:131], v[238:241], v[4:7]
	v_mfma_f32_16x16x32_bf16 v[0:3], v[150:153], v[238:241], v[0:3]
	v_mfma_f32_16x16x32_bf16 v[116:119], v[132:135], v[178:181], v[116:119]
	s_waitcnt lgkmcnt(0)
	v_mfma_f32_16x16x32_bf16 v[112:115], v[154:157], v[178:181], v[112:115]
	v_mfma_f32_16x16x32_bf16 v[100:103], v[132:135], v[186:189], v[100:103]
	v_mfma_f32_16x16x32_bf16 v[96:99], v[154:157], v[186:189], v[96:99]
	v_mfma_f32_16x16x32_bf16 v[84:87], v[132:135], v[194:197], v[84:87]
	v_mfma_f32_16x16x32_bf16 v[80:83], v[154:157], v[194:197], v[80:83]
	v_mfma_f32_16x16x32_bf16 v[68:71], v[132:135], v[202:205], v[68:71]
	v_mfma_f32_16x16x32_bf16 v[64:67], v[154:157], v[202:205], v[64:67]
	v_mfma_f32_16x16x32_bf16 v[52:55], v[132:135], v[218:221], v[52:55]
	v_mfma_f32_16x16x32_bf16 v[48:51], v[154:157], v[218:221], v[48:51]
	v_mfma_f32_16x16x32_bf16 v[36:39], v[132:135], v[226:229], v[36:39]
	v_mfma_f32_16x16x32_bf16 v[32:35], v[154:157], v[226:229], v[32:35]
	v_mfma_f32_16x16x32_bf16 v[20:23], v[132:135], v[234:237], v[20:23]
	v_mfma_f32_16x16x32_bf16 v[16:19], v[154:157], v[234:237], v[16:19]
	v_mfma_f32_16x16x32_bf16 v[4:7], v[132:135], v[242:245], v[4:7]
	v_mfma_f32_16x16x32_bf16 v[0:3], v[154:157], v[242:245], v[0:3]
	s_setprio 1
	s_barrier
	ds_read_b128 v[128:131], v147
	ds_read_b128 v[132:135], v147 offset:1024
	ds_read_b128 v[150:153], v147 offset:2048
	ds_read_b128 v[154:157], v147 offset:3072
	ds_read_b128 v[166:169], v145 offset:32768
	ds_read_b128 v[178:181], v145 offset:33792
	ds_read_b128 v[182:185], v145 offset:34816
	ds_read_b128 v[186:189], v145 offset:35840
	ds_read_b128 v[190:193], v145 offset:36864
	ds_read_b128 v[194:197], v145 offset:37888
	ds_read_b128 v[198:201], v145 offset:38912
	ds_read_b128 v[202:205], v145 offset:39936
	ds_read_b128 v[214:217], v145 offset:49152
	ds_read_b128 v[218:221], v145 offset:50176
	ds_read_b128 v[222:225], v145 offset:51200
	ds_read_b128 v[226:229], v145 offset:52224
	ds_read_b128 v[230:233], v145 offset:53248
	ds_read_b128 v[234:237], v145 offset:54272
	ds_read_b128 v[238:241], v145 offset:55296
	ds_read_b128 v[242:245], v145 offset:56320
	s_add_u32 s64, s82, 0x20000
	s_addc_u32 s65, s83, 0
	s_mov_b32 m0, s90
	s_nop 0
	global_load_lds_dwordx4 v141, s[64:65]
	s_mov_b32 m0, s91
	s_nop 0
	global_load_lds_dwordx4 v143, s[64:65]
	s_waitcnt vmcnt(8)
	s_waitcnt lgkmcnt(0)
	s_barrier
; #define PG8_STAGE(bufoff, gbase, voff) do { _Pragma("unroll") for (int _i = 0; _i < 2; ++_i) { \
;         const unsigned _m0 = ldsu + (unsigned)(bufoff) + ldsw + (unsigned)(_i * 8192); \
;         asm volatile("s_mov_b32 m0, %2\n\ts_nop 0\n\tglobal_load_lds_dwordx4 %0, %1" :: "v"((voff)[_i]), "s"((const char*)(gbase)), "s"(_m0) : "memory"); } } while (0)
; #define PG8_LDB(dst, b, h) do { _Pragma("unroll") for (int n = 0; n < 2; ++n) _Pragma("unroll") for (int k = 0; k < 2; ++k) dst[n][k] = *(const LAS bf16x8*)(lds + bbase[b][h] + n * 2048 + k * 1024); } while (0)
; #define PG8_WAIT_V(n) asm volatile("s_waitcnt vmcnt(" #n ")" ::: "memory")
; #define PG8_WAIT_L(n) asm volatile("s_waitcnt lgkmcnt(" #n ")" ::: "memory")
; #define PG8_BAR __builtin_amdgcn_s_barrier()
; #define PG8_SCHED __builtin_amdgcn_sched_barrier(0)
; template <class Epi>
; __device__ __forceinline__ void gemm_phase(LAS unsigned char* lds, const Gemm g, const StaticOrder& S, const Epi& E) {
;     ...
;             PG8_WAIT_V(8); PG8_WAIT_L(0); PG8_BAR; PG8_MMA2B(0, At, At2, B0); PG8_BAR; PG8_SCHED;
;             PG8_LDB(B0, 1, 1); PG8_STAGE(PG8_SB(1, 0), b3, voffB); PG8_STAGE(PG8_SA(1, 0), a3, voffA); PG8_STAGE(PG8_SA(1, 1), a3 + hstepA, voffA);
;             PG8_WAIT_V(8); PG8_WAIT_L(0); PG8_BAR; PG8_MMA2B(1, At, At2, B0); PG8_BAR; PG8_SCHED;
;         }
	s_setprio 0
	s_waitcnt lgkmcnt(14)
	v_mfma_f32_16x16x32_bf16 v[120:123], v[128:131], v[166:169], v[120:123]
	v_mfma_f32_16x16x32_bf16 v[124:127], v[150:153], v[166:169], v[124:127]
	s_waitcnt lgkmcnt(13)
	v_mfma_f32_16x16x32_bf16 v[108:111], v[128:131], v[182:185], v[108:111]
	v_mfma_f32_16x16x32_bf16 v[104:107], v[150:153], v[182:185], v[104:107]
	s_waitcnt lgkmcnt(11)
	v_mfma_f32_16x16x32_bf16 v[92:95], v[128:131], v[190:193], v[92:95]
	v_mfma_f32_16x16x32_bf16 v[88:91], v[150:153], v[190:193], v[88:91]
	s_waitcnt lgkmcnt(9)
	v_mfma_f32_16x16x32_bf16 v[76:79], v[128:131], v[198:201], v[76:79]
	v_mfma_f32_16x16x32_bf16 v[72:75], v[150:153], v[198:201], v[72:75]
	s_waitcnt lgkmcnt(7)
	v_mfma_f32_16x16x32_bf16 v[60:63], v[128:131], v[214:217], v[60:63]
	v_mfma_f32_16x16x32_bf16 v[56:59], v[150:153], v[214:217], v[56:59]
	s_waitcnt lgkmcnt(5)
	v_mfma_f32_16x16x32_bf16 v[44:47], v[128:131], v[222:225], v[44:47]
	v_mfma_f32_16x16x32_bf16 v[40:43], v[150:153], v[222:225], v[40:43]
	s_waitcnt lgkmcnt(3)
	v_mfma_f32_16x16x32_bf16 v[28:31], v[128:131], v[230:233], v[28:31]
	v_mfma_f32_16x16x32_bf16 v[24:27], v[150:153], v[230:233], v[24:27]
	s_waitcnt lgkmcnt(1)
	v_mfma_f32_16x16x32_bf16 v[12:15], v[128:131], v[238:241], v[12:15]
	v_mfma_f32_16x16x32_bf16 v[8:11], v[150:153], v[238:241], v[8:11]
	v_mfma_f32_16x16x32_bf16 v[120:123], v[132:135], v[178:181], v[120:123]
	v_mfma_f32_16x16x32_bf16 v[124:127], v[154:157], v[178:181], v[124:127]
	v_mfma_f32_16x16x32_bf16 v[108:111], v[132:135], v[186:189], v[108:111]
	v_mfma_f32_16x16x32_bf16 v[104:107], v[154:157], v[186:189], v[104:107]
	v_mfma_f32_16x16x32_bf16 v[92:95], v[132:135], v[194:197], v[92:95]
	v_mfma_f32_16x16x32_bf16 v[88:91], v[154:157], v[194:197], v[88:91]
	v_mfma_f32_16x16x32_bf16 v[76:79], v[132:135], v[202:205], v[76:79]
	v_mfma_f32_16x16x32_bf16 v[72:75], v[154:157], v[202:205], v[72:75]
	v_mfma_f32_16x16x32_bf16 v[60:63], v[132:135], v[218:221], v[60:63]
	v_mfma_f32_16x16x32_bf16 v[56:59], v[154:157], v[218:221], v[56:59]
	v_mfma_f32_16x16x32_bf16 v[44:47], v[132:135], v[226:229], v[44:47]
	v_mfma_f32_16x16x32_bf16 v[40:43], v[154:157], v[226:229], v[40:43]
	v_mfma_f32_16x16x32_bf16 v[28:31], v[132:135], v[234:237], v[28:31]
	v_mfma_f32_16x16x32_bf16 v[24:27], v[154:157], v[234:237], v[24:27]
	s_waitcnt lgkmcnt(0)
	v_mfma_f32_16x16x32_bf16 v[12:15], v[132:135], v[242:245], v[12:15]
	v_mfma_f32_16x16x32_bf16 v[8:11], v[154:157], v[242:245], v[8:11]
	s_setprio 1
	s_barrier
	ds_read_b128 v[128:131], v148
	ds_read_b128 v[132:135], v148 offset:1024
	ds_read_b128 v[150:153], v148 offset:2048
	ds_read_b128 v[154:157], v148 offset:3072
	s_mov_b32 m0, s97
	s_nop 0
	global_load_lds_dwordx4 v141, s[80:81]
	s_mov_b32 m0, s37
	s_nop 0
	global_load_lds_dwordx4 v143, s[80:81]
	s_mov_b32 m0, s95
	s_nop 0
	global_load_lds_dwordx4 v140, s[38:39]
	s_mov_b32 m0, s48
	s_nop 0
	global_load_lds_dwordx4 v142, s[38:39]
	s_add_u32 s4, s4, 0x20080
	s_addc_u32 s5, s5, 0
	s_mov_b32 m0, s49
	s_nop 0
	global_load_lds_dwordx4 v140, s[4:5]
	s_mov_b32 m0, s50
	s_nop 0
	global_load_lds_dwordx4 v142, s[4:5]
	s_waitcnt vmcnt(8)
	s_waitcnt lgkmcnt(0)
	s_barrier
	s_setprio 0
	s_waitcnt lgkmcnt(3)
	v_mfma_f32_16x16x32_bf16 v[116:119], v[128:131], v[166:169], v[116:119]
	s_waitcnt lgkmcnt(1)
	v_mfma_f32_16x16x32_bf16 v[112:115], v[150:153], v[166:169], v[112:115]
	v_mfma_f32_16x16x32_bf16 v[100:103], v[128:131], v[182:185], v[100:103]
	v_mfma_f32_16x16x32_bf16 v[96:99], v[150:153], v[182:185], v[96:99]
	v_mfma_f32_16x16x32_bf16 v[84:87], v[128:131], v[190:193], v[84:87]
	v_mfma_f32_16x16x32_bf16 v[80:83], v[150:153], v[190:193], v[80:83]
	v_mfma_f32_16x16x32_bf16 v[68:71], v[128:131], v[198:201], v[68:71]
	v_mfma_f32_16x16x32_bf16 v[64:67], v[150:153], v[198:201], v[64:67]
	v_mfma_f32_16x16x32_bf16 v[52:55], v[128:131], v[214:217], v[52:55]
	v_mfma_f32_16x16x32_bf16 v[48:51], v[150:153], v[214:217], v[48:51]
	v_mfma_f32_16x16x32_bf16 v[36:39], v[128:131], v[222:225], v[36:39]
	v_mfma_f32_16x16x32_bf16 v[32:35], v[150:153], v[222:225], v[32:35]
	v_mfma_f32_16x16x32_bf16 v[20:23], v[128:131], v[230:233], v[20:23]
	v_mfma_f32_16x16x32_bf16 v[16:19], v[150:153], v[230:233], v[16:19]
	v_mfma_f32_16x16x32_bf16 v[4:7], v[128:131], v[238:241], v[4:7]
	v_mfma_f32_16x16x32_bf16 v[0:3], v[150:153], v[238:241], v[0:3]
	v_mfma_f32_16x16x32_bf16 v[116:119], v[132:135], v[178:181], v[116:119]
	s_waitcnt lgkmcnt(0)
	v_mfma_f32_16x16x32_bf16 v[112:115], v[154:157], v[178:181], v[112:115]
	v_mfma_f32_16x16x32_bf16 v[100:103], v[132:135], v[186:189], v[100:103]
	v_mfma_f32_16x16x32_bf16 v[96:99], v[154:157], v[186:189], v[96:99]
	v_mfma_f32_16x16x32_bf16 v[84:87], v[132:135], v[194:197], v[84:87]
	v_mfma_f32_16x16x32_bf16 v[80:83], v[154:157], v[194:197], v[80:83]
	v_mfma_f32_16x16x32_bf16 v[68:71], v[132:135], v[202:205], v[68:71]
	v_mfma_f32_16x16x32_bf16 v[64:67], v[154:157], v[202:205], v[64:67]
	v_mfma_f32_16x16x32_bf16 v[52:55], v[132:135], v[218:221], v[52:55]
	v_mfma_f32_16x16x32_bf16 v[48:51], v[154:157], v[218:221], v[48:51]
	v_mfma_f32_16x16x32_bf16 v[36:39], v[132:135], v[226:229], v[36:39]
	v_mfma_f32_16x16x32_bf16 v[32:35], v[154:157], v[226:229], v[32:35]
	v_mfma_f32_16x16x32_bf16 v[20:23], v[132:135], v[234:237], v[20:23]
	v_mfma_f32_16x16x32_bf16 v[16:19], v[154:157], v[234:237], v[16:19]
	v_mfma_f32_16x16x32_bf16 v[4:7], v[132:135], v[242:245], v[4:7]
	v_mfma_f32_16x16x32_bf16 v[0:3], v[154:157], v[242:245], v[0:3]
	s_setprio 1
	s_barrier
	s_add_u32 s59, s59, 0x100
	s_addc_u32 s60, s60, 0
	s_add_u32 s61, s61, 0x100
	s_addc_u32 s62, s62, 0
	s_cmp_ge_i32 s63, s28
	s_mov_b32 s4, s63
	s_cbranch_scc0 .LBB0_509
	v_readlane_b32 s60, v252, 25
	v_readlane_b32 s62, v252, 27
	v_readlane_b32 s64, v252, 9
	v_readlane_b32 s61, v252, 26
	v_readlane_b32 s63, v252, 28
	v_readlane_b32 s65, v252, 10

; #define PG8_STAGE(bufoff, gbase, voff) do { _Pragma("unroll") for (int _i = 0; _i < 2; ++_i) { \
;         const unsigned _m0 = ldsu + (unsigned)(bufoff) + ldsw + (unsigned)(_i * 8192); \
;         asm volatile("s_mov_b32 m0, %2\n\ts_nop 0\n\tglobal_load_lds_dwordx4 %0, %1" :: "v"((voff)[_i]), "s"((const char*)(gbase)), "s"(_m0) : "memory"); } } while (0)
; #define PG8_LDA(dst, b, h) do { _Pragma("unroll") for (int m = 0; m < 4; ++m) _Pragma("unroll") for (int k = 0; k < 2; ++k) dst[m][k] = *(const LAS bf16x8*)(lds + PG8_SA(b, h) + aoff + m * 2048 + k * 1024); } while (0)
; #define PG8_LDB(dst, b, h) do { _Pragma("unroll") for (int n = 0; n < 2; ++n) _Pragma("unroll") for (int k = 0; k < 2; ++k) dst[n][k] = *(const LAS bf16x8*)(lds + bbase[b][h] + n * 2048 + k * 1024); } while (0)
; #define PG8_WAIT_V(n) asm volatile("s_waitcnt vmcnt(" #n ")" ::: "memory")
; #define PG8_WAIT_L(n) asm volatile("s_waitcnt lgkmcnt(" #n ")" ::: "memory")
; #define PG8_BAR __builtin_amdgcn_s_barrier()
; #define PG8_SCHED __builtin_amdgcn_sched_barrier(0)
; template <class Epi>
; __device__ __forceinline__ void gemm_phase(LAS unsigned char* lds, const Gemm g, const StaticOrder& S, const Epi& E) {
;     ...
;             const bool last = (t == nt - 2);
;             const char* a2 = last ? nA : cA + (size_t)(t + 2) * kstep; const char* b2 = last ? nB : cB + (size_t)(t + 2) * kstep;
;             const char* a3 = a2 + kstep; const char* b3 = b2 + kstep;
;             const char* b1 = cB + (size_t)(t + 1) * kstep;
;             PG8_LDB(B0, 0, 0); PG8_SCHED; PG8_LDA(At, 0, 0); PG8_LDA(At2, 0, 1); PG8_STAGE(PG8_SB(1, 1), b1 + hstepB, voffB);
;             PG8_WAIT_V(8); PG8_WAIT_L(0); PG8_BAR; PG8_MMA2B(0, At, At2, B0); PG8_BAR; PG8_SCHED;
;             PG8_LDB(B0, 0, 1); PG8_STAGE(PG8_SB(0, 0), b2, voffB); PG8_STAGE(PG8_SA(0, 0), a2, voffA); PG8_STAGE(PG8_SA(0, 1), a2 + hstepA, voffA);
;             PG8_WAIT_V(8); PG8_WAIT_L(0); PG8_BAR; PG8_MMA2B(1, At, At2, B0); PG8_BAR; PG8_SCHED;
.LBB0_584:
	ds_read_b128 v[128:131], v155
	ds_read_b128 v[132:135], v155 offset:1024
	ds_read_b128 v[136:139], v155 offset:2048
	ds_read_b128 v[140:143], v155 offset:3072
	s_add_u32 s10, s8, 0x100
	s_addc_u32 s11, s9, 0
	s_cmp_eq_u32 s68, 12
	s_cselect_b32 s84, s67, s87
	s_cselect_b32 s85, s43, s88
	s_cselect_b32 s90, s86, s10
	s_cselect_b32 s91, s39, s11
	s_add_u32 s96, s84, 0x80
	s_addc_u32 s97, s85, 0
	ds_read_b128 v[144:147], v156
	ds_read_b128 v[178:181], v156 offset:1024
	ds_read_b128 v[182:185], v156 offset:2048
	ds_read_b128 v[186:189], v156 offset:3072
	ds_read_b128 v[190:193], v156 offset:4096
	ds_read_b128 v[194:197], v156 offset:5120
	ds_read_b128 v[198:201], v156 offset:6144
	ds_read_b128 v[202:205], v156 offset:7168
	ds_read_b128 v[214:217], v156 offset:16384
	ds_read_b128 v[218:221], v156 offset:17408
	ds_read_b128 v[222:225], v156 offset:18432
	ds_read_b128 v[226:229], v156 offset:19456
	ds_read_b128 v[230:233], v156 offset:20480
	ds_read_b128 v[234:237], v156 offset:21504
	ds_read_b128 v[238:241], v156 offset:22528
	ds_read_b128 v[242:245], v156 offset:23552
	s_add_u32 s8, s8, 0x40080
	s_addc_u32 s9, s9, 0
	s_mov_b32 m0, s61
	s_nop 0
	global_load_lds_dwordx4 v151, s[8:9]
	s_mov_b32 m0, s64
	s_nop 0
	global_load_lds_dwordx4 v153, s[8:9]
	s_waitcnt vmcnt(8)
	s_waitcnt lgkmcnt(0)
	s_barrier
	s_setprio 0
	s_waitcnt lgkmcnt(14)
	v_mfma_f32_16x16x32_bf16 v[76:79], v[128:131], v[144:147], v[76:79]
	v_mfma_f32_16x16x32_bf16 v[72:75], v[136:139], v[144:147], v[72:75]
	s_waitcnt lgkmcnt(13)
	v_mfma_f32_16x16x32_bf16 v[64:67], v[128:131], v[182:185], v[64:67]
	v_mfma_f32_16x16x32_bf16 v[60:63], v[136:139], v[182:185], v[60:63]
	s_waitcnt lgkmcnt(11)
	v_mfma_f32_16x16x32_bf16 v[56:59], v[128:131], v[190:193], v[56:59]
	v_mfma_f32_16x16x32_bf16 v[52:55], v[136:139], v[190:193], v[52:55]
	s_waitcnt lgkmcnt(9)
	v_mfma_f32_16x16x32_bf16 v[112:115], v[128:131], v[198:201], v[112:115]
	v_mfma_f32_16x16x32_bf16 v[104:107], v[136:139], v[198:201], v[104:107]
	s_waitcnt lgkmcnt(7)
	v_mfma_f32_16x16x32_bf16 v[36:39], v[128:131], v[214:217], v[36:39]
	v_mfma_f32_16x16x32_bf16 v[32:35], v[136:139], v[214:217], v[32:35]
	s_waitcnt lgkmcnt(5)
	v_mfma_f32_16x16x32_bf16 v[28:31], v[128:131], v[222:225], v[28:31]
	v_mfma_f32_16x16x32_bf16 v[24:27], v[136:139], v[222:225], v[24:27]
	s_waitcnt lgkmcnt(3)
	v_mfma_f32_16x16x32_bf16 v[16:19], v[128:131], v[230:233], v[16:19]
	v_mfma_f32_16x16x32_bf16 v[12:15], v[136:139], v[230:233], v[12:15]
	s_waitcnt lgkmcnt(1)
	v_mfma_f32_16x16x32_bf16 v[88:91], v[128:131], v[238:241], v[88:91]
	v_mfma_f32_16x16x32_bf16 v[84:87], v[136:139], v[238:241], v[84:87]
	v_mfma_f32_16x16x32_bf16 v[76:79], v[132:135], v[178:181], v[76:79]
	v_mfma_f32_16x16x32_bf16 v[72:75], v[140:143], v[178:181], v[72:75]
	v_mfma_f32_16x16x32_bf16 v[64:67], v[132:135], v[186:189], v[64:67]
	v_mfma_f32_16x16x32_bf16 v[60:63], v[140:143], v[186:189], v[60:63]
	v_mfma_f32_16x16x32_bf16 v[56:59], v[132:135], v[194:197], v[56:59]
	v_mfma_f32_16x16x32_bf16 v[52:55], v[140:143], v[194:197], v[52:55]
	v_mfma_f32_16x16x32_bf16 v[112:115], v[132:135], v[202:205], v[112:115]
	v_mfma_f32_16x16x32_bf16 v[104:107], v[140:143], v[202:205], v[104:107]
	v_mfma_f32_16x16x32_bf16 v[36:39], v[132:135], v[218:221], v[36:39]
	v_mfma_f32_16x16x32_bf16 v[32:35], v[140:143], v[218:221], v[32:35]
	v_mfma_f32_16x16x32_bf16 v[28:31], v[132:135], v[226:229], v[28:31]
	v_mfma_f32_16x16x32_bf16 v[24:27], v[140:143], v[226:229], v[24:27]
	v_mfma_f32_16x16x32_bf16 v[16:19], v[132:135], v[234:237], v[16:19]
	v_mfma_f32_16x16x32_bf16 v[12:15], v[140:143], v[234:237], v[12:15]
	s_waitcnt lgkmcnt(0)
	v_mfma_f32_16x16x32_bf16 v[88:91], v[132:135], v[242:245], v[88:91]
	v_mfma_f32_16x16x32_bf16 v[84:87], v[140:143], v[242:245], v[84:87]
	s_setprio 1
	s_barrier
	ds_read_b128 v[128:131], v157
	ds_read_b128 v[132:135], v157 offset:1024
	ds_read_b128 v[136:139], v157 offset:2048
	ds_read_b128 v[140:143], v157 offset:3072
	s_mov_b32 m0, s47
	s_nop 0
	global_load_lds_dwordx4 v151, s[90:91]
	s_mov_b32 m0, s48
	s_nop 0
	global_load_lds_dwordx4 v153, s[90:91]
	s_mov_b32 m0, s37
	s_nop 0
	global_load_lds_dwordx4 v150, s[84:85]
	s_mov_b32 m0, s49
	s_nop 0
	global_load_lds_dwordx4 v152, s[84:85]
	s_add_u32 s8, s84, 0x40000
	s_addc_u32 s9, s85, 0
	s_mov_b32 m0, s50
	s_nop 0
	global_load_lds_dwordx4 v150, s[8:9]
	s_mov_b32 m0, s51
	s_nop 0
	global_load_lds_dwordx4 v152, s[8:9]
	s_waitcnt vmcnt(8)
	s_waitcnt lgkmcnt(0)
	s_barrier
	s_setprio 0
	s_waitcnt lgkmcnt(3)
	v_mfma_f32_16x16x32_bf16 v[68:71], v[128:131], v[144:147], v[68:71]
	s_waitcnt lgkmcnt(1)
	v_mfma_f32_16x16x32_bf16 v[124:127], v[136:139], v[144:147], v[124:127]
	v_mfma_f32_16x16x32_bf16 v[48:51], v[128:131], v[182:185], v[48:51]
	v_mfma_f32_16x16x32_bf16 v[120:123], v[136:139], v[182:185], v[120:123]
	v_mfma_f32_16x16x32_bf16 v[44:47], v[128:131], v[190:193], v[44:47]
	v_mfma_f32_16x16x32_bf16 v[116:119], v[136:139], v[190:193], v[116:119]
	v_mfma_f32_16x16x32_bf16 v[40:43], v[128:131], v[198:201], v[40:43]
	v_mfma_f32_16x16x32_bf16 v[108:111], v[136:139], v[198:201], v[108:111]
	v_mfma_f32_16x16x32_bf16 v[20:23], v[128:131], v[214:217], v[20:23]
	v_mfma_f32_16x16x32_bf16 v[100:103], v[136:139], v[214:217], v[100:103]
	v_mfma_f32_16x16x32_bf16 v[8:11], v[128:131], v[222:225], v[8:11]
	v_mfma_f32_16x16x32_bf16 v[96:99], v[136:139], v[222:225], v[96:99]
	v_mfma_f32_16x16x32_bf16 v[4:7], v[128:131], v[230:233], v[4:7]
	v_mfma_f32_16x16x32_bf16 v[92:95], v[136:139], v[230:233], v[92:95]
	v_mfma_f32_16x16x32_bf16 v[0:3], v[128:131], v[238:241], v[0:3]
	v_mfma_f32_16x16x32_bf16 v[80:83], v[136:139], v[238:241], v[80:83]
	v_mfma_f32_16x16x32_bf16 v[68:71], v[132:135], v[178:181], v[68:71]
	s_waitcnt lgkmcnt(0)
	v_mfma_f32_16x16x32_bf16 v[124:127], v[140:143], v[178:181], v[124:127]
	v_mfma_f32_16x16x32_bf16 v[48:51], v[132:135], v[186:189], v[48:51]
	v_mfma_f32_16x16x32_bf16 v[120:123], v[140:143], v[186:189], v[120:123]
	v_mfma_f32_16x16x32_bf16 v[44:47], v[132:135], v[194:197], v[44:47]
	v_mfma_f32_16x16x32_bf16 v[116:119], v[140:143], v[194:197], v[116:119]
	v_mfma_f32_16x16x32_bf16 v[40:43], v[132:135], v[202:205], v[40:43]
	v_mfma_f32_16x16x32_bf16 v[108:111], v[140:143], v[202:205], v[108:111]
	v_mfma_f32_16x16x32_bf16 v[20:23], v[132:135], v[218:221], v[20:23]
	v_mfma_f32_16x16x32_bf16 v[100:103], v[140:143], v[218:221], v[100:103]
	v_mfma_f32_16x16x32_bf16 v[8:11], v[132:135], v[226:229], v[8:11]
	v_mfma_f32_16x16x32_bf16 v[96:99], v[140:143], v[226:229], v[96:99]
	v_mfma_f32_16x16x32_bf16 v[4:7], v[132:135], v[234:237], v[4:7]
	v_mfma_f32_16x16x32_bf16 v[92:95], v[140:143], v[234:237], v[92:95]
	v_mfma_f32_16x16x32_bf16 v[0:3], v[132:135], v[242:245], v[0:3]
	v_mfma_f32_16x16x32_bf16 v[80:83], v[140:143], v[242:245], v[80:83]
	s_setprio 1
	s_barrier
; #define PG8_STAGE(bufoff, gbase, voff) do { _Pragma("unroll") for (int _i = 0; _i < 2; ++_i) { \
;         const unsigned _m0 = ldsu + (unsigned)(bufoff) + ldsw + (unsigned)(_i * 8192); \
;         asm volatile("s_mov_b32 m0, %2\n\ts_nop 0\n\tglobal_load_lds_dwordx4 %0, %1" :: "v"((voff)[_i]), "s"((const char*)(gbase)), "s"(_m0) : "memory"); } } while (0)
; #define PG8_LDA(dst, b, h) do { _Pragma("unroll") for (int m = 0; m < 4; ++m) _Pragma("unroll") for (int k = 0; k < 2; ++k) dst[m][k] = *(const LAS bf16x8*)(lds + PG8_SA(b, h) + aoff + m * 2048 + k * 1024); } while (0)
; #define PG8_LDB(dst, b, h) do { _Pragma("unroll") for (int n = 0; n < 2; ++n) _Pragma("unroll") for (int k = 0; k < 2; ++k) dst[n][k] = *(const LAS bf16x8*)(lds + bbase[b][h] + n * 2048 + k * 1024); } while (0)
; #define PG8_WAIT_V(n) asm volatile("s_waitcnt vmcnt(" #n ")" ::: "memory")
; #define PG8_WAIT_L(n) asm volatile("s_waitcnt lgkmcnt(" #n ")" ::: "memory")
; #define PG8_BAR __builtin_amdgcn_s_barrier()
; #define PG8_SCHED __builtin_amdgcn_sched_barrier(0)
; template <class Epi>
; __device__ __forceinline__ void gemm_phase(LAS unsigned char* lds, const Gemm g, const StaticOrder& S, const Epi& E) {
;     ...
;             PG8_LDB(B0, 1, 0); PG8_SCHED; PG8_LDA(At, 1, 0); PG8_LDA(At2, 1, 1); PG8_STAGE(PG8_SB(0, 1), b2 + hstepB, voffB);
;             PG8_WAIT_V(8); PG8_WAIT_L(0); PG8_BAR; PG8_MMA2B(0, At, At2, B0); PG8_BAR; PG8_SCHED;
;             PG8_LDB(B0, 1, 1); PG8_STAGE(PG8_SB(1, 0), b3, voffB); PG8_STAGE(PG8_SA(1, 0), a3, voffA); PG8_STAGE(PG8_SA(1, 1), a3 + hstepA, voffA);
;             PG8_WAIT_V(8); PG8_WAIT_L(0); PG8_BAR; PG8_MMA2B(1, At, At2, B0); PG8_BAR; PG8_SCHED;
;         }
;         if (wr == 0) PG8_BAR;
	ds_read_b128 v[128:131], v158
	ds_read_b128 v[132:135], v158 offset:1024
	ds_read_b128 v[136:139], v158 offset:2048
	ds_read_b128 v[140:143], v158 offset:3072
	ds_read_b128 v[144:147], v156 offset:32768
	ds_read_b128 v[178:181], v156 offset:33792
	ds_read_b128 v[182:185], v156 offset:34816
	ds_read_b128 v[186:189], v156 offset:35840
	ds_read_b128 v[190:193], v156 offset:36864
	ds_read_b128 v[194:197], v156 offset:37888
	ds_read_b128 v[198:201], v156 offset:38912
	ds_read_b128 v[202:205], v156 offset:39936
	ds_read_b128 v[214:217], v156 offset:49152
	ds_read_b128 v[218:221], v156 offset:50176
	ds_read_b128 v[222:225], v156 offset:51200
	ds_read_b128 v[226:229], v156 offset:52224
	ds_read_b128 v[230:233], v156 offset:53248
	ds_read_b128 v[234:237], v156 offset:54272
	ds_read_b128 v[238:241], v156 offset:55296
	ds_read_b128 v[242:245], v156 offset:56320
	s_add_u32 s8, s90, 0x40000
	s_addc_u32 s9, s91, 0
	s_mov_b32 m0, s52
	s_nop 0
	global_load_lds_dwordx4 v151, s[8:9]
	s_mov_b32 m0, s53
	s_nop 0
	global_load_lds_dwordx4 v153, s[8:9]
	s_waitcnt vmcnt(8)
	s_waitcnt lgkmcnt(0)
	s_barrier
	s_setprio 0
	s_waitcnt lgkmcnt(14)
	v_mfma_f32_16x16x32_bf16 v[76:79], v[128:131], v[144:147], v[76:79]
	v_mfma_f32_16x16x32_bf16 v[72:75], v[136:139], v[144:147], v[72:75]
	s_waitcnt lgkmcnt(13)
	v_mfma_f32_16x16x32_bf16 v[64:67], v[128:131], v[182:185], v[64:67]
	v_mfma_f32_16x16x32_bf16 v[60:63], v[136:139], v[182:185], v[60:63]
	s_waitcnt lgkmcnt(11)
	v_mfma_f32_16x16x32_bf16 v[56:59], v[128:131], v[190:193], v[56:59]
	v_mfma_f32_16x16x32_bf16 v[52:55], v[136:139], v[190:193], v[52:55]
	s_waitcnt lgkmcnt(9)
	v_mfma_f32_16x16x32_bf16 v[112:115], v[128:131], v[198:201], v[112:115]
	v_mfma_f32_16x16x32_bf16 v[104:107], v[136:139], v[198:201], v[104:107]
	s_waitcnt lgkmcnt(7)
	v_mfma_f32_16x16x32_bf16 v[36:39], v[128:131], v[214:217], v[36:39]
	v_mfma_f32_16x16x32_bf16 v[32:35], v[136:139], v[214:217], v[32:35]
	s_waitcnt lgkmcnt(5)
	v_mfma_f32_16x16x32_bf16 v[28:31], v[128:131], v[222:225], v[28:31]
	v_mfma_f32_16x16x32_bf16 v[24:27], v[136:139], v[222:225], v[24:27]
	s_waitcnt lgkmcnt(3)
	v_mfma_f32_16x16x32_bf16 v[16:19], v[128:131], v[230:233], v[16:19]
	v_mfma_f32_16x16x32_bf16 v[12:15], v[136:139], v[230:233], v[12:15]
	s_waitcnt lgkmcnt(1)
	v_mfma_f32_16x16x32_bf16 v[88:91], v[128:131], v[238:241], v[88:91]
	v_mfma_f32_16x16x32_bf16 v[84:87], v[136:139], v[238:241], v[84:87]
	v_mfma_f32_16x16x32_bf16 v[76:79], v[132:135], v[178:181], v[76:79]
	v_mfma_f32_16x16x32_bf16 v[72:75], v[140:143], v[178:181], v[72:75]
	v_mfma_f32_16x16x32_bf16 v[64:67], v[132:135], v[186:189], v[64:67]
	v_mfma_f32_16x16x32_bf16 v[60:63], v[140:143], v[186:189], v[60:63]
	v_mfma_f32_16x16x32_bf16 v[56:59], v[132:135], v[194:197], v[56:59]
	v_mfma_f32_16x16x32_bf16 v[52:55], v[140:143], v[194:197], v[52:55]
	v_mfma_f32_16x16x32_bf16 v[112:115], v[132:135], v[202:205], v[112:115]
	v_mfma_f32_16x16x32_bf16 v[104:107], v[140:143], v[202:205], v[104:107]
	v_mfma_f32_16x16x32_bf16 v[36:39], v[132:135], v[218:221], v[36:39]
	v_mfma_f32_16x16x32_bf16 v[32:35], v[140:143], v[218:221], v[32:35]
	v_mfma_f32_16x16x32_bf16 v[28:31], v[132:135], v[226:229], v[28:31]
	v_mfma_f32_16x16x32_bf16 v[24:27], v[140:143], v[226:229], v[24:27]
	v_mfma_f32_16x16x32_bf16 v[16:19], v[132:135], v[234:237], v[16:19]
	v_mfma_f32_16x16x32_bf16 v[12:15], v[140:143], v[234:237], v[12:15]
	s_waitcnt lgkmcnt(0)
	v_mfma_f32_16x16x32_bf16 v[88:91], v[132:135], v[242:245], v[88:91]
	v_mfma_f32_16x16x32_bf16 v[84:87], v[140:143], v[242:245], v[84:87]
	s_setprio 1
	s_barrier
	s_add_u32 s8, s90, 0x80
	ds_read_b128 v[128:131], v159
	ds_read_b128 v[132:135], v159 offset:1024
	ds_read_b128 v[136:139], v159 offset:2048
	ds_read_b128 v[140:143], v159 offset:3072
	s_addc_u32 s9, s91, 0
	s_mov_b32 m0, s55
	s_nop 0
	global_load_lds_dwordx4 v151, s[8:9]
	s_mov_b32 m0, s56
	s_nop 0
	global_load_lds_dwordx4 v153, s[8:9]
	s_mov_b32 m0, s57
	s_nop 0
	global_load_lds_dwordx4 v150, s[96:97]
	s_mov_b32 m0, s58
	s_nop 0
	global_load_lds_dwordx4 v152, s[96:97]
	s_add_u32 s8, s84, 0x40080
	s_addc_u32 s9, s85, 0
	s_mov_b32 m0, s59
	s_nop 0
	global_load_lds_dwordx4 v150, s[8:9]
	s_mov_b32 m0, s60
	s_nop 0
	global_load_lds_dwordx4 v152, s[8:9]
	s_waitcnt vmcnt(8)
	s_waitcnt lgkmcnt(0)
	s_barrier
	s_setprio 0
	s_waitcnt lgkmcnt(3)
	v_mfma_f32_16x16x32_bf16 v[68:71], v[128:131], v[144:147], v[68:71]
	s_waitcnt lgkmcnt(1)
	v_mfma_f32_16x16x32_bf16 v[124:127], v[136:139], v[144:147], v[124:127]
	v_mfma_f32_16x16x32_bf16 v[48:51], v[128:131], v[182:185], v[48:51]
	v_mfma_f32_16x16x32_bf16 v[120:123], v[136:139], v[182:185], v[120:123]
	v_mfma_f32_16x16x32_bf16 v[44:47], v[128:131], v[190:193], v[44:47]
	v_mfma_f32_16x16x32_bf16 v[116:119], v[136:139], v[190:193], v[116:119]
	v_mfma_f32_16x16x32_bf16 v[40:43], v[128:131], v[198:201], v[40:43]
	v_mfma_f32_16x16x32_bf16 v[108:111], v[136:139], v[198:201], v[108:111]
	v_mfma_f32_16x16x32_bf16 v[20:23], v[128:131], v[214:217], v[20:23]
	v_mfma_f32_16x16x32_bf16 v[100:103], v[136:139], v[214:217], v[100:103]
	v_mfma_f32_16x16x32_bf16 v[8:11], v[128:131], v[222:225], v[8:11]
	v_mfma_f32_16x16x32_bf16 v[96:99], v[136:139], v[222:225], v[96:99]
	v_mfma_f32_16x16x32_bf16 v[4:7], v[128:131], v[230:233], v[4:7]
	v_mfma_f32_16x16x32_bf16 v[92:95], v[136:139], v[230:233], v[92:95]
	v_mfma_f32_16x16x32_bf16 v[0:3], v[128:131], v[238:241], v[0:3]
	v_mfma_f32_16x16x32_bf16 v[80:83], v[136:139], v[238:241], v[80:83]
	v_mfma_f32_16x16x32_bf16 v[68:71], v[132:135], v[178:181], v[68:71]
	s_waitcnt lgkmcnt(0)
	v_mfma_f32_16x16x32_bf16 v[124:127], v[140:143], v[178:181], v[124:127]
	v_mfma_f32_16x16x32_bf16 v[48:51], v[132:135], v[186:189], v[48:51]
	v_mfma_f32_16x16x32_bf16 v[120:123], v[140:143], v[186:189], v[120:123]
	v_mfma_f32_16x16x32_bf16 v[44:47], v[132:135], v[194:197], v[44:47]
	v_mfma_f32_16x16x32_bf16 v[116:119], v[140:143], v[194:197], v[116:119]
	v_mfma_f32_16x16x32_bf16 v[40:43], v[132:135], v[202:205], v[40:43]
	v_mfma_f32_16x16x32_bf16 v[108:111], v[140:143], v[202:205], v[108:111]
	v_mfma_f32_16x16x32_bf16 v[20:23], v[132:135], v[218:221], v[20:23]
	v_mfma_f32_16x16x32_bf16 v[100:103], v[140:143], v[218:221], v[100:103]
	v_mfma_f32_16x16x32_bf16 v[8:11], v[132:135], v[226:229], v[8:11]
	v_mfma_f32_16x16x32_bf16 v[96:99], v[140:143], v[226:229], v[96:99]
	v_mfma_f32_16x16x32_bf16 v[4:7], v[132:135], v[234:237], v[4:7]
	v_mfma_f32_16x16x32_bf16 v[92:95], v[140:143], v[234:237], v[92:95]
	v_mfma_f32_16x16x32_bf16 v[0:3], v[132:135], v[242:245], v[0:3]
	v_mfma_f32_16x16x32_bf16 v[80:83], v[140:143], v[242:245], v[80:83]
	s_setprio 1
	s_barrier
	s_add_i32 s68, s68, 2
	s_add_u32 s87, s87, 0x100
	s_addc_u32 s88, s88, 0
	s_cmp_gt_u32 s68, 13
	s_mov_b64 s[8:9], s[10:11]
	s_cbranch_scc0 .LBB0_584
	s_and_b64 vcc, exec, s[4:5]
	s_cbranch_vccz .LBB0_587
	s_barrier

; #define PG8_STAGE(bufoff, gbase, voff) do { _Pragma("unroll") for (int _i = 0; _i < 2; ++_i) { \
;         const unsigned _m0 = ldsu + (unsigned)(bufoff) + ldsw + (unsigned)(_i * 8192); \
;         asm volatile("s_mov_b32 m0, %2\n\ts_nop 0\n\tglobal_load_lds_dwordx4 %0, %1" :: "v"((voff)[_i]), "s"((const char*)(gbase)), "s"(_m0) : "memory"); } } while (0)
; #define PG8_LDA(dst, b, h) do { _Pragma("unroll") for (int m = 0; m < 4; ++m) _Pragma("unroll") for (int k = 0; k < 2; ++k) dst[m][k] = *(const LAS bf16x8*)(lds + PG8_SA(b, h) + aoff + m * 2048 + k * 1024); } while (0)
; #define PG8_LDB(dst, b, h) do { _Pragma("unroll") for (int n = 0; n < 2; ++n) _Pragma("unroll") for (int k = 0; k < 2; ++k) dst[n][k] = *(const LAS bf16x8*)(lds + bbase[b][h] + n * 2048 + k * 1024); } while (0)
; #define PG8_WAIT_V(n) asm volatile("s_waitcnt vmcnt(" #n ")" ::: "memory")
; #define PG8_WAIT_L(n) asm volatile("s_waitcnt lgkmcnt(" #n ")" ::: "memory")
; #define PG8_BAR __builtin_amdgcn_s_barrier()
; #define PG8_SCHED __builtin_amdgcn_sched_barrier(0)
; template <class Epi>
; __device__ __forceinline__ void gemm_phase(LAS unsigned char* lds, const Gemm g, const StaticOrder& S, const Epi& E) {
;     ...
;             const bool last = (t == nt - 2);
;             const char* a2 = last ? nA : cA + (size_t)(t + 2) * kstep; const char* b2 = last ? nB : cB + (size_t)(t + 2) * kstep;
;             const char* a3 = a2 + kstep; const char* b3 = b2 + kstep;
;             const char* b1 = cB + (size_t)(t + 1) * kstep;
;             PG8_LDB(B0, 0, 0); PG8_SCHED; PG8_LDA(At, 0, 0); PG8_LDA(At2, 0, 1); PG8_STAGE(PG8_SB(1, 1), b1 + hstepB, voffB);
;             PG8_WAIT_V(8); PG8_WAIT_L(0); PG8_BAR; PG8_MMA2B(0, At, At2, B0); PG8_BAR; PG8_SCHED;
;             PG8_LDB(B0, 0, 1); PG8_STAGE(PG8_SB(0, 0), b2, voffB); PG8_STAGE(PG8_SA(0, 0), a2, voffA); PG8_STAGE(PG8_SA(0, 1), a2 + hstepA, voffA);
;             PG8_WAIT_V(8); PG8_WAIT_L(0); PG8_BAR; PG8_MMA2B(1, At, At2, B0); PG8_BAR; PG8_SCHED;
.LBB0_662:
	s_add_i32 s85, s38, 2
	s_add_u32 s42, s67, 0x80
	ds_read_b128 v[74:77], v71
	ds_read_b128 v[78:81], v71 offset:1024
	ds_read_b128 v[82:85], v71 offset:2048
	ds_read_b128 v[86:89], v71 offset:3072
	s_addc_u32 s43, s68, 0
	s_cmp_eq_u32 s62, s38
	s_cselect_b32 s38, s10, s69
	s_cselect_b32 s39, s11, s84
	s_cselect_b32 s82, s37, s42
	s_cselect_b32 s83, s13, s43
	s_add_u32 s42, s38, 0x80
	s_addc_u32 s43, s39, 0
	s_add_u32 s80, s82, 0x80
	s_addc_u32 s81, s83, 0
	ds_read_b128 v[90:93], v72
	ds_read_b128 v[94:97], v72 offset:1024
	ds_read_b128 v[98:101], v72 offset:2048
	ds_read_b128 v[102:105], v72 offset:3072
	ds_read_b128 v[106:109], v72 offset:4096
	ds_read_b128 v[110:113], v72 offset:5120
	ds_read_b128 v[114:117], v72 offset:6144
	ds_read_b128 v[118:121], v72 offset:7168
	ds_read_b128 v[122:125], v72 offset:16384
	ds_read_b128 v[126:129], v72 offset:17408
	ds_read_b128 v[130:133], v72 offset:18432
	ds_read_b128 v[134:137], v72 offset:19456
	ds_read_b128 v[138:141], v72 offset:20480
	ds_read_b128 v[142:145], v72 offset:21504
	ds_read_b128 v[146:149], v72 offset:22528
	ds_read_b128 v[150:153], v72 offset:23552
	s_add_u32 s86, s67, 0x10000
	s_addc_u32 s87, s68, 0
	s_mov_b32 m0, s63
	s_nop 0
	global_load_lds_dwordx4 v67, s[86:87]
	s_mov_b32 m0, s64
	s_nop 0
	global_load_lds_dwordx4 v69, s[86:87]
	s_waitcnt vmcnt(8)
	s_waitcnt lgkmcnt(0)
	s_barrier
	s_setprio 0
	s_waitcnt lgkmcnt(14)
	v_mfma_f32_16x16x32_bf16 v[60:63], v[74:77], v[90:93], v[60:63]
	v_mfma_f32_16x16x32_bf16 v[56:59], v[82:85], v[90:93], v[56:59]
	s_waitcnt lgkmcnt(13)
	v_mfma_f32_16x16x32_bf16 v[52:55], v[74:77], v[98:101], v[52:55]
	v_mfma_f32_16x16x32_bf16 v[48:51], v[82:85], v[98:101], v[48:51]
	s_waitcnt lgkmcnt(11)
	v_mfma_f32_16x16x32_bf16 v[44:47], v[74:77], v[106:109], v[44:47]
	v_mfma_f32_16x16x32_bf16 v[40:43], v[82:85], v[106:109], v[40:43]
	s_waitcnt lgkmcnt(9)
	v_mfma_f32_16x16x32_bf16 v[36:39], v[74:77], v[114:117], v[36:39]
	v_mfma_f32_16x16x32_bf16 v[32:35], v[82:85], v[114:117], v[32:35]
	s_waitcnt lgkmcnt(7)
	v_mfma_f32_16x16x32_bf16 v[28:31], v[74:77], v[122:125], v[28:31]
	v_mfma_f32_16x16x32_bf16 v[24:27], v[82:85], v[122:125], v[24:27]
	s_waitcnt lgkmcnt(5)
	v_mfma_f32_16x16x32_bf16 v[20:23], v[74:77], v[130:133], v[20:23]
	v_mfma_f32_16x16x32_bf16 v[16:19], v[82:85], v[130:133], v[16:19]
	s_waitcnt lgkmcnt(3)
	v_mfma_f32_16x16x32_bf16 v[12:15], v[74:77], v[138:141], v[12:15]
	v_mfma_f32_16x16x32_bf16 v[8:11], v[82:85], v[138:141], v[8:11]
	s_waitcnt lgkmcnt(1)
	v_mfma_f32_16x16x32_bf16 v[4:7], v[74:77], v[146:149], v[4:7]
	v_mfma_f32_16x16x32_bf16 v[0:3], v[82:85], v[146:149], v[0:3]
	v_mfma_f32_16x16x32_bf16 v[60:63], v[78:81], v[94:97], v[60:63]
	v_mfma_f32_16x16x32_bf16 v[56:59], v[86:89], v[94:97], v[56:59]
	v_mfma_f32_16x16x32_bf16 v[52:55], v[78:81], v[102:105], v[52:55]
	v_mfma_f32_16x16x32_bf16 v[48:51], v[86:89], v[102:105], v[48:51]
	v_mfma_f32_16x16x32_bf16 v[44:47], v[78:81], v[110:113], v[44:47]
	v_mfma_f32_16x16x32_bf16 v[40:43], v[86:89], v[110:113], v[40:43]
	v_mfma_f32_16x16x32_bf16 v[36:39], v[78:81], v[118:121], v[36:39]
	v_mfma_f32_16x16x32_bf16 v[32:35], v[86:89], v[118:121], v[32:35]
	v_mfma_f32_16x16x32_bf16 v[28:31], v[78:81], v[126:129], v[28:31]
	v_mfma_f32_16x16x32_bf16 v[24:27], v[86:89], v[126:129], v[24:27]
	v_mfma_f32_16x16x32_bf16 v[20:23], v[78:81], v[134:137], v[20:23]
	v_mfma_f32_16x16x32_bf16 v[16:19], v[86:89], v[134:137], v[16:19]
	v_mfma_f32_16x16x32_bf16 v[12:15], v[78:81], v[142:145], v[12:15]
	v_mfma_f32_16x16x32_bf16 v[8:11], v[86:89], v[142:145], v[8:11]
	s_waitcnt lgkmcnt(0)
	v_mfma_f32_16x16x32_bf16 v[4:7], v[78:81], v[150:153], v[4:7]
	v_mfma_f32_16x16x32_bf16 v[0:3], v[86:89], v[150:153], v[0:3]
	s_setprio 1
	s_barrier
	s_mov_b32 m0, s48
	s_nop 0
	global_load_lds_dwordx4 v67, s[82:83]
	s_mov_b32 m0, s49
	s_nop 0
	global_load_lds_dwordx4 v69, s[82:83]
	s_mov_b32 m0, s47
	s_nop 0
	global_load_lds_dwordx4 v66, s[38:39]
	s_mov_b32 m0, s50
	s_nop 0
	global_load_lds_dwordx4 v68, s[38:39]
	s_add_u32 s86, s38, 0x18000
	s_addc_u32 s87, s39, 0
	s_mov_b32 m0, s51
	s_nop 0
	global_load_lds_dwordx4 v66, s[86:87]
	s_mov_b32 m0, s52
	s_nop 0
	global_load_lds_dwordx4 v68, s[86:87]
	s_waitcnt vmcnt(8)
	s_waitcnt lgkmcnt(0)
	s_barrier
; #define PG8_STAGE(bufoff, gbase, voff) do { _Pragma("unroll") for (int _i = 0; _i < 2; ++_i) { \
;         const unsigned _m0 = ldsu + (unsigned)(bufoff) + ldsw + (unsigned)(_i * 8192); \
;         asm volatile("s_mov_b32 m0, %2\n\ts_nop 0\n\tglobal_load_lds_dwordx4 %0, %1" :: "v"((voff)[_i]), "s"((const char*)(gbase)), "s"(_m0) : "memory"); } } while (0)
; #define PG8_LDA(dst, b, h) do { _Pragma("unroll") for (int m = 0; m < 4; ++m) _Pragma("unroll") for (int k = 0; k < 2; ++k) dst[m][k] = *(const LAS bf16x8*)(lds + PG8_SA(b, h) + aoff + m * 2048 + k * 1024); } while (0)
; #define PG8_LDB(dst, b, h) do { _Pragma("unroll") for (int n = 0; n < 2; ++n) _Pragma("unroll") for (int k = 0; k < 2; ++k) dst[n][k] = *(const LAS bf16x8*)(lds + bbase[b][h] + n * 2048 + k * 1024); } while (0)
; #define PG8_WAIT_V(n) asm volatile("s_waitcnt vmcnt(" #n ")" ::: "memory")
; #define PG8_WAIT_L(n) asm volatile("s_waitcnt lgkmcnt(" #n ")" ::: "memory")
; #define PG8_BAR __builtin_amdgcn_s_barrier()
; #define PG8_SCHED __builtin_amdgcn_sched_barrier(0)
; template <class Epi>
; __device__ __forceinline__ void gemm_phase(LAS unsigned char* lds, const Gemm g, const StaticOrder& S, const Epi& E) {
;     ...
;             PG8_WAIT_V(8); PG8_WAIT_L(0); PG8_BAR; PG8_MMA2B(1, At, At2, B0); PG8_BAR; PG8_SCHED;
;             PG8_LDB(B0, 1, 0); PG8_SCHED; PG8_LDA(At, 1, 0); PG8_LDA(At2, 1, 1); PG8_STAGE(PG8_SB(0, 1), b2 + hstepB, voffB);
;             PG8_WAIT_V(8); PG8_WAIT_L(0); PG8_BAR; PG8_MMA2B(0, At, At2, B0); PG8_BAR; PG8_SCHED;
;             PG8_LDB(B0, 1, 1); PG8_STAGE(PG8_SB(1, 0), b3, voffB); PG8_STAGE(PG8_SA(1, 0), a3, voffA); PG8_STAGE(PG8_SA(1, 1), a3 + hstepA, voffA);
;             PG8_WAIT_V(8); PG8_WAIT_L(0); PG8_BAR; PG8_MMA2B(1, At, At2, B0); PG8_BAR; PG8_SCHED;
;         }
	s_setprio 0
	s_setprio 1
	s_barrier
	ds_read_b128 v[74:77], v73
	ds_read_b128 v[78:81], v73 offset:1024
	ds_read_b128 v[82:85], v73 offset:2048
	ds_read_b128 v[86:89], v73 offset:3072
	ds_read_b128 v[90:93], v72 offset:32768
	ds_read_b128 v[94:97], v72 offset:33792
	ds_read_b128 v[98:101], v72 offset:34816
	ds_read_b128 v[102:105], v72 offset:35840
	ds_read_b128 v[106:109], v72 offset:36864
	ds_read_b128 v[110:113], v72 offset:37888
	ds_read_b128 v[114:117], v72 offset:38912
	ds_read_b128 v[118:121], v72 offset:39936
	ds_read_b128 v[122:125], v72 offset:49152
	ds_read_b128 v[126:129], v72 offset:50176
	ds_read_b128 v[130:133], v72 offset:51200
	ds_read_b128 v[134:137], v72 offset:52224
	ds_read_b128 v[138:141], v72 offset:53248
	ds_read_b128 v[142:145], v72 offset:54272
	ds_read_b128 v[146:149], v72 offset:55296
	ds_read_b128 v[150:153], v72 offset:56320
	s_add_u32 s82, s82, 0x10000
	s_addc_u32 s83, s83, 0
	s_mov_b32 m0, s53
	s_nop 0
	global_load_lds_dwordx4 v67, s[82:83]
	s_mov_b32 m0, s54
	s_nop 0
	global_load_lds_dwordx4 v69, s[82:83]
	s_waitcnt vmcnt(8)
	s_waitcnt lgkmcnt(0)
	s_barrier
	s_setprio 0
	s_waitcnt lgkmcnt(14)
	v_mfma_f32_16x16x32_bf16 v[60:63], v[74:77], v[90:93], v[60:63]
	v_mfma_f32_16x16x32_bf16 v[56:59], v[82:85], v[90:93], v[56:59]
	s_waitcnt lgkmcnt(13)
	v_mfma_f32_16x16x32_bf16 v[52:55], v[74:77], v[98:101], v[52:55]
	v_mfma_f32_16x16x32_bf16 v[48:51], v[82:85], v[98:101], v[48:51]
	s_waitcnt lgkmcnt(11)
	v_mfma_f32_16x16x32_bf16 v[44:47], v[74:77], v[106:109], v[44:47]
	v_mfma_f32_16x16x32_bf16 v[40:43], v[82:85], v[106:109], v[40:43]
	s_waitcnt lgkmcnt(9)
	v_mfma_f32_16x16x32_bf16 v[36:39], v[74:77], v[114:117], v[36:39]
	v_mfma_f32_16x16x32_bf16 v[32:35], v[82:85], v[114:117], v[32:35]
	s_waitcnt lgkmcnt(7)
	v_mfma_f32_16x16x32_bf16 v[28:31], v[74:77], v[122:125], v[28:31]
	v_mfma_f32_16x16x32_bf16 v[24:27], v[82:85], v[122:125], v[24:27]
	s_waitcnt lgkmcnt(5)
	v_mfma_f32_16x16x32_bf16 v[20:23], v[74:77], v[130:133], v[20:23]
	v_mfma_f32_16x16x32_bf16 v[16:19], v[82:85], v[130:133], v[16:19]
	s_waitcnt lgkmcnt(3)
	v_mfma_f32_16x16x32_bf16 v[12:15], v[74:77], v[138:141], v[12:15]
	v_mfma_f32_16x16x32_bf16 v[8:11], v[82:85], v[138:141], v[8:11]
	s_waitcnt lgkmcnt(1)
	v_mfma_f32_16x16x32_bf16 v[4:7], v[74:77], v[146:149], v[4:7]
	v_mfma_f32_16x16x32_bf16 v[0:3], v[82:85], v[146:149], v[0:3]
	v_mfma_f32_16x16x32_bf16 v[60:63], v[78:81], v[94:97], v[60:63]
	v_mfma_f32_16x16x32_bf16 v[56:59], v[86:89], v[94:97], v[56:59]
	v_mfma_f32_16x16x32_bf16 v[52:55], v[78:81], v[102:105], v[52:55]
	v_mfma_f32_16x16x32_bf16 v[48:51], v[86:89], v[102:105], v[48:51]
	v_mfma_f32_16x16x32_bf16 v[44:47], v[78:81], v[110:113], v[44:47]
	v_mfma_f32_16x16x32_bf16 v[40:43], v[86:89], v[110:113], v[40:43]
	v_mfma_f32_16x16x32_bf16 v[36:39], v[78:81], v[118:121], v[36:39]
	v_mfma_f32_16x16x32_bf16 v[32:35], v[86:89], v[118:121], v[32:35]
	v_mfma_f32_16x16x32_bf16 v[28:31], v[78:81], v[126:129], v[28:31]
	v_mfma_f32_16x16x32_bf16 v[24:27], v[86:89], v[126:129], v[24:27]
	v_mfma_f32_16x16x32_bf16 v[20:23], v[78:81], v[134:137], v[20:23]
	v_mfma_f32_16x16x32_bf16 v[16:19], v[86:89], v[134:137], v[16:19]
	v_mfma_f32_16x16x32_bf16 v[12:15], v[78:81], v[142:145], v[12:15]
	v_mfma_f32_16x16x32_bf16 v[8:11], v[86:89], v[142:145], v[8:11]
	s_waitcnt lgkmcnt(0)
	v_mfma_f32_16x16x32_bf16 v[4:7], v[78:81], v[150:153], v[4:7]
	v_mfma_f32_16x16x32_bf16 v[0:3], v[86:89], v[150:153], v[0:3]
	s_setprio 1
	s_barrier
	s_mov_b32 m0, s56
	s_nop 0
	global_load_lds_dwordx4 v67, s[80:81]
	s_mov_b32 m0, s57
	s_nop 0
	global_load_lds_dwordx4 v69, s[80:81]
	s_mov_b32 m0, s58
	s_nop 0
	global_load_lds_dwordx4 v66, s[42:43]
	s_mov_b32 m0, s59
	s_nop 0
	global_load_lds_dwordx4 v68, s[42:43]
	s_add_u32 s38, s38, 0x18080
	s_addc_u32 s39, s39, 0
	s_mov_b32 m0, s60
	s_nop 0
	global_load_lds_dwordx4 v66, s[38:39]
	s_mov_b32 m0, s61
	s_nop 0
	global_load_lds_dwordx4 v68, s[38:39]
	s_waitcnt vmcnt(8)
	s_waitcnt lgkmcnt(0)
	s_barrier
	s_setprio 0
	s_setprio 1
	s_barrier
	s_add_u32 s67, s67, 0x100
	s_addc_u32 s68, s68, 0
	s_add_u32 s69, s69, 0x100
	s_addc_u32 s84, s84, 0
	s_cmp_ge_i32 s85, s55
	s_mov_b32 s38, s85
	s_cbranch_scc0 .LBB0_662

; #define PG8_STAGE(bufoff, gbase, voff) do { _Pragma("unroll") for (int _i = 0; _i < 2; ++_i) { \
;         const unsigned _m0 = ldsu + (unsigned)(bufoff) + ldsw + (unsigned)(_i * 8192); \
;         asm volatile("s_mov_b32 m0, %2\n\ts_nop 0\n\tglobal_load_lds_dwordx4 %0, %1" :: "v"((voff)[_i]), "s"((const char*)(gbase)), "s"(_m0) : "memory"); } } while (0)
; #define PG8_LDA(dst, b, h) do { _Pragma("unroll") for (int m = 0; m < 4; ++m) _Pragma("unroll") for (int k = 0; k < 2; ++k) dst[m][k] = *(const LAS bf16x8*)(lds + PG8_SA(b, h) + aoff + m * 2048 + k * 1024); } while (0)
; #define PG8_LDB(dst, b, h) do { _Pragma("unroll") for (int n = 0; n < 2; ++n) _Pragma("unroll") for (int k = 0; k < 2; ++k) dst[n][k] = *(const LAS bf16x8*)(lds + bbase[b][h] + n * 2048 + k * 1024); } while (0)
; #define PG8_WAIT_V(n) asm volatile("s_waitcnt vmcnt(" #n ")" ::: "memory")
; #define PG8_WAIT_L(n) asm volatile("s_waitcnt lgkmcnt(" #n ")" ::: "memory")
; #define PG8_BAR __builtin_amdgcn_s_barrier()
; #define PG8_SCHED __builtin_amdgcn_sched_barrier(0)
; template <class Epi>
; __device__ __forceinline__ void gemm_phase(LAS unsigned char* lds, const Gemm g, const StaticOrder& S, const Epi& E) {
;     ...
;             const bool last = (t == nt - 2);
;             const char* a2 = last ? nA : cA + (size_t)(t + 2) * kstep; const char* b2 = last ? nB : cB + (size_t)(t + 2) * kstep;
;             const char* a3 = a2 + kstep; const char* b3 = b2 + kstep;
;             const char* b1 = cB + (size_t)(t + 1) * kstep;
;             PG8_LDB(B0, 0, 0); PG8_SCHED; PG8_LDA(At, 0, 0); PG8_LDA(At2, 0, 1); PG8_STAGE(PG8_SB(1, 1), b1 + hstepB, voffB);
;             PG8_WAIT_V(8); PG8_WAIT_L(0); PG8_BAR; PG8_MMA2B(0, At, At2, B0); PG8_BAR; PG8_SCHED;
;             PG8_LDB(B0, 0, 1); PG8_STAGE(PG8_SB(0, 0), b2, voffB); PG8_STAGE(PG8_SA(0, 0), a2, voffA); PG8_STAGE(PG8_SA(0, 1), a2 + hstepA, voffA);
;             PG8_WAIT_V(8); PG8_WAIT_L(0); PG8_BAR; PG8_MMA2B(1, At, At2, B0); PG8_BAR; PG8_SCHED;
.LBB0_797:
	s_add_i32 s52, s4, 2
	s_add_u32 s38, s1, 0x80
	ds_read_b128 v[128:131], v153
	ds_read_b128 v[132:135], v153 offset:1024
	ds_read_b128 v[142:145], v153 offset:2048
	ds_read_b128 v[178:181], v153 offset:3072
	s_addc_u32 s39, s43, 0
	s_cmp_eq_u32 s47, s4
	s_cselect_b32 s4, s16, s50
	s_cselect_b32 s5, s17, s51
	s_cselect_b32 s82, s10, s38
	s_cselect_b32 s83, s11, s39
	s_add_u32 s38, s4, 0x80
	s_addc_u32 s39, s5, 0
	s_add_u32 s80, s82, 0x80
	s_addc_u32 s81, s83, 0
	ds_read_b128 v[182:185], v154
	ds_read_b128 v[186:189], v154 offset:1024
	ds_read_b128 v[190:193], v154 offset:2048
	ds_read_b128 v[194:197], v154 offset:3072
	ds_read_b128 v[198:201], v154 offset:4096
	ds_read_b128 v[202:205], v154 offset:5120
	ds_read_b128 v[214:217], v154 offset:6144
	ds_read_b128 v[218:221], v154 offset:7168
	ds_read_b128 v[222:225], v154 offset:16384
	ds_read_b128 v[226:229], v154 offset:17408
	ds_read_b128 v[230:233], v154 offset:18432
	ds_read_b128 v[234:237], v154 offset:19456
	ds_read_b128 v[238:241], v154 offset:20480
	ds_read_b128 v[242:245], v154 offset:21504
	ds_read_b128 v[246:249], v154 offset:22528
	ds_read_b128 v[166:169], v154 offset:23552
	s_add_u32 s54, s1, 0x18000
	s_addc_u32 s55, s43, 0
	s_mov_b32 m0, s87
	s_nop 0
	global_load_lds_dwordx4 v147, s[54:55]
	s_mov_b32 m0, s28
	s_nop 0
	global_load_lds_dwordx4 v149, s[54:55]
	s_waitcnt vmcnt(8)
	s_waitcnt lgkmcnt(0)
	s_barrier
	s_setprio 0
	s_waitcnt lgkmcnt(14)
	v_mfma_f32_16x16x32_bf16 v[124:127], v[128:131], v[182:185], v[124:127]
	v_mfma_f32_16x16x32_bf16 v[120:123], v[142:145], v[182:185], v[120:123]
	s_waitcnt lgkmcnt(13)
	v_mfma_f32_16x16x32_bf16 v[108:111], v[128:131], v[190:193], v[108:111]
	v_mfma_f32_16x16x32_bf16 v[104:107], v[142:145], v[190:193], v[104:107]
	s_waitcnt lgkmcnt(11)
	v_mfma_f32_16x16x32_bf16 v[92:95], v[128:131], v[198:201], v[92:95]
	v_mfma_f32_16x16x32_bf16 v[88:91], v[142:145], v[198:201], v[88:91]
	s_waitcnt lgkmcnt(9)
	v_mfma_f32_16x16x32_bf16 v[76:79], v[128:131], v[214:217], v[76:79]
	v_mfma_f32_16x16x32_bf16 v[72:75], v[142:145], v[214:217], v[72:75]
	s_waitcnt lgkmcnt(7)
	v_mfma_f32_16x16x32_bf16 v[60:63], v[128:131], v[222:225], v[60:63]
	v_mfma_f32_16x16x32_bf16 v[56:59], v[142:145], v[222:225], v[56:59]
	s_waitcnt lgkmcnt(5)
	v_mfma_f32_16x16x32_bf16 v[44:47], v[128:131], v[230:233], v[44:47]
	v_mfma_f32_16x16x32_bf16 v[40:43], v[142:145], v[230:233], v[40:43]
	s_waitcnt lgkmcnt(3)
	v_mfma_f32_16x16x32_bf16 v[28:31], v[128:131], v[238:241], v[28:31]
	v_mfma_f32_16x16x32_bf16 v[24:27], v[142:145], v[238:241], v[24:27]
	s_waitcnt lgkmcnt(1)
	v_mfma_f32_16x16x32_bf16 v[12:15], v[128:131], v[246:249], v[12:15]
	v_mfma_f32_16x16x32_bf16 v[8:11], v[142:145], v[246:249], v[8:11]
	v_mfma_f32_16x16x32_bf16 v[124:127], v[132:135], v[186:189], v[124:127]
	v_mfma_f32_16x16x32_bf16 v[120:123], v[178:181], v[186:189], v[120:123]
	v_mfma_f32_16x16x32_bf16 v[108:111], v[132:135], v[194:197], v[108:111]
	v_mfma_f32_16x16x32_bf16 v[104:107], v[178:181], v[194:197], v[104:107]
	v_mfma_f32_16x16x32_bf16 v[92:95], v[132:135], v[202:205], v[92:95]
	v_mfma_f32_16x16x32_bf16 v[88:91], v[178:181], v[202:205], v[88:91]
	v_mfma_f32_16x16x32_bf16 v[76:79], v[132:135], v[218:221], v[76:79]
	v_mfma_f32_16x16x32_bf16 v[72:75], v[178:181], v[218:221], v[72:75]
	v_mfma_f32_16x16x32_bf16 v[60:63], v[132:135], v[226:229], v[60:63]
	v_mfma_f32_16x16x32_bf16 v[56:59], v[178:181], v[226:229], v[56:59]
	v_mfma_f32_16x16x32_bf16 v[44:47], v[132:135], v[234:237], v[44:47]
	v_mfma_f32_16x16x32_bf16 v[40:43], v[178:181], v[234:237], v[40:43]
	v_mfma_f32_16x16x32_bf16 v[28:31], v[132:135], v[242:245], v[28:31]
	v_mfma_f32_16x16x32_bf16 v[24:27], v[178:181], v[242:245], v[24:27]
	s_waitcnt lgkmcnt(0)
	v_mfma_f32_16x16x32_bf16 v[12:15], v[132:135], v[166:169], v[12:15]
	v_mfma_f32_16x16x32_bf16 v[8:11], v[178:181], v[166:169], v[8:11]
	s_setprio 1
	s_barrier
	ds_read_b128 v[128:131], v155
	ds_read_b128 v[132:135], v155 offset:1024
	ds_read_b128 v[142:145], v155 offset:2048
	ds_read_b128 v[178:181], v155 offset:3072
	s_mov_b32 m0, s90
	s_nop 0
	global_load_lds_dwordx4 v147, s[82:83]
	s_mov_b32 m0, s91
	s_nop 0
	global_load_lds_dwordx4 v149, s[82:83]
	s_mov_b32 m0, s85
	s_nop 0
	global_load_lds_dwordx4 v146, s[4:5]
	s_mov_b32 m0, s95
	s_nop 0
	global_load_lds_dwordx4 v148, s[4:5]
	s_add_u32 s54, s4, 0x18000
	s_addc_u32 s55, s5, 0
	s_mov_b32 m0, s96
	s_nop 0
	global_load_lds_dwordx4 v146, s[54:55]
	s_mov_b32 m0, s97
	s_nop 0
	global_load_lds_dwordx4 v148, s[54:55]
	s_waitcnt vmcnt(8)
	s_waitcnt lgkmcnt(0)
	s_barrier
; #define PG8_STAGE(bufoff, gbase, voff) do { _Pragma("unroll") for (int _i = 0; _i < 2; ++_i) { \
;         const unsigned _m0 = ldsu + (unsigned)(bufoff) + ldsw + (unsigned)(_i * 8192); \
;         asm volatile("s_mov_b32 m0, %2\n\ts_nop 0\n\tglobal_load_lds_dwordx4 %0, %1" :: "v"((voff)[_i]), "s"((const char*)(gbase)), "s"(_m0) : "memory"); } } while (0)
; #define PG8_LDA(dst, b, h) do { _Pragma("unroll") for (int m = 0; m < 4; ++m) _Pragma("unroll") for (int k = 0; k < 2; ++k) dst[m][k] = *(const LAS bf16x8*)(lds + PG8_SA(b, h) + aoff + m * 2048 + k * 1024); } while (0)
; #define PG8_LDB(dst, b, h) do { _Pragma("unroll") for (int n = 0; n < 2; ++n) _Pragma("unroll") for (int k = 0; k < 2; ++k) dst[n][k] = *(const LAS bf16x8*)(lds + bbase[b][h] + n * 2048 + k * 1024); } while (0)
; #define PG8_WAIT_V(n) asm volatile("s_waitcnt vmcnt(" #n ")" ::: "memory")
; #define PG8_WAIT_L(n) asm volatile("s_waitcnt lgkmcnt(" #n ")" ::: "memory")
; #define PG8_BAR __builtin_amdgcn_s_barrier()
; #define PG8_SCHED __builtin_amdgcn_sched_barrier(0)
; template <class Epi>
; __device__ __forceinline__ void gemm_phase(LAS unsigned char* lds, const Gemm g, const StaticOrder& S, const Epi& E) {
;     ...
;             PG8_WAIT_V(8); PG8_WAIT_L(0); PG8_BAR; PG8_MMA2B(1, At, At2, B0); PG8_BAR; PG8_SCHED;
;             PG8_LDB(B0, 1, 0); PG8_SCHED; PG8_LDA(At, 1, 0); PG8_LDA(At2, 1, 1); PG8_STAGE(PG8_SB(0, 1), b2 + hstepB, voffB);
;             PG8_WAIT_V(8); PG8_WAIT_L(0); PG8_BAR; PG8_MMA2B(0, At, At2, B0); PG8_BAR; PG8_SCHED;
	s_setprio 0
	s_waitcnt lgkmcnt(3)
	v_mfma_f32_16x16x32_bf16 v[116:119], v[128:131], v[182:185], v[116:119]
	s_waitcnt lgkmcnt(1)
	v_mfma_f32_16x16x32_bf16 v[112:115], v[142:145], v[182:185], v[112:115]
	v_mfma_f32_16x16x32_bf16 v[100:103], v[128:131], v[190:193], v[100:103]
	v_mfma_f32_16x16x32_bf16 v[96:99], v[142:145], v[190:193], v[96:99]
	v_mfma_f32_16x16x32_bf16 v[84:87], v[128:131], v[198:201], v[84:87]
	v_mfma_f32_16x16x32_bf16 v[80:83], v[142:145], v[198:201], v[80:83]
	v_mfma_f32_16x16x32_bf16 v[68:71], v[128:131], v[214:217], v[68:71]
	v_mfma_f32_16x16x32_bf16 v[64:67], v[142:145], v[214:217], v[64:67]
	v_mfma_f32_16x16x32_bf16 v[52:55], v[128:131], v[222:225], v[52:55]
	v_mfma_f32_16x16x32_bf16 v[48:51], v[142:145], v[222:225], v[48:51]
	v_mfma_f32_16x16x32_bf16 v[36:39], v[128:131], v[230:233], v[36:39]
	v_mfma_f32_16x16x32_bf16 v[32:35], v[142:145], v[230:233], v[32:35]
	v_mfma_f32_16x16x32_bf16 v[20:23], v[128:131], v[238:241], v[20:23]
	v_mfma_f32_16x16x32_bf16 v[16:19], v[142:145], v[238:241], v[16:19]
	v_mfma_f32_16x16x32_bf16 v[4:7], v[128:131], v[246:249], v[4:7]
	v_mfma_f32_16x16x32_bf16 v[0:3], v[142:145], v[246:249], v[0:3]
	v_mfma_f32_16x16x32_bf16 v[116:119], v[132:135], v[186:189], v[116:119]
	s_waitcnt lgkmcnt(0)
	v_mfma_f32_16x16x32_bf16 v[112:115], v[178:181], v[186:189], v[112:115]
	v_mfma_f32_16x16x32_bf16 v[100:103], v[132:135], v[194:197], v[100:103]
	v_mfma_f32_16x16x32_bf16 v[96:99], v[178:181], v[194:197], v[96:99]
	v_mfma_f32_16x16x32_bf16 v[84:87], v[132:135], v[202:205], v[84:87]
	v_mfma_f32_16x16x32_bf16 v[80:83], v[178:181], v[202:205], v[80:83]
	v_mfma_f32_16x16x32_bf16 v[68:71], v[132:135], v[218:221], v[68:71]
	v_mfma_f32_16x16x32_bf16 v[64:67], v[178:181], v[218:221], v[64:67]
	v_mfma_f32_16x16x32_bf16 v[52:55], v[132:135], v[226:229], v[52:55]
	v_mfma_f32_16x16x32_bf16 v[48:51], v[178:181], v[226:229], v[48:51]
	v_mfma_f32_16x16x32_bf16 v[36:39], v[132:135], v[234:237], v[36:39]
	v_mfma_f32_16x16x32_bf16 v[32:35], v[178:181], v[234:237], v[32:35]
	v_mfma_f32_16x16x32_bf16 v[20:23], v[132:135], v[242:245], v[20:23]
	v_mfma_f32_16x16x32_bf16 v[16:19], v[178:181], v[242:245], v[16:19]
	v_mfma_f32_16x16x32_bf16 v[4:7], v[132:135], v[166:169], v[4:7]
	v_mfma_f32_16x16x32_bf16 v[0:3], v[178:181], v[166:169], v[0:3]
	s_setprio 1
	s_barrier
	ds_read_b128 v[128:131], v156
	ds_read_b128 v[132:135], v156 offset:1024
	ds_read_b128 v[142:145], v156 offset:2048
	ds_read_b128 v[166:169], v156 offset:3072
	ds_read_b128 v[178:181], v154 offset:32768
	ds_read_b128 v[182:185], v154 offset:33792
	ds_read_b128 v[186:189], v154 offset:34816
	ds_read_b128 v[190:193], v154 offset:35840
	ds_read_b128 v[194:197], v154 offset:36864
	ds_read_b128 v[198:201], v154 offset:37888
	ds_read_b128 v[202:205], v154 offset:38912
	ds_read_b128 v[214:217], v154 offset:39936
	ds_read_b128 v[218:221], v154 offset:49152
	ds_read_b128 v[222:225], v154 offset:50176
	ds_read_b128 v[226:229], v154 offset:51200
	ds_read_b128 v[230:233], v154 offset:52224
	ds_read_b128 v[234:237], v154 offset:53248
	ds_read_b128 v[238:241], v154 offset:54272
	ds_read_b128 v[242:245], v154 offset:55296
	ds_read_b128 v[246:249], v154 offset:56320
	s_add_u32 s54, s82, 0x18000
	s_addc_u32 s55, s83, 0
	s_mov_b32 m0, s6
	s_nop 0
	global_load_lds_dwordx4 v147, s[54:55]
	s_mov_b32 m0, s7
	s_nop 0
	global_load_lds_dwordx4 v149, s[54:55]
	s_waitcnt vmcnt(8)
	s_waitcnt lgkmcnt(0)
	s_barrier
; #define PG8_STAGE(bufoff, gbase, voff) do { _Pragma("unroll") for (int _i = 0; _i < 2; ++_i) { \
;         const unsigned _m0 = ldsu + (unsigned)(bufoff) + ldsw + (unsigned)(_i * 8192); \
;         asm volatile("s_mov_b32 m0, %2\n\ts_nop 0\n\tglobal_load_lds_dwordx4 %0, %1" :: "v"((voff)[_i]), "s"((const char*)(gbase)), "s"(_m0) : "memory"); } } while (0)
; #define PG8_LDB(dst, b, h) do { _Pragma("unroll") for (int n = 0; n < 2; ++n) _Pragma("unroll") for (int k = 0; k < 2; ++k) dst[n][k] = *(const LAS bf16x8*)(lds + bbase[b][h] + n * 2048 + k * 1024); } while (0)
; #define PG8_WAIT_V(n) asm volatile("s_waitcnt vmcnt(" #n ")" ::: "memory")
; #define PG8_WAIT_L(n) asm volatile("s_waitcnt lgkmcnt(" #n ")" ::: "memory")
; #define PG8_BAR __builtin_amdgcn_s_barrier()
; #define PG8_SCHED __builtin_amdgcn_sched_barrier(0)
; template <class Epi>
; __device__ __forceinline__ void gemm_phase(LAS unsigned char* lds, const Gemm g, const StaticOrder& S, const Epi& E) {
;     ...
;             PG8_WAIT_V(8); PG8_WAIT_L(0); PG8_BAR; PG8_MMA2B(0, At, At2, B0); PG8_BAR; PG8_SCHED;
;             PG8_LDB(B0, 1, 1); PG8_STAGE(PG8_SB(1, 0), b3, voffB); PG8_STAGE(PG8_SA(1, 0), a3, voffA); PG8_STAGE(PG8_SA(1, 1), a3 + hstepA, voffA);
;             PG8_WAIT_V(8); PG8_WAIT_L(0); PG8_BAR; PG8_MMA2B(1, At, At2, B0); PG8_BAR; PG8_SCHED;
;         }
	s_setprio 0
	s_waitcnt lgkmcnt(14)
	v_mfma_f32_16x16x32_bf16 v[124:127], v[128:131], v[178:181], v[124:127]
	v_mfma_f32_16x16x32_bf16 v[120:123], v[142:145], v[178:181], v[120:123]
	s_waitcnt lgkmcnt(13)
	v_mfma_f32_16x16x32_bf16 v[108:111], v[128:131], v[186:189], v[108:111]
	v_mfma_f32_16x16x32_bf16 v[104:107], v[142:145], v[186:189], v[104:107]
	s_waitcnt lgkmcnt(11)
	v_mfma_f32_16x16x32_bf16 v[92:95], v[128:131], v[194:197], v[92:95]
	v_mfma_f32_16x16x32_bf16 v[88:91], v[142:145], v[194:197], v[88:91]
	s_waitcnt lgkmcnt(9)
	v_mfma_f32_16x16x32_bf16 v[76:79], v[128:131], v[202:205], v[76:79]
	v_mfma_f32_16x16x32_bf16 v[72:75], v[142:145], v[202:205], v[72:75]
	s_waitcnt lgkmcnt(7)
	v_mfma_f32_16x16x32_bf16 v[60:63], v[128:131], v[218:221], v[60:63]
	v_mfma_f32_16x16x32_bf16 v[56:59], v[142:145], v[218:221], v[56:59]
	s_waitcnt lgkmcnt(5)
	v_mfma_f32_16x16x32_bf16 v[44:47], v[128:131], v[226:229], v[44:47]
	v_mfma_f32_16x16x32_bf16 v[40:43], v[142:145], v[226:229], v[40:43]
	s_waitcnt lgkmcnt(3)
	v_mfma_f32_16x16x32_bf16 v[28:31], v[128:131], v[234:237], v[28:31]
	v_mfma_f32_16x16x32_bf16 v[24:27], v[142:145], v[234:237], v[24:27]
	s_waitcnt lgkmcnt(1)
	v_mfma_f32_16x16x32_bf16 v[12:15], v[128:131], v[242:245], v[12:15]
	v_mfma_f32_16x16x32_bf16 v[8:11], v[142:145], v[242:245], v[8:11]
	v_mfma_f32_16x16x32_bf16 v[124:127], v[132:135], v[182:185], v[124:127]
	v_mfma_f32_16x16x32_bf16 v[120:123], v[166:169], v[182:185], v[120:123]
	v_mfma_f32_16x16x32_bf16 v[108:111], v[132:135], v[190:193], v[108:111]
	v_mfma_f32_16x16x32_bf16 v[104:107], v[166:169], v[190:193], v[104:107]
	v_mfma_f32_16x16x32_bf16 v[92:95], v[132:135], v[198:201], v[92:95]
	v_mfma_f32_16x16x32_bf16 v[88:91], v[166:169], v[198:201], v[88:91]
	v_mfma_f32_16x16x32_bf16 v[76:79], v[132:135], v[214:217], v[76:79]
	v_mfma_f32_16x16x32_bf16 v[72:75], v[166:169], v[214:217], v[72:75]
	v_mfma_f32_16x16x32_bf16 v[60:63], v[132:135], v[222:225], v[60:63]
	v_mfma_f32_16x16x32_bf16 v[56:59], v[166:169], v[222:225], v[56:59]
	v_mfma_f32_16x16x32_bf16 v[44:47], v[132:135], v[230:233], v[44:47]
	v_mfma_f32_16x16x32_bf16 v[40:43], v[166:169], v[230:233], v[40:43]
	v_mfma_f32_16x16x32_bf16 v[28:31], v[132:135], v[238:241], v[28:31]
	v_mfma_f32_16x16x32_bf16 v[24:27], v[166:169], v[238:241], v[24:27]
	s_waitcnt lgkmcnt(0)
	v_mfma_f32_16x16x32_bf16 v[12:15], v[132:135], v[246:249], v[12:15]
	v_mfma_f32_16x16x32_bf16 v[8:11], v[166:169], v[246:249], v[8:11]
	s_setprio 1
	s_barrier
	ds_read_b128 v[128:131], v157
	ds_read_b128 v[132:135], v157 offset:1024
	ds_read_b128 v[142:145], v157 offset:2048
	ds_read_b128 v[166:169], v157 offset:3072
	s_mov_b32 m0, s2
	s_nop 0
	global_load_lds_dwordx4 v147, s[80:81]
	s_mov_b32 m0, s3
	s_nop 0
	global_load_lds_dwordx4 v149, s[80:81]
	s_mov_b32 m0, s88
	s_nop 0
	global_load_lds_dwordx4 v146, s[38:39]
	s_mov_b32 m0, s89
	s_nop 0
	global_load_lds_dwordx4 v148, s[38:39]
	s_add_u32 s4, s4, 0x18080
	s_addc_u32 s5, s5, 0
	s_mov_b32 m0, s37
	s_nop 0
	global_load_lds_dwordx4 v146, s[4:5]
	s_mov_b32 m0, s84
	s_nop 0
	global_load_lds_dwordx4 v148, s[4:5]
	s_waitcnt vmcnt(8)
	s_waitcnt lgkmcnt(0)
	s_barrier
	s_setprio 0
	s_waitcnt lgkmcnt(3)
	v_mfma_f32_16x16x32_bf16 v[116:119], v[128:131], v[178:181], v[116:119]
	s_waitcnt lgkmcnt(1)
	v_mfma_f32_16x16x32_bf16 v[112:115], v[142:145], v[178:181], v[112:115]
	v_mfma_f32_16x16x32_bf16 v[100:103], v[128:131], v[186:189], v[100:103]
	v_mfma_f32_16x16x32_bf16 v[96:99], v[142:145], v[186:189], v[96:99]
	v_mfma_f32_16x16x32_bf16 v[84:87], v[128:131], v[194:197], v[84:87]
	v_mfma_f32_16x16x32_bf16 v[80:83], v[142:145], v[194:197], v[80:83]
	v_mfma_f32_16x16x32_bf16 v[68:71], v[128:131], v[202:205], v[68:71]
	v_mfma_f32_16x16x32_bf16 v[64:67], v[142:145], v[202:205], v[64:67]
	v_mfma_f32_16x16x32_bf16 v[52:55], v[128:131], v[218:221], v[52:55]
	v_mfma_f32_16x16x32_bf16 v[48:51], v[142:145], v[218:221], v[48:51]
	v_mfma_f32_16x16x32_bf16 v[36:39], v[128:131], v[226:229], v[36:39]
	v_mfma_f32_16x16x32_bf16 v[32:35], v[142:145], v[226:229], v[32:35]
	v_mfma_f32_16x16x32_bf16 v[20:23], v[128:131], v[234:237], v[20:23]
	v_mfma_f32_16x16x32_bf16 v[16:19], v[142:145], v[234:237], v[16:19]
	v_mfma_f32_16x16x32_bf16 v[4:7], v[128:131], v[242:245], v[4:7]
	v_mfma_f32_16x16x32_bf16 v[0:3], v[142:145], v[242:245], v[0:3]
	v_mfma_f32_16x16x32_bf16 v[116:119], v[132:135], v[182:185], v[116:119]
	s_waitcnt lgkmcnt(0)
	v_mfma_f32_16x16x32_bf16 v[112:115], v[166:169], v[182:185], v[112:115]
	v_mfma_f32_16x16x32_bf16 v[100:103], v[132:135], v[190:193], v[100:103]
	v_mfma_f32_16x16x32_bf16 v[96:99], v[166:169], v[190:193], v[96:99]
	v_mfma_f32_16x16x32_bf16 v[84:87], v[132:135], v[198:201], v[84:87]
	v_mfma_f32_16x16x32_bf16 v[80:83], v[166:169], v[198:201], v[80:83]
	v_mfma_f32_16x16x32_bf16 v[68:71], v[132:135], v[214:217], v[68:71]
	v_mfma_f32_16x16x32_bf16 v[64:67], v[166:169], v[214:217], v[64:67]
	v_mfma_f32_16x16x32_bf16 v[52:55], v[132:135], v[222:225], v[52:55]
	v_mfma_f32_16x16x32_bf16 v[48:51], v[166:169], v[222:225], v[48:51]
	v_mfma_f32_16x16x32_bf16 v[36:39], v[132:135], v[230:233], v[36:39]
	v_mfma_f32_16x16x32_bf16 v[32:35], v[166:169], v[230:233], v[32:35]
	v_mfma_f32_16x16x32_bf16 v[20:23], v[132:135], v[238:241], v[20:23]
	v_mfma_f32_16x16x32_bf16 v[16:19], v[166:169], v[238:241], v[16:19]
	v_mfma_f32_16x16x32_bf16 v[4:7], v[132:135], v[246:249], v[4:7]
	v_mfma_f32_16x16x32_bf16 v[0:3], v[166:169], v[246:249], v[0:3]
	s_setprio 1
	s_barrier
	s_add_u32 s1, s1, 0x100
	s_addc_u32 s43, s43, 0
	s_add_u32 s50, s50, 0x100
	s_addc_u32 s51, s51, 0
	s_cmp_ge_i32 s52, s86
	s_mov_b32 s4, s52
	s_cbranch_scc0 .LBB0_797
	v_readlane_b32 s52, v252, 7
	v_readlane_b32 s54, v254, 61
	v_readlane_b32 s53, v252, 8
	v_readlane_b32 s55, v254, 62
	v_mov_b32_e32 v246, v141

; #define PG8_STAGE(bufoff, gbase, voff) do { _Pragma("unroll") for (int _i = 0; _i < 2; ++_i) { \
;         const unsigned _m0 = ldsu + (unsigned)(bufoff) + ldsw + (unsigned)(_i * 8192); \
;         asm volatile("s_mov_b32 m0, %2\n\ts_nop 0\n\tglobal_load_lds_dwordx4 %0, %1" :: "v"((voff)[_i]), "s"((const char*)(gbase)), "s"(_m0) : "memory"); } } while (0)
; #define PG8_LDA(dst, b, h) do { _Pragma("unroll") for (int m = 0; m < 4; ++m) _Pragma("unroll") for (int k = 0; k < 2; ++k) dst[m][k] = *(const LAS bf16x8*)(lds + PG8_SA(b, h) + aoff + m * 2048 + k * 1024); } while (0)
; #define PG8_LDB(dst, b, h) do { _Pragma("unroll") for (int n = 0; n < 2; ++n) _Pragma("unroll") for (int k = 0; k < 2; ++k) dst[n][k] = *(const LAS bf16x8*)(lds + bbase[b][h] + n * 2048 + k * 1024); } while (0)
; #define PG8_WAIT_V(n) asm volatile("s_waitcnt vmcnt(" #n ")" ::: "memory")
; #define PG8_WAIT_L(n) asm volatile("s_waitcnt lgkmcnt(" #n ")" ::: "memory")
; #define PG8_BAR __builtin_amdgcn_s_barrier()
; #define PG8_SCHED __builtin_amdgcn_sched_barrier(0)
; template <class Epi>
; __device__ __forceinline__ void gemm_phase(LAS unsigned char* lds, const Gemm g, const StaticOrder& S, const Epi& E) {
;     ...
;             const bool last = (t == nt - 2);
;             const char* a2 = last ? nA : cA + (size_t)(t + 2) * kstep; const char* b2 = last ? nB : cB + (size_t)(t + 2) * kstep;
;             const char* a3 = a2 + kstep; const char* b3 = b2 + kstep;
;             const char* b1 = cB + (size_t)(t + 1) * kstep;
;             PG8_LDB(B0, 0, 0); PG8_SCHED; PG8_LDA(At, 0, 0); PG8_LDA(At2, 0, 1); PG8_STAGE(PG8_SB(1, 1), b1 + hstepB, voffB);
;             PG8_WAIT_V(8); PG8_WAIT_L(0); PG8_BAR; PG8_MMA2B(0, At, At2, B0); PG8_BAR; PG8_SCHED;
;             PG8_LDB(B0, 0, 1); PG8_STAGE(PG8_SB(0, 0), b2, voffB); PG8_STAGE(PG8_SA(0, 0), a2, voffA); PG8_STAGE(PG8_SA(0, 1), a2 + hstepA, voffA);
;             PG8_WAIT_V(8); PG8_WAIT_L(0); PG8_BAR; PG8_MMA2B(1, At, At2, B0); PG8_BAR; PG8_SCHED;
.LBB0_870:
	ds_read_b128 v[128:131], v140
	ds_read_b128 v[146:149], v140 offset:1024
	ds_read_b128 v[150:153], v140 offset:2048
	ds_read_b128 v[154:157], v140 offset:3072
	s_add_u32 s38, s16, 0x100
	s_addc_u32 s39, s17, 0
	s_cmp_eq_u32 s68, 4
	s_cselect_b32 s42, s65, s67
	s_cselect_b32 s43, s11, s84
	s_cselect_b32 s82, s66, s38
	s_cselect_b32 s83, s9, s39
	s_add_u32 s80, s42, 0x80
	s_addc_u32 s81, s43, 0
	ds_read_b128 v[166:169], v141
	ds_read_b128 v[178:181], v141 offset:1024
	ds_read_b128 v[182:185], v141 offset:2048
	ds_read_b128 v[186:189], v141 offset:3072
	ds_read_b128 v[190:193], v141 offset:4096
	ds_read_b128 v[194:197], v141 offset:5120
	ds_read_b128 v[198:201], v141 offset:6144
	ds_read_b128 v[202:205], v141 offset:7168
	ds_read_b128 v[214:217], v141 offset:16384
	ds_read_b128 v[218:221], v141 offset:17408
	ds_read_b128 v[222:225], v141 offset:18432
	ds_read_b128 v[226:229], v141 offset:19456
	ds_read_b128 v[230:233], v141 offset:20480
	ds_read_b128 v[234:237], v141 offset:21504
	ds_read_b128 v[238:241], v141 offset:22528
	ds_read_b128 v[242:245], v141 offset:23552
	s_add_u32 s16, s16, 0x20080
	s_addc_u32 s17, s17, 0
	s_mov_b32 m0, s60
	s_nop 0
	global_load_lds_dwordx4 v135, s[16:17]
	s_mov_b32 m0, s61
	s_nop 0
	global_load_lds_dwordx4 v137, s[16:17]
	s_waitcnt vmcnt(8)
	s_waitcnt lgkmcnt(0)
	s_barrier
	s_setprio 0
	s_waitcnt lgkmcnt(14)
	v_mfma_f32_16x16x32_bf16 v[124:127], v[128:131], v[166:169], v[124:127]
	v_mfma_f32_16x16x32_bf16 v[120:123], v[150:153], v[166:169], v[120:123]
	s_waitcnt lgkmcnt(13)
	v_mfma_f32_16x16x32_bf16 v[108:111], v[128:131], v[182:185], v[108:111]
	v_mfma_f32_16x16x32_bf16 v[104:107], v[150:153], v[182:185], v[104:107]
	s_waitcnt lgkmcnt(11)
	v_mfma_f32_16x16x32_bf16 v[92:95], v[128:131], v[190:193], v[92:95]
	v_mfma_f32_16x16x32_bf16 v[88:91], v[150:153], v[190:193], v[88:91]
	s_waitcnt lgkmcnt(9)
	v_mfma_f32_16x16x32_bf16 v[76:79], v[128:131], v[198:201], v[76:79]
	v_mfma_f32_16x16x32_bf16 v[72:75], v[150:153], v[198:201], v[72:75]
	s_waitcnt lgkmcnt(7)
	v_mfma_f32_16x16x32_bf16 v[60:63], v[128:131], v[214:217], v[60:63]
	v_mfma_f32_16x16x32_bf16 v[56:59], v[150:153], v[214:217], v[56:59]
	s_waitcnt lgkmcnt(5)
	v_mfma_f32_16x16x32_bf16 v[44:47], v[128:131], v[222:225], v[44:47]
	v_mfma_f32_16x16x32_bf16 v[40:43], v[150:153], v[222:225], v[40:43]
	s_waitcnt lgkmcnt(3)
	v_mfma_f32_16x16x32_bf16 v[28:31], v[128:131], v[230:233], v[28:31]
	v_mfma_f32_16x16x32_bf16 v[24:27], v[150:153], v[230:233], v[24:27]
	s_waitcnt lgkmcnt(1)
	v_mfma_f32_16x16x32_bf16 v[12:15], v[128:131], v[238:241], v[12:15]
	v_mfma_f32_16x16x32_bf16 v[8:11], v[150:153], v[238:241], v[8:11]
	v_mfma_f32_16x16x32_bf16 v[124:127], v[146:149], v[178:181], v[124:127]
	v_mfma_f32_16x16x32_bf16 v[120:123], v[154:157], v[178:181], v[120:123]
	v_mfma_f32_16x16x32_bf16 v[108:111], v[146:149], v[186:189], v[108:111]
	v_mfma_f32_16x16x32_bf16 v[104:107], v[154:157], v[186:189], v[104:107]
	v_mfma_f32_16x16x32_bf16 v[92:95], v[146:149], v[194:197], v[92:95]
	v_mfma_f32_16x16x32_bf16 v[88:91], v[154:157], v[194:197], v[88:91]
	v_mfma_f32_16x16x32_bf16 v[76:79], v[146:149], v[202:205], v[76:79]
	v_mfma_f32_16x16x32_bf16 v[72:75], v[154:157], v[202:205], v[72:75]
	v_mfma_f32_16x16x32_bf16 v[60:63], v[146:149], v[218:221], v[60:63]
	v_mfma_f32_16x16x32_bf16 v[56:59], v[154:157], v[218:221], v[56:59]
	v_mfma_f32_16x16x32_bf16 v[44:47], v[146:149], v[226:229], v[44:47]
	v_mfma_f32_16x16x32_bf16 v[40:43], v[154:157], v[226:229], v[40:43]
	v_mfma_f32_16x16x32_bf16 v[28:31], v[146:149], v[234:237], v[28:31]
	v_mfma_f32_16x16x32_bf16 v[24:27], v[154:157], v[234:237], v[24:27]
	s_waitcnt lgkmcnt(0)
	v_mfma_f32_16x16x32_bf16 v[12:15], v[146:149], v[242:245], v[12:15]
	v_mfma_f32_16x16x32_bf16 v[8:11], v[154:157], v[242:245], v[8:11]
	s_setprio 1
	s_barrier
	ds_read_b128 v[128:131], v142
	ds_read_b128 v[146:149], v142 offset:1024
	ds_read_b128 v[150:153], v142 offset:2048
	ds_read_b128 v[154:157], v142 offset:3072
	s_mov_b32 m0, s47
	s_nop 0
	global_load_lds_dwordx4 v135, s[82:83]
	s_mov_b32 m0, s48
	s_nop 0
	global_load_lds_dwordx4 v137, s[82:83]
	s_mov_b32 m0, s37
	s_nop 0
	global_load_lds_dwordx4 v134, s[42:43]
	s_mov_b32 m0, s49
	s_nop 0
	global_load_lds_dwordx4 v136, s[42:43]
	s_add_u32 s16, s42, 0x20000
	s_addc_u32 s17, s43, 0
	s_mov_b32 m0, s50
	s_nop 0
	global_load_lds_dwordx4 v134, s[16:17]
	s_mov_b32 m0, s51
	s_nop 0
	global_load_lds_dwordx4 v136, s[16:17]
	s_waitcnt vmcnt(8)
	s_waitcnt lgkmcnt(0)
	s_barrier
; #define PG8_STAGE(bufoff, gbase, voff) do { _Pragma("unroll") for (int _i = 0; _i < 2; ++_i) { \
;         const unsigned _m0 = ldsu + (unsigned)(bufoff) + ldsw + (unsigned)(_i * 8192); \
;         asm volatile("s_mov_b32 m0, %2\n\ts_nop 0\n\tglobal_load_lds_dwordx4 %0, %1" :: "v"((voff)[_i]), "s"((const char*)(gbase)), "s"(_m0) : "memory"); } } while (0)
; #define PG8_LDA(dst, b, h) do { _Pragma("unroll") for (int m = 0; m < 4; ++m) _Pragma("unroll") for (int k = 0; k < 2; ++k) dst[m][k] = *(const LAS bf16x8*)(lds + PG8_SA(b, h) + aoff + m * 2048 + k * 1024); } while (0)
; #define PG8_LDB(dst, b, h) do { _Pragma("unroll") for (int n = 0; n < 2; ++n) _Pragma("unroll") for (int k = 0; k < 2; ++k) dst[n][k] = *(const LAS bf16x8*)(lds + bbase[b][h] + n * 2048 + k * 1024); } while (0)
; #define PG8_WAIT_V(n) asm volatile("s_waitcnt vmcnt(" #n ")" ::: "memory")
; #define PG8_WAIT_L(n) asm volatile("s_waitcnt lgkmcnt(" #n ")" ::: "memory")
; #define PG8_BAR __builtin_amdgcn_s_barrier()
; #define PG8_SCHED __builtin_amdgcn_sched_barrier(0)
; template <class Epi>
; __device__ __forceinline__ void gemm_phase(LAS unsigned char* lds, const Gemm g, const StaticOrder& S, const Epi& E) {
;     ...
;             PG8_WAIT_V(8); PG8_WAIT_L(0); PG8_BAR; PG8_MMA2B(1, At, At2, B0); PG8_BAR; PG8_SCHED;
;             PG8_LDB(B0, 1, 0); PG8_SCHED; PG8_LDA(At, 1, 0); PG8_LDA(At2, 1, 1); PG8_STAGE(PG8_SB(0, 1), b2 + hstepB, voffB);
;             PG8_WAIT_V(8); PG8_WAIT_L(0); PG8_BAR; PG8_MMA2B(0, At, At2, B0); PG8_BAR; PG8_SCHED;
	s_setprio 0
	s_waitcnt lgkmcnt(3)
	v_mfma_f32_16x16x32_bf16 v[116:119], v[128:131], v[166:169], v[116:119]
	s_waitcnt lgkmcnt(1)
	v_mfma_f32_16x16x32_bf16 v[112:115], v[150:153], v[166:169], v[112:115]
	v_mfma_f32_16x16x32_bf16 v[100:103], v[128:131], v[182:185], v[100:103]
	v_mfma_f32_16x16x32_bf16 v[96:99], v[150:153], v[182:185], v[96:99]
	v_mfma_f32_16x16x32_bf16 v[84:87], v[128:131], v[190:193], v[84:87]
	v_mfma_f32_16x16x32_bf16 v[80:83], v[150:153], v[190:193], v[80:83]
	v_mfma_f32_16x16x32_bf16 v[68:71], v[128:131], v[198:201], v[68:71]
	v_mfma_f32_16x16x32_bf16 v[64:67], v[150:153], v[198:201], v[64:67]
	v_mfma_f32_16x16x32_bf16 v[52:55], v[128:131], v[214:217], v[52:55]
	v_mfma_f32_16x16x32_bf16 v[48:51], v[150:153], v[214:217], v[48:51]
	v_mfma_f32_16x16x32_bf16 v[36:39], v[128:131], v[222:225], v[36:39]
	v_mfma_f32_16x16x32_bf16 v[32:35], v[150:153], v[222:225], v[32:35]
	v_mfma_f32_16x16x32_bf16 v[20:23], v[128:131], v[230:233], v[20:23]
	v_mfma_f32_16x16x32_bf16 v[16:19], v[150:153], v[230:233], v[16:19]
	v_mfma_f32_16x16x32_bf16 v[4:7], v[128:131], v[238:241], v[4:7]
	v_mfma_f32_16x16x32_bf16 v[0:3], v[150:153], v[238:241], v[0:3]
	v_mfma_f32_16x16x32_bf16 v[116:119], v[146:149], v[178:181], v[116:119]
	s_waitcnt lgkmcnt(0)
	v_mfma_f32_16x16x32_bf16 v[112:115], v[154:157], v[178:181], v[112:115]
	v_mfma_f32_16x16x32_bf16 v[100:103], v[146:149], v[186:189], v[100:103]
	v_mfma_f32_16x16x32_bf16 v[96:99], v[154:157], v[186:189], v[96:99]
	v_mfma_f32_16x16x32_bf16 v[84:87], v[146:149], v[194:197], v[84:87]
	v_mfma_f32_16x16x32_bf16 v[80:83], v[154:157], v[194:197], v[80:83]
	v_mfma_f32_16x16x32_bf16 v[68:71], v[146:149], v[202:205], v[68:71]
	v_mfma_f32_16x16x32_bf16 v[64:67], v[154:157], v[202:205], v[64:67]
	v_mfma_f32_16x16x32_bf16 v[52:55], v[146:149], v[218:221], v[52:55]
	v_mfma_f32_16x16x32_bf16 v[48:51], v[154:157], v[218:221], v[48:51]
	v_mfma_f32_16x16x32_bf16 v[36:39], v[146:149], v[226:229], v[36:39]
	v_mfma_f32_16x16x32_bf16 v[32:35], v[154:157], v[226:229], v[32:35]
	v_mfma_f32_16x16x32_bf16 v[20:23], v[146:149], v[234:237], v[20:23]
	v_mfma_f32_16x16x32_bf16 v[16:19], v[154:157], v[234:237], v[16:19]
	v_mfma_f32_16x16x32_bf16 v[4:7], v[146:149], v[242:245], v[4:7]
	v_mfma_f32_16x16x32_bf16 v[0:3], v[154:157], v[242:245], v[0:3]
	s_setprio 1
	s_barrier
	ds_read_b128 v[128:131], v143
	ds_read_b128 v[146:149], v143 offset:1024
	ds_read_b128 v[150:153], v143 offset:2048
	ds_read_b128 v[154:157], v143 offset:3072
	ds_read_b128 v[166:169], v141 offset:32768
	ds_read_b128 v[178:181], v141 offset:33792
	ds_read_b128 v[182:185], v141 offset:34816
	ds_read_b128 v[186:189], v141 offset:35840
	ds_read_b128 v[190:193], v141 offset:36864
	ds_read_b128 v[194:197], v141 offset:37888
	ds_read_b128 v[198:201], v141 offset:38912
	ds_read_b128 v[202:205], v141 offset:39936
	ds_read_b128 v[214:217], v141 offset:49152
	ds_read_b128 v[218:221], v141 offset:50176
	ds_read_b128 v[222:225], v141 offset:51200
	ds_read_b128 v[226:229], v141 offset:52224
	ds_read_b128 v[230:233], v141 offset:53248
	ds_read_b128 v[234:237], v141 offset:54272
	ds_read_b128 v[238:241], v141 offset:55296
	ds_read_b128 v[242:245], v141 offset:56320
	s_add_u32 s16, s82, 0x20000
	s_addc_u32 s17, s83, 0
	s_mov_b32 m0, s52
	s_nop 0
	global_load_lds_dwordx4 v135, s[16:17]
	s_mov_b32 m0, s53
	s_nop 0
	global_load_lds_dwordx4 v137, s[16:17]
	s_waitcnt vmcnt(8)
	s_waitcnt lgkmcnt(0)
	s_barrier
; #define PG8_STAGE(bufoff, gbase, voff) do { _Pragma("unroll") for (int _i = 0; _i < 2; ++_i) { \
;         const unsigned _m0 = ldsu + (unsigned)(bufoff) + ldsw + (unsigned)(_i * 8192); \
;         asm volatile("s_mov_b32 m0, %2\n\ts_nop 0\n\tglobal_load_lds_dwordx4 %0, %1" :: "v"((voff)[_i]), "s"((const char*)(gbase)), "s"(_m0) : "memory"); } } while (0)
; #define PG8_LDA(dst, b, h) do { _Pragma("unroll") for (int m = 0; m < 4; ++m) _Pragma("unroll") for (int k = 0; k < 2; ++k) dst[m][k] = *(const LAS bf16x8*)(lds + PG8_SA(b, h) + aoff + m * 2048 + k * 1024); } while (0)
; #define PG8_LDB(dst, b, h) do { _Pragma("unroll") for (int n = 0; n < 2; ++n) _Pragma("unroll") for (int k = 0; k < 2; ++k) dst[n][k] = *(const LAS bf16x8*)(lds + bbase[b][h] + n * 2048 + k * 1024); } while (0)
; #define PG8_WAIT_V(n) asm volatile("s_waitcnt vmcnt(" #n ")" ::: "memory")
; #define PG8_WAIT_L(n) asm volatile("s_waitcnt lgkmcnt(" #n ")" ::: "memory")
; #define PG8_BAR __builtin_amdgcn_s_barrier()
; #define PG8_SCHED __builtin_amdgcn_sched_barrier(0)
; template <class Epi>
; __device__ __forceinline__ void gemm_phase(LAS unsigned char* lds, const Gemm g, const StaticOrder& S, const Epi& E) {
;     ...
;             PG8_LDB(B0, 0, 0); PG8_SCHED; PG8_LDA(At, 0, 0); PG8_LDA(At2, 0, 1); PG8_STAGE(PG8_SB(1, 1), b1 + hstepB, voffB);
;             PG8_WAIT_V(8); PG8_WAIT_L(0); PG8_BAR; PG8_MMA2B(0, At, At2, B0); PG8_BAR; PG8_SCHED;
;             PG8_LDB(B0, 0, 1); PG8_STAGE(PG8_SB(0, 0), b2, voffB); PG8_STAGE(PG8_SA(0, 0), a2, voffA); PG8_STAGE(PG8_SA(0, 1), a2 + hstepA, voffA);
;             PG8_WAIT_V(8); PG8_WAIT_L(0); PG8_BAR; PG8_MMA2B(1, At, At2, B0); PG8_BAR; PG8_SCHED;
;             PG8_LDB(B0, 1, 0); PG8_SCHED; PG8_LDA(At, 1, 0); PG8_LDA(At2, 1, 1); PG8_STAGE(PG8_SB(0, 1), b2 + hstepB, voffB);
;             PG8_WAIT_V(8); PG8_WAIT_L(0); PG8_BAR; PG8_MMA2B(0, At, At2, B0); PG8_BAR; PG8_SCHED;
;             PG8_LDB(B0, 1, 1); PG8_STAGE(PG8_SB(1, 0), b3, voffB); PG8_STAGE(PG8_SA(1, 0), a3, voffA); PG8_STAGE(PG8_SA(1, 1), a3 + hstepA, voffA);
;             PG8_WAIT_V(8); PG8_WAIT_L(0); PG8_BAR; PG8_MMA2B(1, At, At2, B0); PG8_BAR; PG8_SCHED;
	s_setprio 0
	s_waitcnt lgkmcnt(14)
	v_mfma_f32_16x16x32_bf16 v[124:127], v[128:131], v[166:169], v[124:127]
	v_mfma_f32_16x16x32_bf16 v[120:123], v[150:153], v[166:169], v[120:123]
	s_waitcnt lgkmcnt(13)
	v_mfma_f32_16x16x32_bf16 v[108:111], v[128:131], v[182:185], v[108:111]
	v_mfma_f32_16x16x32_bf16 v[104:107], v[150:153], v[182:185], v[104:107]
	s_waitcnt lgkmcnt(11)
	v_mfma_f32_16x16x32_bf16 v[92:95], v[128:131], v[190:193], v[92:95]
	v_mfma_f32_16x16x32_bf16 v[88:91], v[150:153], v[190:193], v[88:91]
	s_waitcnt lgkmcnt(9)
	v_mfma_f32_16x16x32_bf16 v[76:79], v[128:131], v[198:201], v[76:79]
	v_mfma_f32_16x16x32_bf16 v[72:75], v[150:153], v[198:201], v[72:75]
	s_waitcnt lgkmcnt(7)
	v_mfma_f32_16x16x32_bf16 v[60:63], v[128:131], v[214:217], v[60:63]
	v_mfma_f32_16x16x32_bf16 v[56:59], v[150:153], v[214:217], v[56:59]
	s_waitcnt lgkmcnt(5)
	v_mfma_f32_16x16x32_bf16 v[44:47], v[128:131], v[222:225], v[44:47]
	v_mfma_f32_16x16x32_bf16 v[40:43], v[150:153], v[222:225], v[40:43]
	s_waitcnt lgkmcnt(3)
	v_mfma_f32_16x16x32_bf16 v[28:31], v[128:131], v[230:233], v[28:31]
	v_mfma_f32_16x16x32_bf16 v[24:27], v[150:153], v[230:233], v[24:27]
	s_waitcnt lgkmcnt(1)
	v_mfma_f32_16x16x32_bf16 v[12:15], v[128:131], v[238:241], v[12:15]
	v_mfma_f32_16x16x32_bf16 v[8:11], v[150:153], v[238:241], v[8:11]
	v_mfma_f32_16x16x32_bf16 v[124:127], v[146:149], v[178:181], v[124:127]
	v_mfma_f32_16x16x32_bf16 v[120:123], v[154:157], v[178:181], v[120:123]
	v_mfma_f32_16x16x32_bf16 v[108:111], v[146:149], v[186:189], v[108:111]
	v_mfma_f32_16x16x32_bf16 v[104:107], v[154:157], v[186:189], v[104:107]
	v_mfma_f32_16x16x32_bf16 v[92:95], v[146:149], v[194:197], v[92:95]
	v_mfma_f32_16x16x32_bf16 v[88:91], v[154:157], v[194:197], v[88:91]
	v_mfma_f32_16x16x32_bf16 v[76:79], v[146:149], v[202:205], v[76:79]
	v_mfma_f32_16x16x32_bf16 v[72:75], v[154:157], v[202:205], v[72:75]
	v_mfma_f32_16x16x32_bf16 v[60:63], v[146:149], v[218:221], v[60:63]
	v_mfma_f32_16x16x32_bf16 v[56:59], v[154:157], v[218:221], v[56:59]
	v_mfma_f32_16x16x32_bf16 v[44:47], v[146:149], v[226:229], v[44:47]
	v_mfma_f32_16x16x32_bf16 v[40:43], v[154:157], v[226:229], v[40:43]
	v_mfma_f32_16x16x32_bf16 v[28:31], v[146:149], v[234:237], v[28:31]
	v_mfma_f32_16x16x32_bf16 v[24:27], v[154:157], v[234:237], v[24:27]
	s_waitcnt lgkmcnt(0)
	v_mfma_f32_16x16x32_bf16 v[12:15], v[146:149], v[242:245], v[12:15]
	v_mfma_f32_16x16x32_bf16 v[8:11], v[154:157], v[242:245], v[8:11]
	s_setprio 1
	s_barrier
	s_add_u32 s16, s82, 0x80
	ds_read_b128 v[128:131], v144
	ds_read_b128 v[146:149], v144 offset:1024
	ds_read_b128 v[150:153], v144 offset:2048
	ds_read_b128 v[154:157], v144 offset:3072
	s_addc_u32 s17, s83, 0
	s_mov_b32 m0, s54
	s_nop 0
	global_load_lds_dwordx4 v135, s[16:17]
	s_mov_b32 m0, s55
	s_nop 0
	global_load_lds_dwordx4 v137, s[16:17]
	s_mov_b32 m0, s56
	s_nop 0
	global_load_lds_dwordx4 v134, s[80:81]
	s_mov_b32 m0, s57
	s_nop 0
	global_load_lds_dwordx4 v136, s[80:81]
	s_add_u32 s16, s42, 0x20080
	s_addc_u32 s17, s43, 0
	s_mov_b32 m0, s58
	s_nop 0
	global_load_lds_dwordx4 v134, s[16:17]
	s_mov_b32 m0, s59
	s_nop 0
	global_load_lds_dwordx4 v136, s[16:17]
	s_waitcnt vmcnt(8)
	s_waitcnt lgkmcnt(0)
	s_barrier
	s_setprio 0
	s_waitcnt lgkmcnt(3)
	v_mfma_f32_16x16x32_bf16 v[116:119], v[128:131], v[166:169], v[116:119]
	s_waitcnt lgkmcnt(1)
	v_mfma_f32_16x16x32_bf16 v[112:115], v[150:153], v[166:169], v[112:115]
	v_mfma_f32_16x16x32_bf16 v[100:103], v[128:131], v[182:185], v[100:103]
	v_mfma_f32_16x16x32_bf16 v[96:99], v[150:153], v[182:185], v[96:99]
	v_mfma_f32_16x16x32_bf16 v[84:87], v[128:131], v[190:193], v[84:87]
	v_mfma_f32_16x16x32_bf16 v[80:83], v[150:153], v[190:193], v[80:83]
	v_mfma_f32_16x16x32_bf16 v[68:71], v[128:131], v[198:201], v[68:71]
	v_mfma_f32_16x16x32_bf16 v[64:67], v[150:153], v[198:201], v[64:67]
	v_mfma_f32_16x16x32_bf16 v[52:55], v[128:131], v[214:217], v[52:55]
	v_mfma_f32_16x16x32_bf16 v[48:51], v[150:153], v[214:217], v[48:51]
	v_mfma_f32_16x16x32_bf16 v[36:39], v[128:131], v[222:225], v[36:39]
	v_mfma_f32_16x16x32_bf16 v[32:35], v[150:153], v[222:225], v[32:35]
	v_mfma_f32_16x16x32_bf16 v[20:23], v[128:131], v[230:233], v[20:23]
	v_mfma_f32_16x16x32_bf16 v[16:19], v[150:153], v[230:233], v[16:19]
	v_mfma_f32_16x16x32_bf16 v[4:7], v[128:131], v[238:241], v[4:7]
	v_mfma_f32_16x16x32_bf16 v[0:3], v[150:153], v[238:241], v[0:3]
	v_mfma_f32_16x16x32_bf16 v[116:119], v[146:149], v[178:181], v[116:119]
	s_waitcnt lgkmcnt(0)
	v_mfma_f32_16x16x32_bf16 v[112:115], v[154:157], v[178:181], v[112:115]
	v_mfma_f32_16x16x32_bf16 v[100:103], v[146:149], v[186:189], v[100:103]
	v_mfma_f32_16x16x32_bf16 v[96:99], v[154:157], v[186:189], v[96:99]
	v_mfma_f32_16x16x32_bf16 v[84:87], v[146:149], v[194:197], v[84:87]
	v_mfma_f32_16x16x32_bf16 v[80:83], v[154:157], v[194:197], v[80:83]
	v_mfma_f32_16x16x32_bf16 v[68:71], v[146:149], v[202:205], v[68:71]
	v_mfma_f32_16x16x32_bf16 v[64:67], v[154:157], v[202:205], v[64:67]
	v_mfma_f32_16x16x32_bf16 v[52:55], v[146:149], v[218:221], v[52:55]
	v_mfma_f32_16x16x32_bf16 v[48:51], v[154:157], v[218:221], v[48:51]
	v_mfma_f32_16x16x32_bf16 v[36:39], v[146:149], v[226:229], v[36:39]
	v_mfma_f32_16x16x32_bf16 v[32:35], v[154:157], v[226:229], v[32:35]
	v_mfma_f32_16x16x32_bf16 v[20:23], v[146:149], v[234:237], v[20:23]
	v_mfma_f32_16x16x32_bf16 v[16:19], v[154:157], v[234:237], v[16:19]
	v_mfma_f32_16x16x32_bf16 v[4:7], v[146:149], v[242:245], v[4:7]
	v_mfma_f32_16x16x32_bf16 v[0:3], v[154:157], v[242:245], v[0:3]
	s_setprio 1
	s_barrier
	s_add_i32 s68, s68, 2
	s_add_u32 s67, s67, 0x100
	s_addc_u32 s84, s84, 0
	s_cmp_gt_u32 s68, 5
	s_mov_b64 s[16:17], s[38:39]
	s_cbranch_scc0 .LBB0_870
	s_and_b64 vcc, exec, s[4:5]
	s_cbranch_vccz .LBB0_873
	s_barrier

; #define PG8_STAGE(bufoff, gbase, voff) do { _Pragma("unroll") for (int _i = 0; _i < 2; ++_i) { \
;         const unsigned _m0 = ldsu + (unsigned)(bufoff) + ldsw + (unsigned)(_i * 8192); \
;         asm volatile("s_mov_b32 m0, %2\n\ts_nop 0\n\tglobal_load_lds_dwordx4 %0, %1" :: "v"((voff)[_i]), "s"((const char*)(gbase)), "s"(_m0) : "memory"); } } while (0)
; #define PG8_LDA(dst, b, h) do { _Pragma("unroll") for (int m = 0; m < 4; ++m) _Pragma("unroll") for (int k = 0; k < 2; ++k) dst[m][k] = *(const LAS bf16x8*)(lds + PG8_SA(b, h) + aoff + m * 2048 + k * 1024); } while (0)
; #define PG8_LDB(dst, b, h) do { _Pragma("unroll") for (int n = 0; n < 2; ++n) _Pragma("unroll") for (int k = 0; k < 2; ++k) dst[n][k] = *(const LAS bf16x8*)(lds + bbase[b][h] + n * 2048 + k * 1024); } while (0)
; #define PG8_WAIT_V(n) asm volatile("s_waitcnt vmcnt(" #n ")" ::: "memory")
; #define PG8_WAIT_L(n) asm volatile("s_waitcnt lgkmcnt(" #n ")" ::: "memory")
; #define PG8_BAR __builtin_amdgcn_s_barrier()
; #define PG8_SCHED __builtin_amdgcn_sched_barrier(0)
; template <class Epi>
; __device__ __forceinline__ void gemm_phase(LAS unsigned char* lds, const Gemm g, const StaticOrder& S, const Epi& E) {
;     ...
;             PG8_LDB(B0, 0, 0); PG8_SCHED; PG8_LDA(At, 0, 0); PG8_LDA(At2, 0, 1); PG8_STAGE(PG8_SB(1, 1), b1 + hstepB, voffB);
;             PG8_WAIT_V(8); PG8_WAIT_L(0); PG8_BAR; PG8_MMA2B(0, At, At2, B0); PG8_BAR; PG8_SCHED;
;             PG8_LDB(B0, 0, 1); PG8_STAGE(PG8_SB(0, 0), b2, voffB); PG8_STAGE(PG8_SA(0, 0), a2, voffA); PG8_STAGE(PG8_SA(0, 1), a2 + hstepA, voffA);
;             PG8_WAIT_V(8); PG8_WAIT_L(0); PG8_BAR; PG8_MMA2B(1, At, At2, B0); PG8_BAR; PG8_SCHED;
;             PG8_LDB(B0, 1, 0); PG8_SCHED; PG8_LDA(At, 1, 0); PG8_LDA(At2, 1, 1); PG8_STAGE(PG8_SB(0, 1), b2 + hstepB, voffB);
;             PG8_WAIT_V(8); PG8_WAIT_L(0); PG8_BAR; PG8_MMA2B(0, At, At2, B0); PG8_BAR; PG8_SCHED;
;             PG8_LDB(B0, 1, 1); PG8_STAGE(PG8_SB(1, 0), b3, voffB); PG8_STAGE(PG8_SA(1, 0), a3, voffA); PG8_STAGE(PG8_SA(1, 1), a3 + hstepA, voffA);
;             PG8_WAIT_V(8); PG8_WAIT_L(0); PG8_BAR; PG8_MMA2B(1, At, At2, B0); PG8_BAR; PG8_SCHED;
.LBB0_943:
	ds_read_b128 v[128:131], v138
	ds_read_b128 v[144:147], v138 offset:1024
	ds_read_b128 v[148:151], v138 offset:2048
	ds_read_b128 v[152:155], v138 offset:3072
	s_cmp_eq_u32 s68, 12
	s_cselect_b32 s38, s66, s84
	s_cselect_b32 s39, s13, s85
	s_cselect_b32 s82, s67, s86
	s_cselect_b32 s83, s5, s87
	s_add_u32 s42, s38, 0x80
	s_addc_u32 s43, s39, 0
	s_add_u32 s80, s82, 0x80
	s_addc_u32 s81, s83, 0
	ds_read_b128 v[156:159], v139
	ds_read_b128 v[166:169], v139 offset:1024
	ds_read_b128 v[178:181], v139 offset:2048
	ds_read_b128 v[182:185], v139 offset:3072
	ds_read_b128 v[186:189], v139 offset:4096
	ds_read_b128 v[190:193], v139 offset:5120
	ds_read_b128 v[194:197], v139 offset:6144
	ds_read_b128 v[198:201], v139 offset:7168
	ds_read_b128 v[202:205], v139 offset:16384
	ds_read_b128 v[214:217], v139 offset:17408
	ds_read_b128 v[218:221], v139 offset:18432
	ds_read_b128 v[222:225], v139 offset:19456
	ds_read_b128 v[226:229], v139 offset:20480
	ds_read_b128 v[230:233], v139 offset:21504
	ds_read_b128 v[234:237], v139 offset:22528
	ds_read_b128 v[238:241], v139 offset:23552
	s_mov_b32 m0, s61
	s_nop 0
	global_load_lds_dwordx4 v133, s[6:7]
	s_mov_b32 m0, s63
	s_nop 0
	global_load_lds_dwordx4 v135, s[6:7]
	s_waitcnt vmcnt(8)
	s_waitcnt lgkmcnt(0)
	s_barrier
	s_setprio 0
	s_waitcnt lgkmcnt(14)
	v_mfma_f32_16x16x32_bf16 v[124:127], v[128:131], v[156:159], v[124:127]
	v_mfma_f32_16x16x32_bf16 v[120:123], v[148:151], v[156:159], v[120:123]
	s_waitcnt lgkmcnt(13)
	v_mfma_f32_16x16x32_bf16 v[108:111], v[128:131], v[178:181], v[108:111]
	v_mfma_f32_16x16x32_bf16 v[104:107], v[148:151], v[178:181], v[104:107]
	s_waitcnt lgkmcnt(11)
	v_mfma_f32_16x16x32_bf16 v[92:95], v[128:131], v[186:189], v[92:95]
	v_mfma_f32_16x16x32_bf16 v[88:91], v[148:151], v[186:189], v[88:91]
	s_waitcnt lgkmcnt(9)
	v_mfma_f32_16x16x32_bf16 v[76:79], v[128:131], v[194:197], v[76:79]
	v_mfma_f32_16x16x32_bf16 v[72:75], v[148:151], v[194:197], v[72:75]
	s_waitcnt lgkmcnt(7)
	v_mfma_f32_16x16x32_bf16 v[60:63], v[128:131], v[202:205], v[60:63]
	v_mfma_f32_16x16x32_bf16 v[56:59], v[148:151], v[202:205], v[56:59]
	s_waitcnt lgkmcnt(5)
	v_mfma_f32_16x16x32_bf16 v[44:47], v[128:131], v[218:221], v[44:47]
	v_mfma_f32_16x16x32_bf16 v[40:43], v[148:151], v[218:221], v[40:43]
	s_waitcnt lgkmcnt(3)
	v_mfma_f32_16x16x32_bf16 v[28:31], v[128:131], v[226:229], v[28:31]
	v_mfma_f32_16x16x32_bf16 v[24:27], v[148:151], v[226:229], v[24:27]
	s_waitcnt lgkmcnt(1)
	v_mfma_f32_16x16x32_bf16 v[12:15], v[128:131], v[234:237], v[12:15]
	v_mfma_f32_16x16x32_bf16 v[8:11], v[148:151], v[234:237], v[8:11]
	v_mfma_f32_16x16x32_bf16 v[124:127], v[144:147], v[166:169], v[124:127]
	v_mfma_f32_16x16x32_bf16 v[120:123], v[152:155], v[166:169], v[120:123]
	v_mfma_f32_16x16x32_bf16 v[108:111], v[144:147], v[182:185], v[108:111]
	v_mfma_f32_16x16x32_bf16 v[104:107], v[152:155], v[182:185], v[104:107]
	v_mfma_f32_16x16x32_bf16 v[92:95], v[144:147], v[190:193], v[92:95]
	v_mfma_f32_16x16x32_bf16 v[88:91], v[152:155], v[190:193], v[88:91]
	v_mfma_f32_16x16x32_bf16 v[76:79], v[144:147], v[198:201], v[76:79]
	v_mfma_f32_16x16x32_bf16 v[72:75], v[152:155], v[198:201], v[72:75]
	v_mfma_f32_16x16x32_bf16 v[60:63], v[144:147], v[214:217], v[60:63]
	v_mfma_f32_16x16x32_bf16 v[56:59], v[152:155], v[214:217], v[56:59]
	v_mfma_f32_16x16x32_bf16 v[44:47], v[144:147], v[222:225], v[44:47]
	v_mfma_f32_16x16x32_bf16 v[40:43], v[152:155], v[222:225], v[40:43]
	v_mfma_f32_16x16x32_bf16 v[28:31], v[144:147], v[230:233], v[28:31]
	v_mfma_f32_16x16x32_bf16 v[24:27], v[152:155], v[230:233], v[24:27]
	s_waitcnt lgkmcnt(0)
	v_mfma_f32_16x16x32_bf16 v[12:15], v[144:147], v[238:241], v[12:15]
	v_mfma_f32_16x16x32_bf16 v[8:11], v[152:155], v[238:241], v[8:11]
	s_setprio 1
	s_barrier
	ds_read_b128 v[128:131], v140
	ds_read_b128 v[144:147], v140 offset:1024
	ds_read_b128 v[148:151], v140 offset:2048
	ds_read_b128 v[152:155], v140 offset:3072
	s_mov_b32 m0, s48
	s_nop 0
	global_load_lds_dwordx4 v133, s[82:83]
	s_mov_b32 m0, s49
	s_nop 0
	global_load_lds_dwordx4 v135, s[82:83]
	s_mov_b32 m0, s47
	s_nop 0
	global_load_lds_dwordx4 v132, s[38:39]
	s_mov_b32 m0, s50
	s_nop 0
	global_load_lds_dwordx4 v134, s[38:39]
	s_add_u32 s88, s38, 0x40000
	s_addc_u32 s89, s39, 0
	s_mov_b32 m0, s51
	s_nop 0
	global_load_lds_dwordx4 v132, s[88:89]
	s_mov_b32 m0, s52
	s_nop 0
	global_load_lds_dwordx4 v134, s[88:89]
	s_waitcnt vmcnt(8)
	s_waitcnt lgkmcnt(0)
	s_barrier
	s_setprio 0
	s_waitcnt lgkmcnt(3)
	v_mfma_f32_16x16x32_bf16 v[116:119], v[128:131], v[156:159], v[116:119]
	s_waitcnt lgkmcnt(1)
	v_mfma_f32_16x16x32_bf16 v[112:115], v[148:151], v[156:159], v[112:115]
	v_mfma_f32_16x16x32_bf16 v[100:103], v[128:131], v[178:181], v[100:103]
	v_mfma_f32_16x16x32_bf16 v[96:99], v[148:151], v[178:181], v[96:99]
	v_mfma_f32_16x16x32_bf16 v[84:87], v[128:131], v[186:189], v[84:87]
	v_mfma_f32_16x16x32_bf16 v[80:83], v[148:151], v[186:189], v[80:83]
	v_mfma_f32_16x16x32_bf16 v[68:71], v[128:131], v[194:197], v[68:71]
	v_mfma_f32_16x16x32_bf16 v[64:67], v[148:151], v[194:197], v[64:67]
	v_mfma_f32_16x16x32_bf16 v[52:55], v[128:131], v[202:205], v[52:55]
	v_mfma_f32_16x16x32_bf16 v[48:51], v[148:151], v[202:205], v[48:51]
	v_mfma_f32_16x16x32_bf16 v[36:39], v[128:131], v[218:221], v[36:39]
	v_mfma_f32_16x16x32_bf16 v[32:35], v[148:151], v[218:221], v[32:35]
	v_mfma_f32_16x16x32_bf16 v[20:23], v[128:131], v[226:229], v[20:23]
	v_mfma_f32_16x16x32_bf16 v[16:19], v[148:151], v[226:229], v[16:19]
	v_mfma_f32_16x16x32_bf16 v[4:7], v[128:131], v[234:237], v[4:7]
	v_mfma_f32_16x16x32_bf16 v[0:3], v[148:151], v[234:237], v[0:3]
	v_mfma_f32_16x16x32_bf16 v[116:119], v[144:147], v[166:169], v[116:119]
	s_waitcnt lgkmcnt(0)
	v_mfma_f32_16x16x32_bf16 v[112:115], v[152:155], v[166:169], v[112:115]
	v_mfma_f32_16x16x32_bf16 v[100:103], v[144:147], v[182:185], v[100:103]
	v_mfma_f32_16x16x32_bf16 v[96:99], v[152:155], v[182:185], v[96:99]
	v_mfma_f32_16x16x32_bf16 v[84:87], v[144:147], v[190:193], v[84:87]
	v_mfma_f32_16x16x32_bf16 v[80:83], v[152:155], v[190:193], v[80:83]
	v_mfma_f32_16x16x32_bf16 v[68:71], v[144:147], v[198:201], v[68:71]
	v_mfma_f32_16x16x32_bf16 v[64:67], v[152:155], v[198:201], v[64:67]
	v_mfma_f32_16x16x32_bf16 v[52:55], v[144:147], v[214:217], v[52:55]
	v_mfma_f32_16x16x32_bf16 v[48:51], v[152:155], v[214:217], v[48:51]
	v_mfma_f32_16x16x32_bf16 v[36:39], v[144:147], v[222:225], v[36:39]
	v_mfma_f32_16x16x32_bf16 v[32:35], v[152:155], v[222:225], v[32:35]
	v_mfma_f32_16x16x32_bf16 v[20:23], v[144:147], v[230:233], v[20:23]
	v_mfma_f32_16x16x32_bf16 v[16:19], v[152:155], v[230:233], v[16:19]
	v_mfma_f32_16x16x32_bf16 v[4:7], v[144:147], v[238:241], v[4:7]
	v_mfma_f32_16x16x32_bf16 v[0:3], v[152:155], v[238:241], v[0:3]
	s_setprio 1
	s_barrier
; #define PG8_STAGE(bufoff, gbase, voff) do { _Pragma("unroll") for (int _i = 0; _i < 2; ++_i) { \
;         const unsigned _m0 = ldsu + (unsigned)(bufoff) + ldsw + (unsigned)(_i * 8192); \
;         asm volatile("s_mov_b32 m0, %2\n\ts_nop 0\n\tglobal_load_lds_dwordx4 %0, %1" :: "v"((voff)[_i]), "s"((const char*)(gbase)), "s"(_m0) : "memory"); } } while (0)
; #define PG8_LDA(dst, b, h) do { _Pragma("unroll") for (int m = 0; m < 4; ++m) _Pragma("unroll") for (int k = 0; k < 2; ++k) dst[m][k] = *(const LAS bf16x8*)(lds + PG8_SA(b, h) + aoff + m * 2048 + k * 1024); } while (0)
; #define PG8_LDB(dst, b, h) do { _Pragma("unroll") for (int n = 0; n < 2; ++n) _Pragma("unroll") for (int k = 0; k < 2; ++k) dst[n][k] = *(const LAS bf16x8*)(lds + bbase[b][h] + n * 2048 + k * 1024); } while (0)
; #define PG8_WAIT_V(n) asm volatile("s_waitcnt vmcnt(" #n ")" ::: "memory")
; #define PG8_WAIT_L(n) asm volatile("s_waitcnt lgkmcnt(" #n ")" ::: "memory")
; #define PG8_BAR __builtin_amdgcn_s_barrier()
; #define PG8_SCHED __builtin_amdgcn_sched_barrier(0)
; template <class Epi>
; __device__ __forceinline__ void gemm_phase(LAS unsigned char* lds, const Gemm g, const StaticOrder& S, const Epi& E) {
;     ...
;             PG8_LDB(B0, 0, 0); PG8_SCHED; PG8_LDA(At, 0, 0); PG8_LDA(At2, 0, 1); PG8_STAGE(PG8_SB(1, 1), b1 + hstepB, voffB);
;             PG8_WAIT_V(8); PG8_WAIT_L(0); PG8_BAR; PG8_MMA2B(0, At, At2, B0); PG8_BAR; PG8_SCHED;
;             PG8_LDB(B0, 0, 1); PG8_STAGE(PG8_SB(0, 0), b2, voffB); PG8_STAGE(PG8_SA(0, 0), a2, voffA); PG8_STAGE(PG8_SA(0, 1), a2 + hstepA, voffA);
;             PG8_WAIT_V(8); PG8_WAIT_L(0); PG8_BAR; PG8_MMA2B(1, At, At2, B0); PG8_BAR; PG8_SCHED;
;             PG8_LDB(B0, 1, 0); PG8_SCHED; PG8_LDA(At, 1, 0); PG8_LDA(At2, 1, 1); PG8_STAGE(PG8_SB(0, 1), b2 + hstepB, voffB);
;             PG8_WAIT_V(8); PG8_WAIT_L(0); PG8_BAR; PG8_MMA2B(0, At, At2, B0); PG8_BAR; PG8_SCHED;
;             PG8_LDB(B0, 1, 1); PG8_STAGE(PG8_SB(1, 0), b3, voffB); PG8_STAGE(PG8_SA(1, 0), a3, voffA); PG8_STAGE(PG8_SA(1, 1), a3 + hstepA, voffA);
;             PG8_WAIT_V(8); PG8_WAIT_L(0); PG8_BAR; PG8_MMA2B(1, At, At2, B0); PG8_BAR; PG8_SCHED;
	ds_read_b128 v[128:131], v141
	ds_read_b128 v[144:147], v141 offset:1024
	ds_read_b128 v[148:151], v141 offset:2048
	ds_read_b128 v[152:155], v141 offset:3072
	ds_read_b128 v[156:159], v139 offset:32768
	ds_read_b128 v[166:169], v139 offset:33792
	ds_read_b128 v[178:181], v139 offset:34816
	ds_read_b128 v[182:185], v139 offset:35840
	ds_read_b128 v[186:189], v139 offset:36864
	ds_read_b128 v[190:193], v139 offset:37888
	ds_read_b128 v[194:197], v139 offset:38912
	ds_read_b128 v[198:201], v139 offset:39936
	ds_read_b128 v[202:205], v139 offset:49152
	ds_read_b128 v[214:217], v139 offset:50176
	ds_read_b128 v[218:221], v139 offset:51200
	ds_read_b128 v[222:225], v139 offset:52224
	ds_read_b128 v[226:229], v139 offset:53248
	ds_read_b128 v[230:233], v139 offset:54272
	ds_read_b128 v[234:237], v139 offset:55296
	ds_read_b128 v[238:241], v139 offset:56320
	s_add_u32 s82, s82, 0x40000
	s_addc_u32 s83, s83, 0
	s_mov_b32 m0, s53
	s_nop 0
	global_load_lds_dwordx4 v133, s[82:83]
	s_mov_b32 m0, s54
	s_nop 0
	global_load_lds_dwordx4 v135, s[82:83]
	s_waitcnt vmcnt(8)
	s_waitcnt lgkmcnt(0)
	s_barrier
	s_setprio 0
	s_waitcnt lgkmcnt(14)
	v_mfma_f32_16x16x32_bf16 v[124:127], v[128:131], v[156:159], v[124:127]
	v_mfma_f32_16x16x32_bf16 v[120:123], v[148:151], v[156:159], v[120:123]
	s_waitcnt lgkmcnt(13)
	v_mfma_f32_16x16x32_bf16 v[108:111], v[128:131], v[178:181], v[108:111]
	v_mfma_f32_16x16x32_bf16 v[104:107], v[148:151], v[178:181], v[104:107]
	s_waitcnt lgkmcnt(11)
	v_mfma_f32_16x16x32_bf16 v[92:95], v[128:131], v[186:189], v[92:95]
	v_mfma_f32_16x16x32_bf16 v[88:91], v[148:151], v[186:189], v[88:91]
	s_waitcnt lgkmcnt(9)
	v_mfma_f32_16x16x32_bf16 v[76:79], v[128:131], v[194:197], v[76:79]
	v_mfma_f32_16x16x32_bf16 v[72:75], v[148:151], v[194:197], v[72:75]
	s_waitcnt lgkmcnt(7)
	v_mfma_f32_16x16x32_bf16 v[60:63], v[128:131], v[202:205], v[60:63]
	v_mfma_f32_16x16x32_bf16 v[56:59], v[148:151], v[202:205], v[56:59]
	s_waitcnt lgkmcnt(5)
	v_mfma_f32_16x16x32_bf16 v[44:47], v[128:131], v[218:221], v[44:47]
	v_mfma_f32_16x16x32_bf16 v[40:43], v[148:151], v[218:221], v[40:43]
	s_waitcnt lgkmcnt(3)
	v_mfma_f32_16x16x32_bf16 v[28:31], v[128:131], v[226:229], v[28:31]
	v_mfma_f32_16x16x32_bf16 v[24:27], v[148:151], v[226:229], v[24:27]
	s_waitcnt lgkmcnt(1)
	v_mfma_f32_16x16x32_bf16 v[12:15], v[128:131], v[234:237], v[12:15]
	v_mfma_f32_16x16x32_bf16 v[8:11], v[148:151], v[234:237], v[8:11]
	v_mfma_f32_16x16x32_bf16 v[124:127], v[144:147], v[166:169], v[124:127]
	v_mfma_f32_16x16x32_bf16 v[120:123], v[152:155], v[166:169], v[120:123]
	v_mfma_f32_16x16x32_bf16 v[108:111], v[144:147], v[182:185], v[108:111]
	v_mfma_f32_16x16x32_bf16 v[104:107], v[152:155], v[182:185], v[104:107]
	v_mfma_f32_16x16x32_bf16 v[92:95], v[144:147], v[190:193], v[92:95]
	v_mfma_f32_16x16x32_bf16 v[88:91], v[152:155], v[190:193], v[88:91]
	v_mfma_f32_16x16x32_bf16 v[76:79], v[144:147], v[198:201], v[76:79]
	v_mfma_f32_16x16x32_bf16 v[72:75], v[152:155], v[198:201], v[72:75]
	v_mfma_f32_16x16x32_bf16 v[60:63], v[144:147], v[214:217], v[60:63]
	v_mfma_f32_16x16x32_bf16 v[56:59], v[152:155], v[214:217], v[56:59]
	v_mfma_f32_16x16x32_bf16 v[44:47], v[144:147], v[222:225], v[44:47]
	v_mfma_f32_16x16x32_bf16 v[40:43], v[152:155], v[222:225], v[40:43]
	v_mfma_f32_16x16x32_bf16 v[28:31], v[144:147], v[230:233], v[28:31]
	v_mfma_f32_16x16x32_bf16 v[24:27], v[152:155], v[230:233], v[24:27]
	s_waitcnt lgkmcnt(0)
	v_mfma_f32_16x16x32_bf16 v[12:15], v[144:147], v[238:241], v[12:15]
	v_mfma_f32_16x16x32_bf16 v[8:11], v[152:155], v[238:241], v[8:11]
	s_setprio 1
	s_barrier
	ds_read_b128 v[128:131], v142
	ds_read_b128 v[144:147], v142 offset:1024
	ds_read_b128 v[148:151], v142 offset:2048
	ds_read_b128 v[152:155], v142 offset:3072
	s_mov_b32 m0, s55
	s_nop 0
	global_load_lds_dwordx4 v133, s[80:81]
	s_mov_b32 m0, s56
	s_nop 0
	global_load_lds_dwordx4 v135, s[80:81]
	s_mov_b32 m0, s57
	s_nop 0
	global_load_lds_dwordx4 v132, s[42:43]
	s_mov_b32 m0, s58
	s_nop 0
	global_load_lds_dwordx4 v134, s[42:43]
	s_add_u32 s38, s38, 0x40080
	s_addc_u32 s39, s39, 0
	s_mov_b32 m0, s59
	s_nop 0
	global_load_lds_dwordx4 v132, s[38:39]
	s_mov_b32 m0, s60
	s_nop 0
	global_load_lds_dwordx4 v134, s[38:39]
	s_waitcnt vmcnt(8)
	s_waitcnt lgkmcnt(0)
	s_barrier
	s_setprio 0
	s_waitcnt lgkmcnt(3)
	v_mfma_f32_16x16x32_bf16 v[116:119], v[128:131], v[156:159], v[116:119]
	s_waitcnt lgkmcnt(1)
	v_mfma_f32_16x16x32_bf16 v[112:115], v[148:151], v[156:159], v[112:115]
	v_mfma_f32_16x16x32_bf16 v[100:103], v[128:131], v[178:181], v[100:103]
	v_mfma_f32_16x16x32_bf16 v[96:99], v[148:151], v[178:181], v[96:99]
	v_mfma_f32_16x16x32_bf16 v[84:87], v[128:131], v[186:189], v[84:87]
	v_mfma_f32_16x16x32_bf16 v[80:83], v[148:151], v[186:189], v[80:83]
	v_mfma_f32_16x16x32_bf16 v[68:71], v[128:131], v[194:197], v[68:71]
	v_mfma_f32_16x16x32_bf16 v[64:67], v[148:151], v[194:197], v[64:67]
	v_mfma_f32_16x16x32_bf16 v[52:55], v[128:131], v[202:205], v[52:55]
	v_mfma_f32_16x16x32_bf16 v[48:51], v[148:151], v[202:205], v[48:51]
	v_mfma_f32_16x16x32_bf16 v[36:39], v[128:131], v[218:221], v[36:39]
	v_mfma_f32_16x16x32_bf16 v[32:35], v[148:151], v[218:221], v[32:35]
	v_mfma_f32_16x16x32_bf16 v[20:23], v[128:131], v[226:229], v[20:23]
	v_mfma_f32_16x16x32_bf16 v[16:19], v[148:151], v[226:229], v[16:19]
	v_mfma_f32_16x16x32_bf16 v[4:7], v[128:131], v[234:237], v[4:7]
	v_mfma_f32_16x16x32_bf16 v[0:3], v[148:151], v[234:237], v[0:3]
	v_mfma_f32_16x16x32_bf16 v[116:119], v[144:147], v[166:169], v[116:119]
	s_waitcnt lgkmcnt(0)
	v_mfma_f32_16x16x32_bf16 v[112:115], v[152:155], v[166:169], v[112:115]
	v_mfma_f32_16x16x32_bf16 v[100:103], v[144:147], v[182:185], v[100:103]
	v_mfma_f32_16x16x32_bf16 v[96:99], v[152:155], v[182:185], v[96:99]
	v_mfma_f32_16x16x32_bf16 v[84:87], v[144:147], v[190:193], v[84:87]
	v_mfma_f32_16x16x32_bf16 v[80:83], v[152:155], v[190:193], v[80:83]
	v_mfma_f32_16x16x32_bf16 v[68:71], v[144:147], v[198:201], v[68:71]
	v_mfma_f32_16x16x32_bf16 v[64:67], v[152:155], v[198:201], v[64:67]
	v_mfma_f32_16x16x32_bf16 v[52:55], v[144:147], v[214:217], v[52:55]
	v_mfma_f32_16x16x32_bf16 v[48:51], v[152:155], v[214:217], v[48:51]
	v_mfma_f32_16x16x32_bf16 v[36:39], v[144:147], v[222:225], v[36:39]
	v_mfma_f32_16x16x32_bf16 v[32:35], v[152:155], v[222:225], v[32:35]
	v_mfma_f32_16x16x32_bf16 v[20:23], v[144:147], v[230:233], v[20:23]
	v_mfma_f32_16x16x32_bf16 v[16:19], v[152:155], v[230:233], v[16:19]
	v_mfma_f32_16x16x32_bf16 v[4:7], v[144:147], v[238:241], v[4:7]
	v_mfma_f32_16x16x32_bf16 v[0:3], v[152:155], v[238:241], v[0:3]
	s_setprio 1
	s_barrier
	s_add_i32 s68, s68, 2
	s_add_u32 s6, s6, 0x100
	s_addc_u32 s7, s7, 0
	s_add_u32 s84, s84, 0x100
	s_addc_u32 s85, s85, 0
	s_add_u32 s86, s86, 0x100
	s_addc_u32 s87, s87, 0
	s_cmp_gt_u32 s68, 13
	s_cbranch_scc0 .LBB0_943
	s_and_b64 vcc, exec, s[2:3]
	s_cbranch_vccz .LBB0_946
	s_barrier

; #define PG8_STAGE(bufoff, gbase, voff) do { _Pragma("unroll") for (int _i = 0; _i < 2; ++_i) { \
;         const unsigned _m0 = ldsu + (unsigned)(bufoff) + ldsw + (unsigned)(_i * 8192); \
;         asm volatile("s_mov_b32 m0, %2\n\ts_nop 0\n\tglobal_load_lds_dwordx4 %0, %1" :: "v"((voff)[_i]), "s"((const char*)(gbase)), "s"(_m0) : "memory"); } } while (0)
; #define PG8_LDA(dst, b, h) do { _Pragma("unroll") for (int m = 0; m < 4; ++m) _Pragma("unroll") for (int k = 0; k < 2; ++k) dst[m][k] = *(const LAS bf16x8*)(lds + PG8_SA(b, h) + aoff + m * 2048 + k * 1024); } while (0)
; #define PG8_LDB(dst, b, h) do { _Pragma("unroll") for (int n = 0; n < 2; ++n) _Pragma("unroll") for (int k = 0; k < 2; ++k) dst[n][k] = *(const LAS bf16x8*)(lds + bbase[b][h] + n * 2048 + k * 1024); } while (0)
; #define PG8_WAIT_V(n) asm volatile("s_waitcnt vmcnt(" #n ")" ::: "memory")
; #define PG8_WAIT_L(n) asm volatile("s_waitcnt lgkmcnt(" #n ")" ::: "memory")
; #define PG8_BAR __builtin_amdgcn_s_barrier()
; #define PG8_SCHED __builtin_amdgcn_sched_barrier(0)
; template <class Epi>
; __device__ __forceinline__ void gemm_phase(LAS unsigned char* lds, const Gemm g, const StaticOrder& S, const Epi& E) {
;     ...
;             PG8_LDB(B0, 0, 0); PG8_SCHED; PG8_LDA(At, 0, 0); PG8_LDA(At2, 0, 1); PG8_STAGE(PG8_SB(1, 1), b1 + hstepB, voffB);
;             PG8_WAIT_V(8); PG8_WAIT_L(0); PG8_BAR; PG8_MMA2B(0, At, At2, B0); PG8_BAR; PG8_SCHED;
;             PG8_LDB(B0, 0, 1); PG8_STAGE(PG8_SB(0, 0), b2, voffB); PG8_STAGE(PG8_SA(0, 0), a2, voffA); PG8_STAGE(PG8_SA(0, 1), a2 + hstepA, voffA);
;             PG8_WAIT_V(8); PG8_WAIT_L(0); PG8_BAR; PG8_MMA2B(1, At, At2, B0); PG8_BAR; PG8_SCHED;
;             PG8_LDB(B0, 1, 0); PG8_SCHED; PG8_LDA(At, 1, 0); PG8_LDA(At2, 1, 1); PG8_STAGE(PG8_SB(0, 1), b2 + hstepB, voffB);
;             PG8_WAIT_V(8); PG8_WAIT_L(0); PG8_BAR; PG8_MMA2B(0, At, At2, B0); PG8_BAR; PG8_SCHED;
;             PG8_LDB(B0, 1, 1); PG8_STAGE(PG8_SB(1, 0), b3, voffB); PG8_STAGE(PG8_SA(1, 0), a3, voffA); PG8_STAGE(PG8_SA(1, 1), a3 + hstepA, voffA);
;             PG8_WAIT_V(8); PG8_WAIT_L(0); PG8_BAR; PG8_MMA2B(1, At, At2, B0); PG8_BAR; PG8_SCHED;
.LBB0_1027:
	ds_read_b128 v[68:71], v220
	ds_read_b128 v[84:87], v220 offset:1024
	ds_read_b128 v[88:91], v220 offset:2048
	ds_read_b128 v[92:95], v220 offset:3072
	s_add_u32 s12, s10, 0x100
	s_addc_u32 s13, s11, 0
	s_cmp_eq_u32 s69, 12
	s_cselect_b32 s14, s97, vcc_hi
	s_cselect_b32 s15, s7, s68
	s_cselect_b32 s84, vcc_lo, s12
	s_cselect_b32 s85, s39, s13
	s_add_u32 s16, s14, 0x80
	s_addc_u32 s17, s15, 0
	ds_read_b128 v[96:99], v221
	ds_read_b128 v[100:103], v221 offset:1024
	ds_read_b128 v[152:155], v221 offset:2048
	ds_read_b128 v[156:159], v221 offset:3072
	ds_read_b128 v[166:169], v221 offset:4096
	ds_read_b128 v[178:181], v221 offset:5120
	ds_read_b128 v[182:185], v221 offset:6144
	ds_read_b128 v[186:189], v221 offset:7168
	ds_read_b128 v[190:193], v221 offset:16384
	ds_read_b128 v[194:197], v221 offset:17408
	ds_read_b128 v[198:201], v221 offset:18432
	ds_read_b128 v[202:205], v221 offset:19456
	ds_read_b128 v[226:229], v221 offset:20480
	ds_read_b128 v[230:233], v221 offset:21504
	ds_read_b128 v[234:237], v221 offset:22528
	ds_read_b128 v[238:241], v221 offset:23552
	s_add_u32 s10, s10, 0x40080
	s_addc_u32 s11, s11, 0
	s_mov_b32 m0, s58
	s_nop 0
	global_load_lds_dwordx4 v217, s[10:11]
	s_mov_b32 m0, s60
	s_nop 0
	global_load_lds_dwordx4 v219, s[10:11]
	s_waitcnt vmcnt(8)
	s_waitcnt lgkmcnt(0)
	s_barrier
	s_setprio 0
	s_waitcnt lgkmcnt(14)
	v_mfma_f32_16x16x32_bf16 v[80:83], v[68:71], v[96:99], v[80:83]
	v_mfma_f32_16x16x32_bf16 v[76:79], v[88:91], v[96:99], v[76:79]
	s_waitcnt lgkmcnt(13)
	v_mfma_f32_16x16x32_bf16 v[148:151], v[68:71], v[152:155], v[148:151]
	v_mfma_f32_16x16x32_bf16 v[52:55], v[88:91], v[152:155], v[52:55]
	s_waitcnt lgkmcnt(11)
	v_mfma_f32_16x16x32_bf16 v[144:147], v[68:71], v[166:169], v[144:147]
	v_mfma_f32_16x16x32_bf16 v[48:51], v[88:91], v[166:169], v[48:51]
	s_waitcnt lgkmcnt(9)
	v_mfma_f32_16x16x32_bf16 v[136:139], v[68:71], v[182:185], v[136:139]
	v_mfma_f32_16x16x32_bf16 v[40:43], v[88:91], v[182:185], v[40:43]
	s_waitcnt lgkmcnt(7)
	v_mfma_f32_16x16x32_bf16 v[124:127], v[68:71], v[190:193], v[124:127]
	v_mfma_f32_16x16x32_bf16 v[28:31], v[88:91], v[190:193], v[28:31]
	s_waitcnt lgkmcnt(5)
	v_mfma_f32_16x16x32_bf16 v[120:123], v[68:71], v[198:201], v[120:123]
	v_mfma_f32_16x16x32_bf16 v[24:27], v[88:91], v[198:201], v[24:27]
	s_waitcnt lgkmcnt(3)
	v_mfma_f32_16x16x32_bf16 v[112:115], v[68:71], v[226:229], v[112:115]
	v_mfma_f32_16x16x32_bf16 v[16:19], v[88:91], v[226:229], v[16:19]
	s_waitcnt lgkmcnt(1)
	v_mfma_f32_16x16x32_bf16 v[64:67], v[68:71], v[234:237], v[64:67]
	v_mfma_f32_16x16x32_bf16 v[4:7], v[88:91], v[234:237], v[4:7]
	v_mfma_f32_16x16x32_bf16 v[80:83], v[84:87], v[100:103], v[80:83]
	v_mfma_f32_16x16x32_bf16 v[76:79], v[92:95], v[100:103], v[76:79]
	v_mfma_f32_16x16x32_bf16 v[148:151], v[84:87], v[156:159], v[148:151]
	v_mfma_f32_16x16x32_bf16 v[52:55], v[92:95], v[156:159], v[52:55]
	v_mfma_f32_16x16x32_bf16 v[144:147], v[84:87], v[178:181], v[144:147]
	v_mfma_f32_16x16x32_bf16 v[48:51], v[92:95], v[178:181], v[48:51]
	v_mfma_f32_16x16x32_bf16 v[136:139], v[84:87], v[186:189], v[136:139]
	v_mfma_f32_16x16x32_bf16 v[40:43], v[92:95], v[186:189], v[40:43]
	v_mfma_f32_16x16x32_bf16 v[124:127], v[84:87], v[194:197], v[124:127]
	v_mfma_f32_16x16x32_bf16 v[28:31], v[92:95], v[194:197], v[28:31]
	v_mfma_f32_16x16x32_bf16 v[120:123], v[84:87], v[202:205], v[120:123]
	v_mfma_f32_16x16x32_bf16 v[24:27], v[92:95], v[202:205], v[24:27]
	v_mfma_f32_16x16x32_bf16 v[112:115], v[84:87], v[230:233], v[112:115]
	v_mfma_f32_16x16x32_bf16 v[16:19], v[92:95], v[230:233], v[16:19]
	s_waitcnt lgkmcnt(0)
	v_mfma_f32_16x16x32_bf16 v[64:67], v[84:87], v[238:241], v[64:67]
	v_mfma_f32_16x16x32_bf16 v[4:7], v[92:95], v[238:241], v[4:7]
	s_setprio 1
	s_barrier
	ds_read_b128 v[68:71], v222
	ds_read_b128 v[84:87], v222 offset:1024
	ds_read_b128 v[88:91], v222 offset:2048
	ds_read_b128 v[92:95], v222 offset:3072
	s_mov_b32 m0, s48
	s_nop 0
	global_load_lds_dwordx4 v217, s[84:85]
	s_mov_b32 m0, s49
	s_nop 0
	global_load_lds_dwordx4 v219, s[84:85]
	s_mov_b32 m0, s47
	s_nop 0
	global_load_lds_dwordx4 v216, s[14:15]
	s_mov_b32 m0, s50
	s_nop 0
	global_load_lds_dwordx4 v218, s[14:15]
	s_add_u32 s10, s14, 0x40000
	s_addc_u32 s11, s15, 0
	s_mov_b32 m0, s51
	s_nop 0
	global_load_lds_dwordx4 v216, s[10:11]
	s_mov_b32 m0, s52
	s_nop 0
	global_load_lds_dwordx4 v218, s[10:11]
	s_waitcnt vmcnt(8)
	s_waitcnt lgkmcnt(0)
	s_barrier
	s_setprio 0
	s_waitcnt lgkmcnt(3)
	v_mfma_f32_16x16x32_bf16 v[72:75], v[68:71], v[96:99], v[72:75]
	s_waitcnt lgkmcnt(1)
	v_mfma_f32_16x16x32_bf16 v[56:59], v[88:91], v[96:99], v[56:59]
	v_mfma_f32_16x16x32_bf16 v[44:47], v[88:91], v[152:155], v[44:47]
	v_mfma_f32_16x16x32_bf16 v[36:39], v[88:91], v[166:169], v[36:39]
	v_mfma_f32_16x16x32_bf16 v[128:131], v[68:71], v[182:185], v[128:131]
	v_mfma_f32_16x16x32_bf16 v[32:35], v[88:91], v[182:185], v[32:35]
	v_mfma_f32_16x16x32_bf16 v[116:119], v[68:71], v[190:193], v[116:119]
	v_mfma_f32_16x16x32_bf16 v[20:23], v[88:91], v[190:193], v[20:23]
	v_mfma_f32_16x16x32_bf16 v[108:111], v[68:71], v[198:201], v[108:111]
	v_mfma_f32_16x16x32_bf16 v[12:15], v[88:91], v[198:201], v[12:15]
	v_mfma_f32_16x16x32_bf16 v[104:107], v[68:71], v[226:229], v[104:107]
	v_mfma_f32_16x16x32_bf16 v[8:11], v[88:91], v[226:229], v[8:11]
	v_mfma_f32_16x16x32_bf16 v[60:63], v[68:71], v[234:237], v[60:63]
	v_mfma_f32_16x16x32_bf16 v[0:3], v[88:91], v[234:237], v[0:3]
	v_mfma_f32_16x16x32_bf16 v[72:75], v[84:87], v[100:103], v[72:75]
	s_waitcnt lgkmcnt(0)
	v_mfma_f32_16x16x32_bf16 v[56:59], v[92:95], v[100:103], v[56:59]
	v_mfma_f32_16x16x32_bf16 v[96:99], v[68:71], v[152:155], v[140:143]
	v_mfma_f32_16x16x32_bf16 v[44:47], v[92:95], v[156:159], v[44:47]
	v_mfma_f32_16x16x32_bf16 v[100:103], v[68:71], v[166:169], v[132:135]
	v_mfma_f32_16x16x32_bf16 v[36:39], v[92:95], v[178:181], v[36:39]
	v_mfma_f32_16x16x32_bf16 v[128:131], v[84:87], v[186:189], v[128:131]
	v_mfma_f32_16x16x32_bf16 v[32:35], v[92:95], v[186:189], v[32:35]
	v_mfma_f32_16x16x32_bf16 v[116:119], v[84:87], v[194:197], v[116:119]
	v_mfma_f32_16x16x32_bf16 v[20:23], v[92:95], v[194:197], v[20:23]
	v_mfma_f32_16x16x32_bf16 v[108:111], v[84:87], v[202:205], v[108:111]
	v_mfma_f32_16x16x32_bf16 v[12:15], v[92:95], v[202:205], v[12:15]
	v_mfma_f32_16x16x32_bf16 v[104:107], v[84:87], v[230:233], v[104:107]
	v_mfma_f32_16x16x32_bf16 v[8:11], v[92:95], v[230:233], v[8:11]
	v_mfma_f32_16x16x32_bf16 v[60:63], v[84:87], v[238:241], v[60:63]
	v_mfma_f32_16x16x32_bf16 v[0:3], v[92:95], v[238:241], v[0:3]
	v_mfma_f32_16x16x32_bf16 v[96:99], v[84:87], v[156:159], v[96:99]
	v_mfma_f32_16x16x32_bf16 v[100:103], v[84:87], v[178:181], v[100:103]
	s_setprio 1
	s_barrier
; #define PG8_STAGE(bufoff, gbase, voff) do { _Pragma("unroll") for (int _i = 0; _i < 2; ++_i) { \
;         const unsigned _m0 = ldsu + (unsigned)(bufoff) + ldsw + (unsigned)(_i * 8192); \
;         asm volatile("s_mov_b32 m0, %2\n\ts_nop 0\n\tglobal_load_lds_dwordx4 %0, %1" :: "v"((voff)[_i]), "s"((const char*)(gbase)), "s"(_m0) : "memory"); } } while (0)
; #define PG8_LDA(dst, b, h) do { _Pragma("unroll") for (int m = 0; m < 4; ++m) _Pragma("unroll") for (int k = 0; k < 2; ++k) dst[m][k] = *(const LAS bf16x8*)(lds + PG8_SA(b, h) + aoff + m * 2048 + k * 1024); } while (0)
; #define PG8_LDB(dst, b, h) do { _Pragma("unroll") for (int n = 0; n < 2; ++n) _Pragma("unroll") for (int k = 0; k < 2; ++k) dst[n][k] = *(const LAS bf16x8*)(lds + bbase[b][h] + n * 2048 + k * 1024); } while (0)
; #define PG8_WAIT_V(n) asm volatile("s_waitcnt vmcnt(" #n ")" ::: "memory")
; #define PG8_WAIT_L(n) asm volatile("s_waitcnt lgkmcnt(" #n ")" ::: "memory")
; #define PG8_BAR __builtin_amdgcn_s_barrier()
; #define PG8_SCHED __builtin_amdgcn_sched_barrier(0)
; template <class Epi>
; __device__ __forceinline__ void gemm_phase(LAS unsigned char* lds, const Gemm g, const StaticOrder& S, const Epi& E) {
;     ...
;             PG8_LDB(B0, 0, 0); PG8_SCHED; PG8_LDA(At, 0, 0); PG8_LDA(At2, 0, 1); PG8_STAGE(PG8_SB(1, 1), b1 + hstepB, voffB);
;             PG8_WAIT_V(8); PG8_WAIT_L(0); PG8_BAR; PG8_MMA2B(0, At, At2, B0); PG8_BAR; PG8_SCHED;
;             PG8_LDB(B0, 0, 1); PG8_STAGE(PG8_SB(0, 0), b2, voffB); PG8_STAGE(PG8_SA(0, 0), a2, voffA); PG8_STAGE(PG8_SA(0, 1), a2 + hstepA, voffA);
;             PG8_WAIT_V(8); PG8_WAIT_L(0); PG8_BAR; PG8_MMA2B(1, At, At2, B0); PG8_BAR; PG8_SCHED;
;             PG8_LDB(B0, 1, 0); PG8_SCHED; PG8_LDA(At, 1, 0); PG8_LDA(At2, 1, 1); PG8_STAGE(PG8_SB(0, 1), b2 + hstepB, voffB);
;             PG8_WAIT_V(8); PG8_WAIT_L(0); PG8_BAR; PG8_MMA2B(0, At, At2, B0); PG8_BAR; PG8_SCHED;
;             PG8_LDB(B0, 1, 1); PG8_STAGE(PG8_SB(1, 0), b3, voffB); PG8_STAGE(PG8_SA(1, 0), a3, voffA); PG8_STAGE(PG8_SA(1, 1), a3 + hstepA, voffA);
;             PG8_WAIT_V(8); PG8_WAIT_L(0); PG8_BAR; PG8_MMA2B(1, At, At2, B0); PG8_BAR; PG8_SCHED;
	ds_read_b128 v[68:71], v223
	ds_read_b128 v[84:87], v223 offset:1024
	ds_read_b128 v[88:91], v223 offset:2048
	ds_read_b128 v[92:95], v223 offset:3072
	ds_read_b128 v[132:135], v221 offset:32768
	ds_read_b128 v[140:143], v221 offset:33792
	ds_read_b128 v[152:155], v221 offset:34816
	ds_read_b128 v[156:159], v221 offset:35840
	ds_read_b128 v[166:169], v221 offset:36864
	ds_read_b128 v[178:181], v221 offset:37888
	ds_read_b128 v[182:185], v221 offset:38912
	ds_read_b128 v[186:189], v221 offset:39936
	ds_read_b128 v[190:193], v221 offset:49152
	ds_read_b128 v[194:197], v221 offset:50176
	ds_read_b128 v[198:201], v221 offset:51200
	ds_read_b128 v[202:205], v221 offset:52224
	ds_read_b128 v[226:229], v221 offset:53248
	ds_read_b128 v[230:233], v221 offset:54272
	ds_read_b128 v[234:237], v221 offset:55296
	ds_read_b128 v[238:241], v221 offset:56320
	s_add_u32 s10, s84, 0x40000
	s_addc_u32 s11, s85, 0
	s_mov_b32 m0, s53
	s_nop 0
	global_load_lds_dwordx4 v217, s[10:11]
	s_mov_b32 m0, s54
	s_nop 0
	global_load_lds_dwordx4 v219, s[10:11]
	s_waitcnt vmcnt(8)
	s_waitcnt lgkmcnt(0)
	s_barrier
	s_setprio 0
	s_waitcnt lgkmcnt(14)
	v_mfma_f32_16x16x32_bf16 v[80:83], v[68:71], v[132:135], v[80:83]
	v_mfma_f32_16x16x32_bf16 v[76:79], v[88:91], v[132:135], v[76:79]
	s_waitcnt lgkmcnt(13)
	v_mfma_f32_16x16x32_bf16 v[148:151], v[68:71], v[152:155], v[148:151]
	v_mfma_f32_16x16x32_bf16 v[52:55], v[88:91], v[152:155], v[52:55]
	s_waitcnt lgkmcnt(11)
	v_mfma_f32_16x16x32_bf16 v[144:147], v[68:71], v[166:169], v[144:147]
	v_mfma_f32_16x16x32_bf16 v[48:51], v[88:91], v[166:169], v[48:51]
	s_waitcnt lgkmcnt(9)
	v_mfma_f32_16x16x32_bf16 v[136:139], v[68:71], v[182:185], v[136:139]
	v_mfma_f32_16x16x32_bf16 v[40:43], v[88:91], v[182:185], v[40:43]
	s_waitcnt lgkmcnt(7)
	v_mfma_f32_16x16x32_bf16 v[124:127], v[68:71], v[190:193], v[124:127]
	v_mfma_f32_16x16x32_bf16 v[28:31], v[88:91], v[190:193], v[28:31]
	s_waitcnt lgkmcnt(5)
	v_mfma_f32_16x16x32_bf16 v[120:123], v[68:71], v[198:201], v[120:123]
	v_mfma_f32_16x16x32_bf16 v[24:27], v[88:91], v[198:201], v[24:27]
	s_waitcnt lgkmcnt(3)
	v_mfma_f32_16x16x32_bf16 v[112:115], v[68:71], v[226:229], v[112:115]
	v_mfma_f32_16x16x32_bf16 v[16:19], v[88:91], v[226:229], v[16:19]
	s_waitcnt lgkmcnt(1)
	v_mfma_f32_16x16x32_bf16 v[64:67], v[68:71], v[234:237], v[64:67]
	v_mfma_f32_16x16x32_bf16 v[4:7], v[88:91], v[234:237], v[4:7]
	v_mfma_f32_16x16x32_bf16 v[80:83], v[84:87], v[140:143], v[80:83]
	v_mfma_f32_16x16x32_bf16 v[76:79], v[92:95], v[140:143], v[76:79]
	v_mfma_f32_16x16x32_bf16 v[148:151], v[84:87], v[156:159], v[148:151]
	v_mfma_f32_16x16x32_bf16 v[52:55], v[92:95], v[156:159], v[52:55]
	v_mfma_f32_16x16x32_bf16 v[144:147], v[84:87], v[178:181], v[144:147]
	v_mfma_f32_16x16x32_bf16 v[48:51], v[92:95], v[178:181], v[48:51]
	v_mfma_f32_16x16x32_bf16 v[136:139], v[84:87], v[186:189], v[136:139]
	v_mfma_f32_16x16x32_bf16 v[40:43], v[92:95], v[186:189], v[40:43]
	v_mfma_f32_16x16x32_bf16 v[124:127], v[84:87], v[194:197], v[124:127]
	v_mfma_f32_16x16x32_bf16 v[28:31], v[92:95], v[194:197], v[28:31]
	v_mfma_f32_16x16x32_bf16 v[120:123], v[84:87], v[202:205], v[120:123]
	v_mfma_f32_16x16x32_bf16 v[24:27], v[92:95], v[202:205], v[24:27]
	v_mfma_f32_16x16x32_bf16 v[112:115], v[84:87], v[230:233], v[112:115]
	v_mfma_f32_16x16x32_bf16 v[16:19], v[92:95], v[230:233], v[16:19]
	s_waitcnt lgkmcnt(0)
	v_mfma_f32_16x16x32_bf16 v[64:67], v[84:87], v[238:241], v[64:67]
	v_mfma_f32_16x16x32_bf16 v[4:7], v[92:95], v[238:241], v[4:7]
	s_setprio 1
	s_barrier
; #define PG8_STAGE(bufoff, gbase, voff) do { _Pragma("unroll") for (int _i = 0; _i < 2; ++_i) { \
;         const unsigned _m0 = ldsu + (unsigned)(bufoff) + ldsw + (unsigned)(_i * 8192); \
;         asm volatile("s_mov_b32 m0, %2\n\ts_nop 0\n\tglobal_load_lds_dwordx4 %0, %1" :: "v"((voff)[_i]), "s"((const char*)(gbase)), "s"(_m0) : "memory"); } } while (0)
; #define PG8_LDA(dst, b, h) do { _Pragma("unroll") for (int m = 0; m < 4; ++m) _Pragma("unroll") for (int k = 0; k < 2; ++k) dst[m][k] = *(const LAS bf16x8*)(lds + PG8_SA(b, h) + aoff + m * 2048 + k * 1024); } while (0)
; #define PG8_LDB(dst, b, h) do { _Pragma("unroll") for (int n = 0; n < 2; ++n) _Pragma("unroll") for (int k = 0; k < 2; ++k) dst[n][k] = *(const LAS bf16x8*)(lds + bbase[b][h] + n * 2048 + k * 1024); } while (0)
; #define PG8_WAIT_V(n) asm volatile("s_waitcnt vmcnt(" #n ")" ::: "memory")
; #define PG8_WAIT_L(n) asm volatile("s_waitcnt lgkmcnt(" #n ")" ::: "memory")
; #define PG8_BAR __builtin_amdgcn_s_barrier()
; #define PG8_SCHED __builtin_amdgcn_sched_barrier(0)
; template <class Epi>
; __device__ __forceinline__ void gemm_phase(LAS unsigned char* lds, const Gemm g, const StaticOrder& S, const Epi& E) {
;     ...
;             PG8_LDB(B0, 0, 0); PG8_SCHED; PG8_LDA(At, 0, 0); PG8_LDA(At2, 0, 1); PG8_STAGE(PG8_SB(1, 1), b1 + hstepB, voffB);
;             PG8_WAIT_V(8); PG8_WAIT_L(0); PG8_BAR; PG8_MMA2B(0, At, At2, B0); PG8_BAR; PG8_SCHED;
;             PG8_LDB(B0, 0, 1); PG8_STAGE(PG8_SB(0, 0), b2, voffB); PG8_STAGE(PG8_SA(0, 0), a2, voffA); PG8_STAGE(PG8_SA(0, 1), a2 + hstepA, voffA);
;             PG8_WAIT_V(8); PG8_WAIT_L(0); PG8_BAR; PG8_MMA2B(1, At, At2, B0); PG8_BAR; PG8_SCHED;
;             PG8_LDB(B0, 1, 0); PG8_SCHED; PG8_LDA(At, 1, 0); PG8_LDA(At2, 1, 1); PG8_STAGE(PG8_SB(0, 1), b2 + hstepB, voffB);
;             PG8_WAIT_V(8); PG8_WAIT_L(0); PG8_BAR; PG8_MMA2B(0, At, At2, B0); PG8_BAR; PG8_SCHED;
;             PG8_LDB(B0, 1, 1); PG8_STAGE(PG8_SB(1, 0), b3, voffB); PG8_STAGE(PG8_SA(1, 0), a3, voffA); PG8_STAGE(PG8_SA(1, 1), a3 + hstepA, voffA);
;             PG8_WAIT_V(8); PG8_WAIT_L(0); PG8_BAR; PG8_MMA2B(1, At, At2, B0); PG8_BAR; PG8_SCHED;
	s_add_u32 s10, s84, 0x80
	ds_read_b128 v[68:71], v224
	ds_read_b128 v[84:87], v224 offset:1024
	ds_read_b128 v[88:91], v224 offset:2048
	ds_read_b128 v[92:95], v224 offset:3072
	s_addc_u32 s11, s85, 0
	s_mov_b32 m0, s88
	s_nop 0
	global_load_lds_dwordx4 v217, s[10:11]
	s_mov_b32 m0, s89
	s_nop 0
	global_load_lds_dwordx4 v219, s[10:11]
	s_mov_b32 m0, s95
	s_nop 0
	global_load_lds_dwordx4 v216, s[16:17]
	s_mov_b32 m0, s37
	s_nop 0
	global_load_lds_dwordx4 v218, s[16:17]
	s_add_u32 s10, s14, 0x40080
	s_addc_u32 s11, s15, 0
	s_mov_b32 m0, s56
	s_nop 0
	global_load_lds_dwordx4 v216, s[10:11]
	s_mov_b32 m0, s57
	s_nop 0
	global_load_lds_dwordx4 v218, s[10:11]
	s_waitcnt vmcnt(8)
	s_waitcnt lgkmcnt(0)
	s_barrier
	s_setprio 0
	s_waitcnt lgkmcnt(3)
	v_mfma_f32_16x16x32_bf16 v[72:75], v[68:71], v[132:135], v[72:75]
	s_waitcnt lgkmcnt(1)
	v_mfma_f32_16x16x32_bf16 v[56:59], v[88:91], v[132:135], v[56:59]
	v_mfma_f32_16x16x32_bf16 v[96:99], v[68:71], v[152:155], v[96:99]
	v_mfma_f32_16x16x32_bf16 v[72:75], v[84:87], v[140:143], v[72:75]
	s_waitcnt lgkmcnt(0)
	v_mfma_f32_16x16x32_bf16 v[56:59], v[92:95], v[140:143], v[56:59]
	v_mfma_f32_16x16x32_bf16 v[140:143], v[84:87], v[156:159], v[96:99]
	v_mfma_f32_16x16x32_bf16 v[96:99], v[68:71], v[166:169], v[100:103]
	v_mfma_f32_16x16x32_bf16 v[132:135], v[84:87], v[178:181], v[96:99]
	v_mfma_f32_16x16x32_bf16 v[96:99], v[68:71], v[182:185], v[128:131]
	v_mfma_f32_16x16x32_bf16 v[128:131], v[84:87], v[186:189], v[96:99]
	v_mfma_f32_16x16x32_bf16 v[96:99], v[68:71], v[190:193], v[116:119]
	v_mfma_f32_16x16x32_bf16 v[116:119], v[84:87], v[194:197], v[96:99]
	v_mfma_f32_16x16x32_bf16 v[96:99], v[68:71], v[198:201], v[108:111]
	v_mfma_f32_16x16x32_bf16 v[44:47], v[88:91], v[152:155], v[44:47]
	v_mfma_f32_16x16x32_bf16 v[36:39], v[88:91], v[166:169], v[36:39]
	v_mfma_f32_16x16x32_bf16 v[32:35], v[88:91], v[182:185], v[32:35]
	v_mfma_f32_16x16x32_bf16 v[20:23], v[88:91], v[190:193], v[20:23]
	v_mfma_f32_16x16x32_bf16 v[108:111], v[84:87], v[202:205], v[96:99]
	v_mfma_f32_16x16x32_bf16 v[12:15], v[88:91], v[198:201], v[12:15]
	v_mfma_f32_16x16x32_bf16 v[96:99], v[68:71], v[226:229], v[104:107]
	v_mfma_f32_16x16x32_bf16 v[8:11], v[88:91], v[226:229], v[8:11]
	v_mfma_f32_16x16x32_bf16 v[60:63], v[68:71], v[234:237], v[60:63]
	v_mfma_f32_16x16x32_bf16 v[0:3], v[88:91], v[234:237], v[0:3]
	v_mfma_f32_16x16x32_bf16 v[44:47], v[92:95], v[156:159], v[44:47]
	v_mfma_f32_16x16x32_bf16 v[36:39], v[92:95], v[178:181], v[36:39]
	v_mfma_f32_16x16x32_bf16 v[32:35], v[92:95], v[186:189], v[32:35]
	v_mfma_f32_16x16x32_bf16 v[20:23], v[92:95], v[194:197], v[20:23]
	v_mfma_f32_16x16x32_bf16 v[12:15], v[92:95], v[202:205], v[12:15]
	v_mfma_f32_16x16x32_bf16 v[104:107], v[84:87], v[230:233], v[96:99]
	v_mfma_f32_16x16x32_bf16 v[8:11], v[92:95], v[230:233], v[8:11]
	v_mfma_f32_16x16x32_bf16 v[60:63], v[84:87], v[238:241], v[60:63]
	v_mfma_f32_16x16x32_bf16 v[0:3], v[92:95], v[238:241], v[0:3]
	s_setprio 1
	s_barrier
	s_add_i32 s69, s69, 2
	s_add_u32 vcc_hi, vcc_hi, 0x100
	s_addc_u32 s68, s68, 0
	s_cmp_gt_u32 s69, 13
	s_mov_b64 s[10:11], s[12:13]
	s_cbranch_scc0 .LBB0_1027
	s_and_b64 vcc, exec, s[90:91]
	s_cbranch_vccz .LBB0_1030
	v_lshlrev_b32_e32 v68, 4, v215
	v_add3_u32 v68, v214, s59, v68
	s_ashr_i32 s97, s96, 31
	s_lshl_b64 s[12:13], s[96:97], 14
	v_ashrrev_i32_e32 v69, 31, v68
	s_add_u32 s12, s18, s12
	s_addc_u32 s13, s19, s13
	v_lshlrev_b64 v[70:71], 6, v[68:69]
	v_lshl_add_u64 v[70:71], s[12:13], 0, v[70:71]
	global_load_dwordx4 v[86:89], v[70:71], off
	global_load_dwordx4 v[90:93], v[70:71], off offset:16
	global_load_dwordx4 v[94:97], v[70:71], off offset:32
	global_load_dwordx4 v[98:101], v[70:71], off offset:48
	s_barrier

; #define PG8_STAGE(bufoff, gbase, voff) do { _Pragma("unroll") for (int _i = 0; _i < 2; ++_i) { \
;         const unsigned _m0 = ldsu + (unsigned)(bufoff) + ldsw + (unsigned)(_i * 8192); \
;         asm volatile("s_mov_b32 m0, %2\n\ts_nop 0\n\tglobal_load_lds_dwordx4 %0, %1" :: "v"((voff)[_i]), "s"((const char*)(gbase)), "s"(_m0) : "memory"); } } while (0)
; #define PG8_LDA(dst, b, h) do { _Pragma("unroll") for (int m = 0; m < 4; ++m) _Pragma("unroll") for (int k = 0; k < 2; ++k) dst[m][k] = *(const LAS bf16x8*)(lds + PG8_SA(b, h) + aoff + m * 2048 + k * 1024); } while (0)
; #define PG8_LDB(dst, b, h) do { _Pragma("unroll") for (int n = 0; n < 2; ++n) _Pragma("unroll") for (int k = 0; k < 2; ++k) dst[n][k] = *(const LAS bf16x8*)(lds + bbase[b][h] + n * 2048 + k * 1024); } while (0)
; #define PG8_WAIT_V(n) asm volatile("s_waitcnt vmcnt(" #n ")" ::: "memory")
; #define PG8_WAIT_L(n) asm volatile("s_waitcnt lgkmcnt(" #n ")" ::: "memory")
; #define PG8_BAR __builtin_amdgcn_s_barrier()
; #define PG8_SCHED __builtin_amdgcn_sched_barrier(0)
; template <class Epi>
; __device__ __forceinline__ void gemm_phase(LAS unsigned char* lds, const Gemm g, const StaticOrder& S, const Epi& E) {
;     ...
;             PG8_LDB(B0, 0, 0); PG8_SCHED; PG8_LDA(At, 0, 0); PG8_LDA(At2, 0, 1); PG8_STAGE(PG8_SB(1, 1), b1 + hstepB, voffB);
;             PG8_WAIT_V(8); PG8_WAIT_L(0); PG8_BAR; PG8_MMA2B(0, At, At2, B0); PG8_BAR; PG8_SCHED;
;             PG8_LDB(B0, 0, 1); PG8_STAGE(PG8_SB(0, 0), b2, voffB); PG8_STAGE(PG8_SA(0, 0), a2, voffA); PG8_STAGE(PG8_SA(0, 1), a2 + hstepA, voffA);
;             PG8_WAIT_V(8); PG8_WAIT_L(0); PG8_BAR; PG8_MMA2B(1, At, At2, B0); PG8_BAR; PG8_SCHED;
;             PG8_LDB(B0, 1, 0); PG8_SCHED; PG8_LDA(At, 1, 0); PG8_LDA(At2, 1, 1); PG8_STAGE(PG8_SB(0, 1), b2 + hstepB, voffB);
;             PG8_WAIT_V(8); PG8_WAIT_L(0); PG8_BAR; PG8_MMA2B(0, At, At2, B0); PG8_BAR; PG8_SCHED;
;             PG8_LDB(B0, 1, 1); PG8_STAGE(PG8_SB(1, 0), b3, voffB); PG8_STAGE(PG8_SA(1, 0), a3, voffA); PG8_STAGE(PG8_SA(1, 1), a3 + hstepA, voffA);
;             PG8_WAIT_V(8); PG8_WAIT_L(0); PG8_BAR; PG8_MMA2B(1, At, At2, B0); PG8_BAR; PG8_SCHED;
.LBB0_1140:
	ds_read_b128 v[128:131], v138
	ds_read_b128 v[144:147], v138 offset:1024
	ds_read_b128 v[148:151], v138 offset:2048
	ds_read_b128 v[152:155], v138 offset:3072
	s_cmp_eq_u32 s68, 40
	s_cselect_b32 s14, s4, s80
	s_cselect_b32 s15, s5, s81
	s_cselect_b32 s42, s10, s82
	s_cselect_b32 s43, s11, s83
	s_add_u32 s16, s14, 0x80
	s_addc_u32 s17, s15, 0
	s_add_u32 s38, s42, 0x80
	s_addc_u32 s39, s43, 0
	ds_read_b128 v[156:159], v139
	ds_read_b128 v[166:169], v139 offset:1024
	ds_read_b128 v[178:181], v139 offset:2048
	ds_read_b128 v[182:185], v139 offset:3072
	ds_read_b128 v[186:189], v139 offset:4096
	ds_read_b128 v[190:193], v139 offset:5120
	ds_read_b128 v[194:197], v139 offset:6144
	ds_read_b128 v[198:201], v139 offset:7168
	ds_read_b128 v[202:205], v139 offset:16384
	ds_read_b128 v[214:217], v139 offset:17408
	ds_read_b128 v[218:221], v139 offset:18432
	ds_read_b128 v[222:225], v139 offset:19456
	ds_read_b128 v[226:229], v139 offset:20480
	ds_read_b128 v[230:233], v139 offset:21504
	ds_read_b128 v[234:237], v139 offset:22528
	ds_read_b128 v[238:241], v139 offset:23552
	s_mov_b32 m0, s61
	s_nop 0
	global_load_lds_dwordx4 v133, s[12:13]
	s_mov_b32 m0, s63
	s_nop 0
	global_load_lds_dwordx4 v135, s[12:13]
	s_waitcnt vmcnt(8)
	s_waitcnt lgkmcnt(0)
	s_barrier
	s_setprio 0
	s_waitcnt lgkmcnt(14)
	v_mfma_f32_16x16x32_bf16 v[124:127], v[128:131], v[156:159], v[124:127]
	v_mfma_f32_16x16x32_bf16 v[120:123], v[148:151], v[156:159], v[120:123]
	s_waitcnt lgkmcnt(13)
	v_mfma_f32_16x16x32_bf16 v[108:111], v[128:131], v[178:181], v[108:111]
	v_mfma_f32_16x16x32_bf16 v[104:107], v[148:151], v[178:181], v[104:107]
	s_waitcnt lgkmcnt(11)
	v_mfma_f32_16x16x32_bf16 v[92:95], v[128:131], v[186:189], v[92:95]
	v_mfma_f32_16x16x32_bf16 v[88:91], v[148:151], v[186:189], v[88:91]
	s_waitcnt lgkmcnt(9)
	v_mfma_f32_16x16x32_bf16 v[76:79], v[128:131], v[194:197], v[76:79]
	v_mfma_f32_16x16x32_bf16 v[72:75], v[148:151], v[194:197], v[72:75]
	s_waitcnt lgkmcnt(7)
	v_mfma_f32_16x16x32_bf16 v[60:63], v[128:131], v[202:205], v[60:63]
	v_mfma_f32_16x16x32_bf16 v[56:59], v[148:151], v[202:205], v[56:59]
	s_waitcnt lgkmcnt(5)
	v_mfma_f32_16x16x32_bf16 v[44:47], v[128:131], v[218:221], v[44:47]
	v_mfma_f32_16x16x32_bf16 v[40:43], v[148:151], v[218:221], v[40:43]
	s_waitcnt lgkmcnt(3)
	v_mfma_f32_16x16x32_bf16 v[28:31], v[128:131], v[226:229], v[28:31]
	v_mfma_f32_16x16x32_bf16 v[24:27], v[148:151], v[226:229], v[24:27]
	s_waitcnt lgkmcnt(1)
	v_mfma_f32_16x16x32_bf16 v[12:15], v[128:131], v[234:237], v[12:15]
	v_mfma_f32_16x16x32_bf16 v[8:11], v[148:151], v[234:237], v[8:11]
	v_mfma_f32_16x16x32_bf16 v[124:127], v[144:147], v[166:169], v[124:127]
	v_mfma_f32_16x16x32_bf16 v[120:123], v[152:155], v[166:169], v[120:123]
	v_mfma_f32_16x16x32_bf16 v[108:111], v[144:147], v[182:185], v[108:111]
	v_mfma_f32_16x16x32_bf16 v[104:107], v[152:155], v[182:185], v[104:107]
	v_mfma_f32_16x16x32_bf16 v[92:95], v[144:147], v[190:193], v[92:95]
	v_mfma_f32_16x16x32_bf16 v[88:91], v[152:155], v[190:193], v[88:91]
	v_mfma_f32_16x16x32_bf16 v[76:79], v[144:147], v[198:201], v[76:79]
	v_mfma_f32_16x16x32_bf16 v[72:75], v[152:155], v[198:201], v[72:75]
	v_mfma_f32_16x16x32_bf16 v[60:63], v[144:147], v[214:217], v[60:63]
	v_mfma_f32_16x16x32_bf16 v[56:59], v[152:155], v[214:217], v[56:59]
	v_mfma_f32_16x16x32_bf16 v[44:47], v[144:147], v[222:225], v[44:47]
	v_mfma_f32_16x16x32_bf16 v[40:43], v[152:155], v[222:225], v[40:43]
	v_mfma_f32_16x16x32_bf16 v[28:31], v[144:147], v[230:233], v[28:31]
	v_mfma_f32_16x16x32_bf16 v[24:27], v[152:155], v[230:233], v[24:27]
	s_waitcnt lgkmcnt(0)
	v_mfma_f32_16x16x32_bf16 v[12:15], v[144:147], v[238:241], v[12:15]
	v_mfma_f32_16x16x32_bf16 v[8:11], v[152:155], v[238:241], v[8:11]
	s_setprio 1
	s_barrier
	ds_read_b128 v[128:131], v140
	ds_read_b128 v[144:147], v140 offset:1024
	ds_read_b128 v[148:151], v140 offset:2048
	ds_read_b128 v[152:155], v140 offset:3072
	s_mov_b32 m0, s48
	s_nop 0
	global_load_lds_dwordx4 v133, s[42:43]
	s_mov_b32 m0, s49
	s_nop 0
	global_load_lds_dwordx4 v135, s[42:43]
	s_mov_b32 m0, s47
	s_nop 0
	global_load_lds_dwordx4 v132, s[14:15]
	s_mov_b32 m0, s50
	s_nop 0
	global_load_lds_dwordx4 v134, s[14:15]
	s_add_u32 s84, s14, 0xb0000
	s_addc_u32 s85, s15, 0
	s_mov_b32 m0, s51
	s_nop 0
	global_load_lds_dwordx4 v132, s[84:85]
	s_mov_b32 m0, s52
	s_nop 0
	global_load_lds_dwordx4 v134, s[84:85]
	s_waitcnt vmcnt(8)
	s_waitcnt lgkmcnt(0)
	s_barrier
	s_setprio 0
	s_waitcnt lgkmcnt(3)
	v_mfma_f32_16x16x32_bf16 v[116:119], v[128:131], v[156:159], v[116:119]
	s_waitcnt lgkmcnt(1)
	v_mfma_f32_16x16x32_bf16 v[112:115], v[148:151], v[156:159], v[112:115]
	v_mfma_f32_16x16x32_bf16 v[100:103], v[128:131], v[178:181], v[100:103]
	v_mfma_f32_16x16x32_bf16 v[96:99], v[148:151], v[178:181], v[96:99]
	v_mfma_f32_16x16x32_bf16 v[84:87], v[128:131], v[186:189], v[84:87]
	v_mfma_f32_16x16x32_bf16 v[80:83], v[148:151], v[186:189], v[80:83]
	v_mfma_f32_16x16x32_bf16 v[68:71], v[128:131], v[194:197], v[68:71]
	v_mfma_f32_16x16x32_bf16 v[64:67], v[148:151], v[194:197], v[64:67]
	v_mfma_f32_16x16x32_bf16 v[52:55], v[128:131], v[202:205], v[52:55]
	v_mfma_f32_16x16x32_bf16 v[48:51], v[148:151], v[202:205], v[48:51]
	v_mfma_f32_16x16x32_bf16 v[36:39], v[128:131], v[218:221], v[36:39]
	v_mfma_f32_16x16x32_bf16 v[32:35], v[148:151], v[218:221], v[32:35]
	v_mfma_f32_16x16x32_bf16 v[20:23], v[128:131], v[226:229], v[20:23]
	v_mfma_f32_16x16x32_bf16 v[16:19], v[148:151], v[226:229], v[16:19]
	v_mfma_f32_16x16x32_bf16 v[4:7], v[128:131], v[234:237], v[4:7]
	v_mfma_f32_16x16x32_bf16 v[0:3], v[148:151], v[234:237], v[0:3]
	v_mfma_f32_16x16x32_bf16 v[116:119], v[144:147], v[166:169], v[116:119]
	s_waitcnt lgkmcnt(0)
	v_mfma_f32_16x16x32_bf16 v[112:115], v[152:155], v[166:169], v[112:115]
	v_mfma_f32_16x16x32_bf16 v[100:103], v[144:147], v[182:185], v[100:103]
	v_mfma_f32_16x16x32_bf16 v[96:99], v[152:155], v[182:185], v[96:99]
	v_mfma_f32_16x16x32_bf16 v[84:87], v[144:147], v[190:193], v[84:87]
	v_mfma_f32_16x16x32_bf16 v[80:83], v[152:155], v[190:193], v[80:83]
	v_mfma_f32_16x16x32_bf16 v[68:71], v[144:147], v[198:201], v[68:71]
	v_mfma_f32_16x16x32_bf16 v[64:67], v[152:155], v[198:201], v[64:67]
	v_mfma_f32_16x16x32_bf16 v[52:55], v[144:147], v[214:217], v[52:55]
	v_mfma_f32_16x16x32_bf16 v[48:51], v[152:155], v[214:217], v[48:51]
	v_mfma_f32_16x16x32_bf16 v[36:39], v[144:147], v[222:225], v[36:39]
	v_mfma_f32_16x16x32_bf16 v[32:35], v[152:155], v[222:225], v[32:35]
	v_mfma_f32_16x16x32_bf16 v[20:23], v[144:147], v[230:233], v[20:23]
	v_mfma_f32_16x16x32_bf16 v[16:19], v[152:155], v[230:233], v[16:19]
	v_mfma_f32_16x16x32_bf16 v[4:7], v[144:147], v[238:241], v[4:7]
	v_mfma_f32_16x16x32_bf16 v[0:3], v[152:155], v[238:241], v[0:3]
	s_setprio 1
	s_barrier
; #define PG8_STAGE(bufoff, gbase, voff) do { _Pragma("unroll") for (int _i = 0; _i < 2; ++_i) { \
;         const unsigned _m0 = ldsu + (unsigned)(bufoff) + ldsw + (unsigned)(_i * 8192); \
;         asm volatile("s_mov_b32 m0, %2\n\ts_nop 0\n\tglobal_load_lds_dwordx4 %0, %1" :: "v"((voff)[_i]), "s"((const char*)(gbase)), "s"(_m0) : "memory"); } } while (0)
; #define PG8_LDA(dst, b, h) do { _Pragma("unroll") for (int m = 0; m < 4; ++m) _Pragma("unroll") for (int k = 0; k < 2; ++k) dst[m][k] = *(const LAS bf16x8*)(lds + PG8_SA(b, h) + aoff + m * 2048 + k * 1024); } while (0)
; #define PG8_LDB(dst, b, h) do { _Pragma("unroll") for (int n = 0; n < 2; ++n) _Pragma("unroll") for (int k = 0; k < 2; ++k) dst[n][k] = *(const LAS bf16x8*)(lds + bbase[b][h] + n * 2048 + k * 1024); } while (0)
; #define PG8_WAIT_V(n) asm volatile("s_waitcnt vmcnt(" #n ")" ::: "memory")
; #define PG8_WAIT_L(n) asm volatile("s_waitcnt lgkmcnt(" #n ")" ::: "memory")
; #define PG8_BAR __builtin_amdgcn_s_barrier()
; #define PG8_SCHED __builtin_amdgcn_sched_barrier(0)
; template <class Epi>
; __device__ __forceinline__ void gemm_phase(LAS unsigned char* lds, const Gemm g, const StaticOrder& S, const Epi& E) {
;     ...
;             PG8_LDB(B0, 0, 0); PG8_SCHED; PG8_LDA(At, 0, 0); PG8_LDA(At2, 0, 1); PG8_STAGE(PG8_SB(1, 1), b1 + hstepB, voffB);
;             PG8_WAIT_V(8); PG8_WAIT_L(0); PG8_BAR; PG8_MMA2B(0, At, At2, B0); PG8_BAR; PG8_SCHED;
;             PG8_LDB(B0, 0, 1); PG8_STAGE(PG8_SB(0, 0), b2, voffB); PG8_STAGE(PG8_SA(0, 0), a2, voffA); PG8_STAGE(PG8_SA(0, 1), a2 + hstepA, voffA);
;             PG8_WAIT_V(8); PG8_WAIT_L(0); PG8_BAR; PG8_MMA2B(1, At, At2, B0); PG8_BAR; PG8_SCHED;
;             PG8_LDB(B0, 1, 0); PG8_SCHED; PG8_LDA(At, 1, 0); PG8_LDA(At2, 1, 1); PG8_STAGE(PG8_SB(0, 1), b2 + hstepB, voffB);
;             PG8_WAIT_V(8); PG8_WAIT_L(0); PG8_BAR; PG8_MMA2B(0, At, At2, B0); PG8_BAR; PG8_SCHED;
;             PG8_LDB(B0, 1, 1); PG8_STAGE(PG8_SB(1, 0), b3, voffB); PG8_STAGE(PG8_SA(1, 0), a3, voffA); PG8_STAGE(PG8_SA(1, 1), a3 + hstepA, voffA);
;             PG8_WAIT_V(8); PG8_WAIT_L(0); PG8_BAR; PG8_MMA2B(1, At, At2, B0); PG8_BAR; PG8_SCHED;
	ds_read_b128 v[128:131], v141
	ds_read_b128 v[144:147], v141 offset:1024
	ds_read_b128 v[148:151], v141 offset:2048
	ds_read_b128 v[152:155], v141 offset:3072
	ds_read_b128 v[156:159], v139 offset:32768
	ds_read_b128 v[166:169], v139 offset:33792
	ds_read_b128 v[178:181], v139 offset:34816
	ds_read_b128 v[182:185], v139 offset:35840
	ds_read_b128 v[186:189], v139 offset:36864
	ds_read_b128 v[190:193], v139 offset:37888
	ds_read_b128 v[194:197], v139 offset:38912
	ds_read_b128 v[198:201], v139 offset:39936
	ds_read_b128 v[202:205], v139 offset:49152
	ds_read_b128 v[214:217], v139 offset:50176
	ds_read_b128 v[218:221], v139 offset:51200
	ds_read_b128 v[222:225], v139 offset:52224
	ds_read_b128 v[226:229], v139 offset:53248
	ds_read_b128 v[230:233], v139 offset:54272
	ds_read_b128 v[234:237], v139 offset:55296
	ds_read_b128 v[238:241], v139 offset:56320
	s_add_u32 s42, s42, 0xb0000
	s_addc_u32 s43, s43, 0
	s_mov_b32 m0, s53
	s_nop 0
	global_load_lds_dwordx4 v133, s[42:43]
	s_mov_b32 m0, s54
	s_nop 0
	global_load_lds_dwordx4 v135, s[42:43]
	s_waitcnt vmcnt(8)
	s_waitcnt lgkmcnt(0)
	s_barrier
	s_setprio 0
	s_waitcnt lgkmcnt(14)
	v_mfma_f32_16x16x32_bf16 v[124:127], v[128:131], v[156:159], v[124:127]
	v_mfma_f32_16x16x32_bf16 v[120:123], v[148:151], v[156:159], v[120:123]
	s_waitcnt lgkmcnt(13)
	v_mfma_f32_16x16x32_bf16 v[108:111], v[128:131], v[178:181], v[108:111]
	v_mfma_f32_16x16x32_bf16 v[104:107], v[148:151], v[178:181], v[104:107]
	s_waitcnt lgkmcnt(11)
	v_mfma_f32_16x16x32_bf16 v[92:95], v[128:131], v[186:189], v[92:95]
	v_mfma_f32_16x16x32_bf16 v[88:91], v[148:151], v[186:189], v[88:91]
	s_waitcnt lgkmcnt(9)
	v_mfma_f32_16x16x32_bf16 v[76:79], v[128:131], v[194:197], v[76:79]
	v_mfma_f32_16x16x32_bf16 v[72:75], v[148:151], v[194:197], v[72:75]
	s_waitcnt lgkmcnt(7)
	v_mfma_f32_16x16x32_bf16 v[60:63], v[128:131], v[202:205], v[60:63]
	v_mfma_f32_16x16x32_bf16 v[56:59], v[148:151], v[202:205], v[56:59]
	s_waitcnt lgkmcnt(5)
	v_mfma_f32_16x16x32_bf16 v[44:47], v[128:131], v[218:221], v[44:47]
	v_mfma_f32_16x16x32_bf16 v[40:43], v[148:151], v[218:221], v[40:43]
	s_waitcnt lgkmcnt(3)
	v_mfma_f32_16x16x32_bf16 v[28:31], v[128:131], v[226:229], v[28:31]
	v_mfma_f32_16x16x32_bf16 v[24:27], v[148:151], v[226:229], v[24:27]
	s_waitcnt lgkmcnt(1)
	v_mfma_f32_16x16x32_bf16 v[12:15], v[128:131], v[234:237], v[12:15]
	v_mfma_f32_16x16x32_bf16 v[8:11], v[148:151], v[234:237], v[8:11]
	v_mfma_f32_16x16x32_bf16 v[124:127], v[144:147], v[166:169], v[124:127]
	v_mfma_f32_16x16x32_bf16 v[120:123], v[152:155], v[166:169], v[120:123]
	v_mfma_f32_16x16x32_bf16 v[108:111], v[144:147], v[182:185], v[108:111]
	v_mfma_f32_16x16x32_bf16 v[104:107], v[152:155], v[182:185], v[104:107]
	v_mfma_f32_16x16x32_bf16 v[92:95], v[144:147], v[190:193], v[92:95]
	v_mfma_f32_16x16x32_bf16 v[88:91], v[152:155], v[190:193], v[88:91]
	v_mfma_f32_16x16x32_bf16 v[76:79], v[144:147], v[198:201], v[76:79]
	v_mfma_f32_16x16x32_bf16 v[72:75], v[152:155], v[198:201], v[72:75]
	v_mfma_f32_16x16x32_bf16 v[60:63], v[144:147], v[214:217], v[60:63]
	v_mfma_f32_16x16x32_bf16 v[56:59], v[152:155], v[214:217], v[56:59]
	v_mfma_f32_16x16x32_bf16 v[44:47], v[144:147], v[222:225], v[44:47]
	v_mfma_f32_16x16x32_bf16 v[40:43], v[152:155], v[222:225], v[40:43]
	v_mfma_f32_16x16x32_bf16 v[28:31], v[144:147], v[230:233], v[28:31]
	v_mfma_f32_16x16x32_bf16 v[24:27], v[152:155], v[230:233], v[24:27]
	s_waitcnt lgkmcnt(0)
	v_mfma_f32_16x16x32_bf16 v[12:15], v[144:147], v[238:241], v[12:15]
	v_mfma_f32_16x16x32_bf16 v[8:11], v[152:155], v[238:241], v[8:11]
	s_setprio 1
	s_barrier
	ds_read_b128 v[128:131], v142
	ds_read_b128 v[144:147], v142 offset:1024
	ds_read_b128 v[148:151], v142 offset:2048
	ds_read_b128 v[152:155], v142 offset:3072
	s_mov_b32 m0, s55
	s_nop 0
	global_load_lds_dwordx4 v133, s[38:39]
	s_mov_b32 m0, s56
	s_nop 0
	global_load_lds_dwordx4 v135, s[38:39]
	s_mov_b32 m0, s57
	s_nop 0
	global_load_lds_dwordx4 v132, s[16:17]
	s_mov_b32 m0, s58
	s_nop 0
	global_load_lds_dwordx4 v134, s[16:17]
	s_add_u32 s14, s14, 0xb0080
	s_addc_u32 s15, s15, 0
	s_mov_b32 m0, s59
	s_nop 0
	global_load_lds_dwordx4 v132, s[14:15]
	s_mov_b32 m0, s60
	s_nop 0
	global_load_lds_dwordx4 v134, s[14:15]
	s_waitcnt vmcnt(8)
	s_waitcnt lgkmcnt(0)
	s_barrier
	s_setprio 0
	s_waitcnt lgkmcnt(3)
	v_mfma_f32_16x16x32_bf16 v[116:119], v[128:131], v[156:159], v[116:119]
	s_waitcnt lgkmcnt(1)
	v_mfma_f32_16x16x32_bf16 v[112:115], v[148:151], v[156:159], v[112:115]
	v_mfma_f32_16x16x32_bf16 v[100:103], v[128:131], v[178:181], v[100:103]
	v_mfma_f32_16x16x32_bf16 v[96:99], v[148:151], v[178:181], v[96:99]
	v_mfma_f32_16x16x32_bf16 v[84:87], v[128:131], v[186:189], v[84:87]
	v_mfma_f32_16x16x32_bf16 v[80:83], v[148:151], v[186:189], v[80:83]
	v_mfma_f32_16x16x32_bf16 v[68:71], v[128:131], v[194:197], v[68:71]
	v_mfma_f32_16x16x32_bf16 v[64:67], v[148:151], v[194:197], v[64:67]
	v_mfma_f32_16x16x32_bf16 v[52:55], v[128:131], v[202:205], v[52:55]
	v_mfma_f32_16x16x32_bf16 v[48:51], v[148:151], v[202:205], v[48:51]
	v_mfma_f32_16x16x32_bf16 v[36:39], v[128:131], v[218:221], v[36:39]
	v_mfma_f32_16x16x32_bf16 v[32:35], v[148:151], v[218:221], v[32:35]
	v_mfma_f32_16x16x32_bf16 v[20:23], v[128:131], v[226:229], v[20:23]
	v_mfma_f32_16x16x32_bf16 v[16:19], v[148:151], v[226:229], v[16:19]
	v_mfma_f32_16x16x32_bf16 v[4:7], v[128:131], v[234:237], v[4:7]
	v_mfma_f32_16x16x32_bf16 v[0:3], v[148:151], v[234:237], v[0:3]
	v_mfma_f32_16x16x32_bf16 v[116:119], v[144:147], v[166:169], v[116:119]
	s_waitcnt lgkmcnt(0)
	v_mfma_f32_16x16x32_bf16 v[112:115], v[152:155], v[166:169], v[112:115]
	v_mfma_f32_16x16x32_bf16 v[100:103], v[144:147], v[182:185], v[100:103]
	v_mfma_f32_16x16x32_bf16 v[96:99], v[152:155], v[182:185], v[96:99]
	v_mfma_f32_16x16x32_bf16 v[84:87], v[144:147], v[190:193], v[84:87]
	v_mfma_f32_16x16x32_bf16 v[80:83], v[152:155], v[190:193], v[80:83]
	v_mfma_f32_16x16x32_bf16 v[68:71], v[144:147], v[198:201], v[68:71]
	v_mfma_f32_16x16x32_bf16 v[64:67], v[152:155], v[198:201], v[64:67]
	v_mfma_f32_16x16x32_bf16 v[52:55], v[144:147], v[214:217], v[52:55]
	v_mfma_f32_16x16x32_bf16 v[48:51], v[152:155], v[214:217], v[48:51]
	v_mfma_f32_16x16x32_bf16 v[36:39], v[144:147], v[222:225], v[36:39]
	v_mfma_f32_16x16x32_bf16 v[32:35], v[152:155], v[222:225], v[32:35]
	v_mfma_f32_16x16x32_bf16 v[20:23], v[144:147], v[230:233], v[20:23]
	v_mfma_f32_16x16x32_bf16 v[16:19], v[152:155], v[230:233], v[16:19]
	v_mfma_f32_16x16x32_bf16 v[4:7], v[144:147], v[238:241], v[4:7]
	v_mfma_f32_16x16x32_bf16 v[0:3], v[152:155], v[238:241], v[0:3]
	s_setprio 1
	s_barrier
	s_add_i32 s68, s68, 2
	s_add_u32 s12, s12, 0x100
	s_addc_u32 s13, s13, 0
	s_add_u32 s80, s80, 0x100
	s_addc_u32 s81, s81, 0
	s_add_u32 s82, s82, 0x100
	s_addc_u32 s83, s83, 0
	s_cmp_gt_u32 s68, 41
	s_cbranch_scc0 .LBB0_1140
	s_and_b64 vcc, exec, s[2:3]
	s_cbranch_vccz .LBB0_1143
	s_barrier
